# removed the 36 back-to-back duplicate s_waitcnt lgkmcnt(0) at the head of each GEMM compute segment
# speedup vs baseline: 1.0145x; 1.0029x over previous
; #define PG8_STAGE(bufoff, gbase, voff) do { _Pragma("unroll") for (int _i = 0; _i < 2; ++_i) \
;         __builtin_amdgcn_global_load_lds((const unsigned*)((const char*)(gbase) + (voff)[_i]), (LAS unsigned*)(lds + (bufoff) + ldsw + _i * 8192), 16, 0, 0); } while (0)
; #define PG8_LDA(dst, b, h) do { _Pragma("unroll") for (int m = 0; m < 4; ++m) _Pragma("unroll") for (int k = 0; k < 2; ++k) dst[m][k] = *(const LAS bf16x8*)(lds + PG8_SA(b, h) + aoff + m * 2048 + k * 1024); } while (0)
; #define PG8_LDB(dst, b, h) do { _Pragma("unroll") for (int n = 0; n < 2; ++n) _Pragma("unroll") for (int k = 0; k < 2; ++k) dst[n][k] = *(const LAS bf16x8*)(lds + PG8_SB(b, h) + boff + n * 2048 + k * 1024); } while (0)
; #define PG8_MMA(ai, bj, At, Bt) do { __builtin_amdgcn_s_setprio(1); _Pragma("unroll") for (int m = 0; m < 4; ++m) _Pragma("unroll") for (int n = 0; n < 2; ++n) _Pragma("unroll") for (int k = 0; k < 2; ++k) \
;         acc[ai][bj][m][n] = __builtin_amdgcn_mfma_f32_16x16x32_bf16(Bt[n][k], At[m][k], acc[ai][bj][m][n], 0, 0, 0); __builtin_amdgcn_s_setprio(0); } while (0)
; #define PG8_WAIT_V(n) asm volatile("s_waitcnt vmcnt(" #n ")" ::: "memory")
; #define PG8_WAIT_L(n) asm volatile("s_waitcnt lgkmcnt(" #n ")" ::: "memory")
; #define PG8_BAR __builtin_amdgcn_s_barrier()
; #define PG8_SCHED __builtin_amdgcn_sched_barrier(0)
; template <class Epi, class Sched, bool AREMAP>
; __device__ __forceinline__ void gemm_phase(LAS unsigned char* lds, const Gemm g, const Sched& S, const Epi& E, int wv) {
;     ...
;             const char* a1 = cA + (size_t)(t + 1) * kstep;
;             const char* a2 = last ? nA : cA + (size_t)(t + 2) * kstep; const char* b2 = last ? nB : cB + (size_t)(t + 2) * kstep;
;             const char* a3 = a2 + kstep; const char* b3 = b2 + kstep;
;             PG8_LDB(B0, 0, 0); PG8_SCHED; PG8_LDA(At, 0, 0); PG8_STAGE(PG8_SA(1, 1), a1 + hstepA, voffA);
;             PG8_WAIT_L(8); PG8_BAR; PG8_WAIT_L(0); PG8_MMA(0, 0, At, B0); PG8_BAR; PG8_SCHED;
;             PG8_LDB(B1, 0, 1); PG8_STAGE(PG8_SB(0, 0), b2, voffB);
;             PG8_BAR; PG8_WAIT_L(0); PG8_MMA(0, 1, At, B1); PG8_BAR;
;             PG8_LDA(At, 0, 1); PG8_STAGE(PG8_SA(0, 0), a2, voffA);
;             PG8_BAR; PG8_WAIT_L(0); PG8_MMA(1, 0, At, B0); PG8_BAR; PG8_SCHED;
;             PG8_STAGE(PG8_SB(0, 1), b2 + hstepB, voffB);
;             PG8_WAIT_V(6); PG8_BAR; PG8_MMA(1, 1, At, B1); PG8_BAR;
.LBB0_202:
	s_add_u32 s18, s16, 0xfff80080
	s_addc_u32 s19, s17, -1
	s_add_i32 s38, 0, 0x10000
	v_add_u32_e32 v145, s38, v142
	ds_read_b128 v[146:149], v145
	ds_read_b128 v[150:153], v145 offset:1024
	ds_read_b128 v[154:157], v145 offset:2048
	ds_read_b128 v[158:161], v145 offset:3072
	s_cmp_eq_u32 s56, 28
	s_cselect_b32 s21, s11, s19
	s_cselect_b32 s20, s47, s18
	s_cselect_b32 s19, s9, s55
	s_cselect_b32 s18, s52, s53
	s_add_i32 m0, s7, 0xc000
	ds_read_b128 v[162:165], v144
	ds_read_b128 v[166:169], v144 offset:1024
	ds_read_b128 v[170:173], v144 offset:2048
	ds_read_b128 v[174:177], v144 offset:3072
	ds_read_b128 v[178:181], v144 offset:4096
	ds_read_b128 v[182:185], v144 offset:5120
	ds_read_b128 v[196:199], v144 offset:6144
	ds_read_b128 v[200:203], v144 offset:7168
	global_load_lds_dwordx4 v140, s[16:17]
	s_add_i32 m0, s7, 0xe000
	s_nop 0
	global_load_lds_dwordx4 v138, s[16:17]
	s_waitcnt lgkmcnt(8)
	s_barrier
	s_waitcnt lgkmcnt(0)
	v_mfma_f32_16x16x32_bf16 v[126:129], v[146:149], v[162:165], v[126:129]
	v_mfma_f32_16x16x32_bf16 v[122:125], v[154:157], v[162:165], v[122:125]
	v_mfma_f32_16x16x32_bf16 v[118:121], v[146:149], v[170:173], v[118:121]
	v_mfma_f32_16x16x32_bf16 v[114:117], v[154:157], v[170:173], v[114:117]
	v_mfma_f32_16x16x32_bf16 v[102:105], v[146:149], v[178:181], v[102:105]
	v_mfma_f32_16x16x32_bf16 v[98:101], v[154:157], v[178:181], v[98:101]
	v_mfma_f32_16x16x32_bf16 v[86:89], v[146:149], v[196:199], v[86:89]
	v_mfma_f32_16x16x32_bf16 v[82:85], v[154:157], v[196:199], v[82:85]
	v_mfma_f32_16x16x32_bf16 v[126:129], v[150:153], v[166:169], v[126:129]
	v_mfma_f32_16x16x32_bf16 v[122:125], v[158:161], v[166:169], v[122:125]
	v_mfma_f32_16x16x32_bf16 v[118:121], v[150:153], v[174:177], v[118:121]
	v_mfma_f32_16x16x32_bf16 v[114:117], v[158:161], v[174:177], v[114:117]
	v_mfma_f32_16x16x32_bf16 v[102:105], v[150:153], v[182:185], v[102:105]
	v_mfma_f32_16x16x32_bf16 v[98:101], v[158:161], v[182:185], v[98:101]
	v_mfma_f32_16x16x32_bf16 v[86:89], v[150:153], v[200:203], v[86:89]
	v_mfma_f32_16x16x32_bf16 v[82:85], v[158:161], v[200:203], v[82:85]
	s_barrier
	s_add_i32 s39, 0, 0x14000
	s_add_i32 s38, s38, s29
	v_add_u32_e32 v145, s39, v142
	s_add_u32 s80, s18, 0x80
	s_addc_u32 s81, s19, 0
	s_mov_b32 m0, s38
	ds_read_b128 v[204:207], v145
	ds_read_b128 v[208:211], v145 offset:1024
	ds_read_b128 v[212:215], v145 offset:2048
	ds_read_b128 v[216:219], v145 offset:3072
	global_load_lds_dwordx4 v132, s[18:19]
	s_add_i32 m0, s38, 0x2000
	s_nop 0
	global_load_lds_dwordx4 v136, s[18:19]
	s_barrier
	s_waitcnt lgkmcnt(0)
	v_mfma_f32_16x16x32_bf16 v[110:113], v[204:207], v[162:165], v[110:113]
	v_mfma_f32_16x16x32_bf16 v[106:109], v[212:215], v[162:165], v[106:109]
	v_mfma_f32_16x16x32_bf16 v[94:97], v[204:207], v[170:173], v[94:97]
	v_mfma_f32_16x16x32_bf16 v[90:93], v[212:215], v[170:173], v[90:93]
	v_mfma_f32_16x16x32_bf16 v[78:81], v[204:207], v[178:181], v[78:81]
	v_mfma_f32_16x16x32_bf16 v[74:77], v[212:215], v[178:181], v[74:77]
	v_mfma_f32_16x16x32_bf16 v[70:73], v[204:207], v[196:199], v[70:73]
	v_mfma_f32_16x16x32_bf16 v[66:69], v[212:215], v[196:199], v[66:69]
	v_mfma_f32_16x16x32_bf16 v[110:113], v[208:211], v[166:169], v[110:113]
	v_mfma_f32_16x16x32_bf16 v[106:109], v[216:219], v[166:169], v[106:109]
	v_mfma_f32_16x16x32_bf16 v[94:97], v[208:211], v[174:177], v[94:97]
	v_mfma_f32_16x16x32_bf16 v[90:93], v[216:219], v[174:177], v[90:93]
	v_mfma_f32_16x16x32_bf16 v[78:81], v[208:211], v[182:185], v[78:81]
	v_mfma_f32_16x16x32_bf16 v[74:77], v[216:219], v[182:185], v[74:77]
	v_mfma_f32_16x16x32_bf16 v[70:73], v[208:211], v[200:203], v[70:73]
	v_mfma_f32_16x16x32_bf16 v[66:69], v[216:219], v[200:203], v[66:69]
	s_mov_b32 m0, s7
	s_add_u32 s96, s20, 0x80
	s_addc_u32 s97, s21, 0
	s_barrier
	ds_read_b128 v[162:165], v144 offset:16384
	ds_read_b128 v[166:169], v144 offset:17408
	ds_read_b128 v[170:173], v144 offset:18432
	ds_read_b128 v[174:177], v144 offset:19456
	ds_read_b128 v[178:181], v144 offset:20480
	ds_read_b128 v[182:185], v144 offset:21504
	ds_read_b128 v[196:199], v144 offset:22528
	ds_read_b128 v[200:203], v144 offset:23552
	global_load_lds_dwordx4 v130, s[20:21]
	s_mov_b32 m0, s30
	s_nop 0
	global_load_lds_dwordx4 v134, s[20:21]
	s_barrier
	s_waitcnt lgkmcnt(0)
	v_mfma_f32_16x16x32_bf16 v[62:65], v[146:149], v[162:165], v[62:65]
	v_mfma_f32_16x16x32_bf16 v[58:61], v[154:157], v[162:165], v[58:61]
	v_mfma_f32_16x16x32_bf16 v[54:57], v[146:149], v[170:173], v[54:57]
	v_mfma_f32_16x16x32_bf16 v[50:53], v[154:157], v[170:173], v[50:53]
	v_mfma_f32_16x16x32_bf16 v[38:41], v[146:149], v[178:181], v[38:41]
	v_mfma_f32_16x16x32_bf16 v[34:37], v[154:157], v[178:181], v[34:37]
	v_mfma_f32_16x16x32_bf16 v[22:25], v[146:149], v[196:199], v[22:25]
	v_mfma_f32_16x16x32_bf16 v[18:21], v[154:157], v[196:199], v[18:21]
	v_mfma_f32_16x16x32_bf16 v[62:65], v[150:153], v[166:169], v[62:65]
	v_mfma_f32_16x16x32_bf16 v[58:61], v[158:161], v[166:169], v[58:61]
	v_mfma_f32_16x16x32_bf16 v[54:57], v[150:153], v[174:177], v[54:57]
	v_mfma_f32_16x16x32_bf16 v[50:53], v[158:161], v[174:177], v[50:53]
	v_mfma_f32_16x16x32_bf16 v[38:41], v[150:153], v[182:185], v[38:41]
	v_mfma_f32_16x16x32_bf16 v[34:37], v[158:161], v[182:185], v[34:37]
	v_mfma_f32_16x16x32_bf16 v[22:25], v[150:153], v[200:203], v[22:25]
	v_mfma_f32_16x16x32_bf16 v[18:21], v[158:161], v[200:203], v[18:21]
	s_barrier
	s_add_u32 s62, s18, 0x80000
	s_addc_u32 s63, s19, 0
	s_add_i32 s38, s39, s29
	s_mov_b32 m0, s38
	s_nop 0
	global_load_lds_dwordx4 v132, s[62:63]
	s_add_i32 m0, s38, 0x2000
	s_nop 0
	global_load_lds_dwordx4 v136, s[62:63]
	s_waitcnt vmcnt(6)
	s_barrier
; #define PG8_STAGE(bufoff, gbase, voff) do { _Pragma("unroll") for (int _i = 0; _i < 2; ++_i) \
;         __builtin_amdgcn_global_load_lds((const unsigned*)((const char*)(gbase) + (voff)[_i]), (LAS unsigned*)(lds + (bufoff) + ldsw + _i * 8192), 16, 0, 0); } while (0)
; #define PG8_LDA(dst, b, h) do { _Pragma("unroll") for (int m = 0; m < 4; ++m) _Pragma("unroll") for (int k = 0; k < 2; ++k) dst[m][k] = *(const LAS bf16x8*)(lds + PG8_SA(b, h) + aoff + m * 2048 + k * 1024); } while (0)
; #define PG8_LDB(dst, b, h) do { _Pragma("unroll") for (int n = 0; n < 2; ++n) _Pragma("unroll") for (int k = 0; k < 2; ++k) dst[n][k] = *(const LAS bf16x8*)(lds + PG8_SB(b, h) + boff + n * 2048 + k * 1024); } while (0)
; #define PG8_MMA(ai, bj, At, Bt) do { __builtin_amdgcn_s_setprio(1); _Pragma("unroll") for (int m = 0; m < 4; ++m) _Pragma("unroll") for (int n = 0; n < 2; ++n) _Pragma("unroll") for (int k = 0; k < 2; ++k) \
;         acc[ai][bj][m][n] = __builtin_amdgcn_mfma_f32_16x16x32_bf16(Bt[n][k], At[m][k], acc[ai][bj][m][n], 0, 0, 0); __builtin_amdgcn_s_setprio(0); } while (0)
; #define PG8_WAIT_V(n) asm volatile("s_waitcnt vmcnt(" #n ")" ::: "memory")
; #define PG8_WAIT_L(n) asm volatile("s_waitcnt lgkmcnt(" #n ")" ::: "memory")
; #define PG8_BAR __builtin_amdgcn_s_barrier()
; #define PG8_SCHED __builtin_amdgcn_sched_barrier(0)
; template <class Epi, class Sched, bool AREMAP>
; __device__ __forceinline__ void gemm_phase(LAS unsigned char* lds, const Gemm g, const Sched& S, const Epi& E, int wv) {
;     ...
;             PG8_WAIT_V(6); PG8_BAR; PG8_MMA(1, 1, At, B1); PG8_BAR;
;             PG8_LDB(B0, 1, 0); PG8_SCHED; PG8_LDA(At, 1, 0); PG8_STAGE(PG8_SA(0, 1), a2 + hstepA, voffA);
;             PG8_WAIT_L(8); PG8_BAR; PG8_WAIT_L(0); PG8_MMA(0, 0, At, B0); PG8_BAR; PG8_SCHED;
;             PG8_LDB(B1, 1, 1); PG8_STAGE(PG8_SB(1, 0), b3, voffB);
;             PG8_BAR; PG8_WAIT_L(0); PG8_MMA(0, 1, At, B1); PG8_BAR;
;             PG8_LDA(At, 1, 1); PG8_STAGE(PG8_SA(1, 0), a3, voffA);
	v_mfma_f32_16x16x32_bf16 v[46:49], v[204:207], v[162:165], v[46:49]
	v_mfma_f32_16x16x32_bf16 v[42:45], v[212:215], v[162:165], v[42:45]
	v_mfma_f32_16x16x32_bf16 v[30:33], v[204:207], v[170:173], v[30:33]
	v_mfma_f32_16x16x32_bf16 v[26:29], v[212:215], v[170:173], v[26:29]
	v_mfma_f32_16x16x32_bf16 v[14:17], v[204:207], v[178:181], v[14:17]
	v_mfma_f32_16x16x32_bf16 v[10:13], v[212:215], v[178:181], v[10:13]
	v_mfma_f32_16x16x32_bf16 v[6:9], v[204:207], v[196:199], v[6:9]
	v_mfma_f32_16x16x32_bf16 v[2:5], v[212:215], v[196:199], v[2:5]
	v_mfma_f32_16x16x32_bf16 v[46:49], v[208:211], v[166:169], v[46:49]
	v_mfma_f32_16x16x32_bf16 v[42:45], v[216:219], v[166:169], v[42:45]
	v_mfma_f32_16x16x32_bf16 v[30:33], v[208:211], v[174:177], v[30:33]
	v_mfma_f32_16x16x32_bf16 v[26:29], v[216:219], v[174:177], v[26:29]
	v_mfma_f32_16x16x32_bf16 v[14:17], v[208:211], v[182:185], v[14:17]
	v_mfma_f32_16x16x32_bf16 v[10:13], v[216:219], v[182:185], v[10:13]
	v_mfma_f32_16x16x32_bf16 v[6:9], v[208:211], v[200:203], v[6:9]
	v_mfma_f32_16x16x32_bf16 v[2:5], v[216:219], v[200:203], v[2:5]
	s_add_i32 s38, 0, 0x18000
	v_add_u32_e32 v145, s38, v142
	s_barrier
	ds_read_b128 v[146:149], v145
	ds_read_b128 v[150:153], v145 offset:1024
	ds_read_b128 v[154:157], v145 offset:2048
	ds_read_b128 v[158:161], v145 offset:3072
	s_add_u32 s20, s20, 0x80000
	s_addc_u32 s21, s21, 0
	s_mov_b32 m0, s31
	ds_read_b128 v[162:165], v144 offset:32768
	ds_read_b128 v[166:169], v144 offset:33792
	ds_read_b128 v[170:173], v144 offset:34816
	ds_read_b128 v[174:177], v144 offset:35840
	ds_read_b128 v[178:181], v144 offset:36864
	ds_read_b128 v[182:185], v144 offset:37888
	ds_read_b128 v[196:199], v144 offset:38912
	ds_read_b128 v[200:203], v144 offset:39936
	global_load_lds_dwordx4 v130, s[20:21]
	s_mov_b32 m0, s34
	s_nop 0
	global_load_lds_dwordx4 v134, s[20:21]
	s_waitcnt lgkmcnt(8)
	s_barrier
	s_waitcnt lgkmcnt(0)
	v_mfma_f32_16x16x32_bf16 v[126:129], v[146:149], v[162:165], v[126:129]
	v_mfma_f32_16x16x32_bf16 v[122:125], v[154:157], v[162:165], v[122:125]
	v_mfma_f32_16x16x32_bf16 v[118:121], v[146:149], v[170:173], v[118:121]
	v_mfma_f32_16x16x32_bf16 v[114:117], v[154:157], v[170:173], v[114:117]
	v_mfma_f32_16x16x32_bf16 v[102:105], v[146:149], v[178:181], v[102:105]
	v_mfma_f32_16x16x32_bf16 v[98:101], v[154:157], v[178:181], v[98:101]
	v_mfma_f32_16x16x32_bf16 v[86:89], v[146:149], v[196:199], v[86:89]
	v_mfma_f32_16x16x32_bf16 v[82:85], v[154:157], v[196:199], v[82:85]
	v_mfma_f32_16x16x32_bf16 v[126:129], v[150:153], v[166:169], v[126:129]
	v_mfma_f32_16x16x32_bf16 v[122:125], v[158:161], v[166:169], v[122:125]
	v_mfma_f32_16x16x32_bf16 v[118:121], v[150:153], v[174:177], v[118:121]
	v_mfma_f32_16x16x32_bf16 v[114:117], v[158:161], v[174:177], v[114:117]
	v_mfma_f32_16x16x32_bf16 v[102:105], v[150:153], v[182:185], v[102:105]
	v_mfma_f32_16x16x32_bf16 v[98:101], v[158:161], v[182:185], v[98:101]
	v_mfma_f32_16x16x32_bf16 v[86:89], v[150:153], v[200:203], v[86:89]
	v_mfma_f32_16x16x32_bf16 v[82:85], v[158:161], v[200:203], v[82:85]
	s_barrier
	s_add_i32 s20, 0, 0x1c000
	s_add_i32 s21, s38, s29
	v_add_u32_e32 v145, s20, v142
	s_mov_b32 m0, s21
	ds_read_b128 v[204:207], v145
	ds_read_b128 v[208:211], v145 offset:1024
	ds_read_b128 v[212:215], v145 offset:2048
	ds_read_b128 v[216:219], v145 offset:3072
	global_load_lds_dwordx4 v132, s[80:81]
	s_add_i32 m0, s21, 0x2000
	s_nop 0
	global_load_lds_dwordx4 v136, s[80:81]
	s_barrier
	s_waitcnt lgkmcnt(0)
	v_mfma_f32_16x16x32_bf16 v[110:113], v[204:207], v[162:165], v[110:113]
	v_mfma_f32_16x16x32_bf16 v[106:109], v[212:215], v[162:165], v[106:109]
	v_mfma_f32_16x16x32_bf16 v[94:97], v[204:207], v[170:173], v[94:97]
	v_mfma_f32_16x16x32_bf16 v[90:93], v[212:215], v[170:173], v[90:93]
	v_mfma_f32_16x16x32_bf16 v[78:81], v[204:207], v[178:181], v[78:81]
	v_mfma_f32_16x16x32_bf16 v[74:77], v[212:215], v[178:181], v[74:77]
	v_mfma_f32_16x16x32_bf16 v[70:73], v[204:207], v[196:199], v[70:73]
	v_mfma_f32_16x16x32_bf16 v[66:69], v[212:215], v[196:199], v[66:69]
	v_mfma_f32_16x16x32_bf16 v[110:113], v[208:211], v[166:169], v[110:113]
	v_mfma_f32_16x16x32_bf16 v[106:109], v[216:219], v[166:169], v[106:109]
	v_mfma_f32_16x16x32_bf16 v[94:97], v[208:211], v[174:177], v[94:97]
	v_mfma_f32_16x16x32_bf16 v[90:93], v[216:219], v[174:177], v[90:93]
	v_mfma_f32_16x16x32_bf16 v[78:81], v[208:211], v[182:185], v[78:81]
	v_mfma_f32_16x16x32_bf16 v[74:77], v[216:219], v[182:185], v[74:77]
	v_mfma_f32_16x16x32_bf16 v[70:73], v[208:211], v[200:203], v[70:73]
	v_mfma_f32_16x16x32_bf16 v[66:69], v[216:219], v[200:203], v[66:69]
	s_mov_b32 m0, s35
	s_barrier
	ds_read_b128 v[162:165], v144 offset:49152
	ds_read_b128 v[166:169], v144 offset:50176
	ds_read_b128 v[170:173], v144 offset:51200
	ds_read_b128 v[174:177], v144 offset:52224
	ds_read_b128 v[178:181], v144 offset:53248
	ds_read_b128 v[182:185], v144 offset:54272
	ds_read_b128 v[196:199], v144 offset:55296
	ds_read_b128 v[200:203], v144 offset:56320
	global_load_lds_dwordx4 v130, s[96:97]
	s_mov_b32 m0, s36
	s_nop 0
	global_load_lds_dwordx4 v134, s[96:97]
	s_barrier
; #define PG8_STAGE(bufoff, gbase, voff) do { _Pragma("unroll") for (int _i = 0; _i < 2; ++_i) \
;         __builtin_amdgcn_global_load_lds((const unsigned*)((const char*)(gbase) + (voff)[_i]), (LAS unsigned*)(lds + (bufoff) + ldsw + _i * 8192), 16, 0, 0); } while (0)
; #define PG8_MMA(ai, bj, At, Bt) do { __builtin_amdgcn_s_setprio(1); _Pragma("unroll") for (int m = 0; m < 4; ++m) _Pragma("unroll") for (int n = 0; n < 2; ++n) _Pragma("unroll") for (int k = 0; k < 2; ++k) \
;         acc[ai][bj][m][n] = __builtin_amdgcn_mfma_f32_16x16x32_bf16(Bt[n][k], At[m][k], acc[ai][bj][m][n], 0, 0, 0); __builtin_amdgcn_s_setprio(0); } while (0)
; #define PG8_WAIT_V(n) asm volatile("s_waitcnt vmcnt(" #n ")" ::: "memory")
; #define PG8_WAIT_L(n) asm volatile("s_waitcnt lgkmcnt(" #n ")" ::: "memory")
; #define PG8_BAR __builtin_amdgcn_s_barrier()
; #define PG8_SCHED __builtin_amdgcn_sched_barrier(0)
; template <class Epi, class Sched, bool AREMAP>
; __device__ __forceinline__ void gemm_phase(LAS unsigned char* lds, const Gemm g, const Sched& S, const Epi& E, int wv) {
;     ...
;             PG8_BAR; PG8_WAIT_L(0); PG8_MMA(1, 0, At, B0); PG8_BAR; PG8_SCHED;
;             PG8_STAGE(PG8_SB(1, 1), b3 + hstepB, voffB);
;             PG8_WAIT_V(6); PG8_BAR; PG8_MMA(1, 1, At, B1); PG8_BAR;
;         }
	s_waitcnt lgkmcnt(0)
	v_mfma_f32_16x16x32_bf16 v[62:65], v[146:149], v[162:165], v[62:65]
	v_mfma_f32_16x16x32_bf16 v[58:61], v[154:157], v[162:165], v[58:61]
	v_mfma_f32_16x16x32_bf16 v[54:57], v[146:149], v[170:173], v[54:57]
	v_mfma_f32_16x16x32_bf16 v[50:53], v[154:157], v[170:173], v[50:53]
	v_mfma_f32_16x16x32_bf16 v[38:41], v[146:149], v[178:181], v[38:41]
	v_mfma_f32_16x16x32_bf16 v[34:37], v[154:157], v[178:181], v[34:37]
	v_mfma_f32_16x16x32_bf16 v[22:25], v[146:149], v[196:199], v[22:25]
	v_mfma_f32_16x16x32_bf16 v[18:21], v[154:157], v[196:199], v[18:21]
	v_mfma_f32_16x16x32_bf16 v[62:65], v[150:153], v[166:169], v[62:65]
	v_mfma_f32_16x16x32_bf16 v[58:61], v[158:161], v[166:169], v[58:61]
	v_mfma_f32_16x16x32_bf16 v[54:57], v[150:153], v[174:177], v[54:57]
	v_mfma_f32_16x16x32_bf16 v[50:53], v[158:161], v[174:177], v[50:53]
	v_mfma_f32_16x16x32_bf16 v[38:41], v[150:153], v[182:185], v[38:41]
	v_mfma_f32_16x16x32_bf16 v[34:37], v[158:161], v[182:185], v[34:37]
	v_mfma_f32_16x16x32_bf16 v[22:25], v[150:153], v[200:203], v[22:25]
	v_mfma_f32_16x16x32_bf16 v[18:21], v[158:161], v[200:203], v[18:21]
	s_barrier
	s_add_u32 s18, s18, 0x80080
	s_addc_u32 s19, s19, 0
	s_add_i32 s20, s20, s29
	s_mov_b32 m0, s20
	s_nop 0
	global_load_lds_dwordx4 v132, s[18:19]
	s_add_i32 m0, s20, 0x2000
	s_nop 0
	global_load_lds_dwordx4 v136, s[18:19]
	s_waitcnt vmcnt(6)
	s_barrier
	v_mfma_f32_16x16x32_bf16 v[46:49], v[204:207], v[162:165], v[46:49]
	v_mfma_f32_16x16x32_bf16 v[42:45], v[212:215], v[162:165], v[42:45]
	v_mfma_f32_16x16x32_bf16 v[30:33], v[204:207], v[170:173], v[30:33]
	v_mfma_f32_16x16x32_bf16 v[26:29], v[212:215], v[170:173], v[26:29]
	v_mfma_f32_16x16x32_bf16 v[14:17], v[204:207], v[178:181], v[14:17]
	v_mfma_f32_16x16x32_bf16 v[10:13], v[212:215], v[178:181], v[10:13]
	v_mfma_f32_16x16x32_bf16 v[6:9], v[204:207], v[196:199], v[6:9]
	v_mfma_f32_16x16x32_bf16 v[2:5], v[212:215], v[196:199], v[2:5]
	v_mfma_f32_16x16x32_bf16 v[46:49], v[208:211], v[166:169], v[46:49]
	v_mfma_f32_16x16x32_bf16 v[42:45], v[216:219], v[166:169], v[42:45]
	v_mfma_f32_16x16x32_bf16 v[30:33], v[208:211], v[174:177], v[30:33]
	v_mfma_f32_16x16x32_bf16 v[26:29], v[216:219], v[174:177], v[26:29]
	v_mfma_f32_16x16x32_bf16 v[14:17], v[208:211], v[182:185], v[14:17]
	v_mfma_f32_16x16x32_bf16 v[10:13], v[216:219], v[182:185], v[10:13]
	v_mfma_f32_16x16x32_bf16 v[6:9], v[208:211], v[200:203], v[6:9]
	v_mfma_f32_16x16x32_bf16 v[2:5], v[216:219], v[200:203], v[2:5]
	s_add_i32 s56, s56, 2
	s_add_u32 s53, s53, 0x100
	s_addc_u32 s55, s55, 0
	s_add_u32 s16, s16, 0x100
	s_addc_u32 s17, s17, 0
	s_cmp_gt_u32 s56, 29
	s_barrier
	s_cbranch_scc0 .LBB0_202
; __device__ __forceinline__ unsigned cvt_pk_bf16(float lo, float hi) { f32x2_t f = {lo, hi}; bf16x2_t v = __builtin_convertvector(f, bf16x2_t); return __builtin_bit_cast(unsigned, v); }
; #define PG8_WAIT_V(n) asm volatile("s_waitcnt vmcnt(" #n ")" ::: "memory")
; #define PG8_BAR __builtin_amdgcn_s_barrier()
; template <class Epi, class Sched, bool AREMAP>
; __device__ __forceinline__ void gemm_phase(LAS unsigned char* lds, const Gemm g, const Sched& S, const Epi& E, int wv) {
;     ...
;         if (!has_next) break;
;     ...
;     PG8_WAIT_V(0);
;     if (wr == 0) PG8_BAR;
;     PG8_BAR;
;     __device__ __forceinline__ void operator()(const f32x4 (&acc)[2][2][4][2], const Unit& u, int wr, int wc, int fr, int fq) const {
;         const int row0 = u.pm * BM + wr * 64 + fr; int colt = u.pn * BM; bf16_t* base = O;
;         if (split_cols) { const int t = colt / split_cols; base += (size_t)t * split_stride; colt -= t * split_cols; }
;         const int col0 = colt + wc * 32 + 8 * fq;
; #pragma unroll
;         for (int ai = 0; ai < 2; ++ai)
; #pragma unroll
;             for (int m = 0; m < 4; ++m) { bf16_t* rowp = base + (size_t)(row0 + ai * HALF + m * 16) * ldc + col0;
; #pragma unroll
;                 for (int bj = 0; bj < 2; ++bj) { const f32x4 v0 = acc[ai][bj][m][0], v1 = acc[ai][bj][m][1];
;                     u32x4 w; w.x = cvt_pk_bf16(v0[0], v0[1]); w.y = cvt_pk_bf16(v0[2], v0[3]); w.z = cvt_pk_bf16(v1[0], v1[1]); w.w = cvt_pk_bf16(v1[2], v1[3]);
;                     *(u32x4*)(rowp + bj * HALF) = w; } }
;     }
	v_lshl_add_u32 v146, s6, 8, v1
	v_lshl_or_b32 v148, s46, 8, v143
	v_ashrrev_i32_e32 v149, 31, v148
	v_ashrrev_i32_e32 v147, 31, v146
	v_lshl_add_u64 v[148:149], v[148:149], 1, s[4:5]
	v_lshlrev_b64 v[150:151], 14, v[146:147]
	v_lshl_add_u64 v[150:151], v[148:149], 0, v[150:151]
	s_mov_b32 s6, 0x200000
	s_mov_b64 s[16:17], 0x200000
	v_cvt_pk_bf16_f32 v62, v62, v63
	v_cvt_pk_bf16_f32 v63, v64, v65
	v_cvt_pk_bf16_f32 v64, v58, v59
	v_add_co_u32_e32 v58, vcc, s6, v150
	v_cvt_pk_bf16_f32 v70, v70, v71
	v_cvt_pk_bf16_f32 v71, v72, v73
	v_cvt_pk_bf16_f32 v72, v66, v67
	v_lshl_add_u64 v[66:67], v[150:151], 0, s[16:17]
	v_addc_co_u32_e32 v59, vcc, 0, v151, vcc
	v_cvt_pk_bf16_f32 v46, v46, v47
	v_cvt_pk_bf16_f32 v47, v48, v49
	v_cvt_pk_bf16_f32 v48, v42, v43
	v_cvt_pk_bf16_f32 v49, v44, v45
	s_mov_b32 s6, 0x240000
	global_store_dwordx4 v[66:67], v[46:49], off offset:256
	s_mov_b64 s[16:17], 0x240000
	v_cvt_pk_bf16_f32 v110, v110, v111
	v_add_co_u32_e32 v48, vcc, s6, v150
	v_cvt_pk_bf16_f32 v111, v112, v113
	v_cvt_pk_bf16_f32 v112, v106, v107
	v_or_b32_e32 v106, 16, v146
	v_lshl_add_u64 v[46:47], v[150:151], 0, s[16:17]
	v_addc_co_u32_e32 v49, vcc, 0, v151, vcc
	v_cvt_pk_bf16_f32 v30, v30, v31
	v_cvt_pk_bf16_f32 v31, v32, v33
	v_cvt_pk_bf16_f32 v32, v26, v27
	v_cvt_pk_bf16_f32 v33, v28, v29
	s_mov_b32 s6, 0x280000
	v_ashrrev_i32_e32 v107, 31, v106
	v_cvt_pk_bf16_f32 v94, v94, v95
	v_cvt_pk_bf16_f32 v95, v96, v97
	v_cvt_pk_bf16_f32 v96, v90, v91
	v_or_b32_e32 v90, 32, v146
	global_store_dwordx4 v[46:47], v[30:33], off offset:256
	s_mov_b64 s[16:17], 0x280000
	v_cvt_pk_bf16_f32 v113, v108, v109
	v_add_co_u32_e32 v32, vcc, s6, v150
	v_lshlrev_b64 v[106:107], 14, v[106:107]
	v_ashrrev_i32_e32 v91, 31, v90
	v_cvt_pk_bf16_f32 v78, v78, v79
	v_cvt_pk_bf16_f32 v79, v80, v81
	v_cvt_pk_bf16_f32 v80, v74, v75
	v_or_b32_e32 v74, 48, v146
	v_lshl_add_u64 v[30:31], v[150:151], 0, s[16:17]
	v_addc_co_u32_e32 v33, vcc, 0, v151, vcc
	v_cvt_pk_bf16_f32 v14, v14, v15
	v_cvt_pk_bf16_f32 v15, v16, v17
	v_cvt_pk_bf16_f32 v16, v10, v11
	v_cvt_pk_bf16_f32 v17, v12, v13
	global_store_dwordx4 v[150:151], v[110:113], off offset:256
	v_cvt_pk_bf16_f32 v97, v92, v93
	v_lshlrev_b64 v[90:91], 14, v[90:91]
	v_lshl_add_u64 v[110:111], v[148:149], 0, v[106:107]
	v_ashrrev_i32_e32 v75, 31, v74
	global_store_dwordx4 v[30:31], v[14:17], off offset:256
	global_store_dwordx4 v[110:111], v[94:97], off offset:256
	v_cvt_pk_bf16_f32 v81, v76, v77
	v_add_co_u32_e32 v16, vcc, s33, v150
	v_lshl_add_u64 v[94:95], v[148:149], 0, v[90:91]
	v_lshlrev_b64 v[74:75], 14, v[74:75]
	s_mov_b64 s[16:17], 0x2c0000
	v_addc_co_u32_e32 v17, vcc, 0, v151, vcc
	v_cvt_pk_bf16_f32 v126, v126, v127
	v_cvt_pk_bf16_f32 v127, v128, v129
	v_cvt_pk_bf16_f32 v128, v122, v123
	v_cvt_pk_bf16_f32 v129, v124, v125
	v_cvt_pk_bf16_f32 v106, v118, v119
	v_cvt_pk_bf16_f32 v107, v120, v121
	v_cvt_pk_bf16_f32 v108, v114, v115
	v_cvt_pk_bf16_f32 v109, v116, v117
	v_cvt_pk_bf16_f32 v90, v102, v103
	v_cvt_pk_bf16_f32 v91, v104, v105
	v_cvt_pk_bf16_f32 v92, v98, v99
	v_cvt_pk_bf16_f32 v93, v100, v101
	global_store_dwordx4 v[94:95], v[78:81], off offset:256
	v_cvt_pk_bf16_f32 v76, v82, v83
	v_cvt_pk_bf16_f32 v77, v84, v85
	v_lshl_add_u64 v[78:79], v[148:149], 0, v[74:75]
	v_cvt_pk_bf16_f32 v74, v86, v87
	v_cvt_pk_bf16_f32 v75, v88, v89
	v_cvt_pk_bf16_f32 v73, v68, v69
	v_cvt_pk_bf16_f32 v65, v60, v61
	v_cvt_pk_bf16_f32 v42, v54, v55
	v_cvt_pk_bf16_f32 v43, v56, v57
	v_cvt_pk_bf16_f32 v44, v50, v51
	v_cvt_pk_bf16_f32 v45, v52, v53
	v_cvt_pk_bf16_f32 v26, v38, v39
	v_cvt_pk_bf16_f32 v27, v40, v41
	v_cvt_pk_bf16_f32 v28, v34, v35
	v_cvt_pk_bf16_f32 v29, v36, v37
	v_lshl_add_u64 v[14:15], v[150:151], 0, s[16:17]
	v_cvt_pk_bf16_f32 v10, v22, v23
	v_cvt_pk_bf16_f32 v11, v24, v25
	v_cvt_pk_bf16_f32 v12, v18, v19
	v_cvt_pk_bf16_f32 v13, v20, v21
	v_cvt_pk_bf16_f32 v6, v6, v7
	v_cvt_pk_bf16_f32 v7, v8, v9
	v_cvt_pk_bf16_f32 v8, v2, v3
	v_cvt_pk_bf16_f32 v9, v4, v5
	s_and_b64 vcc, exec, s[0:1]
	s_mov_b32 s46, s8
	s_mov_b32 s6, s10
	s_mov_b64 s[16:17], s[14:15]
	s_mov_b64 s[18:19], s[12:13]
	s_mov_b32 s39, 0xb2a5705f
	s_mov_b32 s38, 0x42ce8ed0
	s_mov_b64 s[52:53], 0x41000
	global_store_dwordx4 v[150:151], v[126:129], off
	global_store_dwordx4 v[110:111], v[106:109], off
	global_store_dwordx4 v[94:95], v[90:93], off
	global_store_dwordx4 v[78:79], v[74:77], off
	global_store_dwordx4 v[78:79], v[70:73], off offset:256
	global_store_dwordx4 v[58:59], v[62:65], off
	global_store_dwordx4 v[48:49], v[42:45], off
	global_store_dwordx4 v[32:33], v[26:29], off
	global_store_dwordx4 v[16:17], v[10:13], off
	global_store_dwordx4 v[14:15], v[6:9], off offset:256
	s_cbranch_vccz .LBB0_195
	s_waitcnt vmcnt(0)
	s_cmpk_gt_u32 s25, 0xff
	s_cbranch_scc1 .LBB0_206
	s_barrier

; #define PG8_STAGE(bufoff, gbase, voff) do { _Pragma("unroll") for (int _i = 0; _i < 2; ++_i) \
;         __builtin_amdgcn_global_load_lds((const unsigned*)((const char*)(gbase) + (voff)[_i]), (LAS unsigned*)(lds + (bufoff) + ldsw + _i * 8192), 16, 0, 0); } while (0)
; #define PG8_LDA(dst, b, h) do { _Pragma("unroll") for (int m = 0; m < 4; ++m) _Pragma("unroll") for (int k = 0; k < 2; ++k) dst[m][k] = *(const LAS bf16x8*)(lds + PG8_SA(b, h) + aoff + m * 2048 + k * 1024); } while (0)
; #define PG8_LDB(dst, b, h) do { _Pragma("unroll") for (int n = 0; n < 2; ++n) _Pragma("unroll") for (int k = 0; k < 2; ++k) dst[n][k] = *(const LAS bf16x8*)(lds + PG8_SB(b, h) + boff + n * 2048 + k * 1024); } while (0)
; #define PG8_MMA(ai, bj, At, Bt) do { __builtin_amdgcn_s_setprio(1); _Pragma("unroll") for (int m = 0; m < 4; ++m) _Pragma("unroll") for (int n = 0; n < 2; ++n) _Pragma("unroll") for (int k = 0; k < 2; ++k) \
;         acc[ai][bj][m][n] = __builtin_amdgcn_mfma_f32_16x16x32_bf16(Bt[n][k], At[m][k], acc[ai][bj][m][n], 0, 0, 0); __builtin_amdgcn_s_setprio(0); } while (0)
; #define PG8_WAIT_V(n) asm volatile("s_waitcnt vmcnt(" #n ")" ::: "memory")
; #define PG8_WAIT_L(n) asm volatile("s_waitcnt lgkmcnt(" #n ")" ::: "memory")
; #define PG8_BAR __builtin_amdgcn_s_barrier()
; #define PG8_SCHED __builtin_amdgcn_sched_barrier(0)
; template <class Epi, class Sched, bool AREMAP>
; __device__ __forceinline__ void gemm_phase(LAS unsigned char* lds, const Gemm g, const Sched& S, const Epi& E, int wv) {
;     ...
;             const char* a1 = cA + (size_t)(t + 1) * kstep;
;             const char* a2 = last ? nA : cA + (size_t)(t + 2) * kstep; const char* b2 = last ? nB : cB + (size_t)(t + 2) * kstep;
;             const char* a3 = a2 + kstep; const char* b3 = b2 + kstep;
;             PG8_LDB(B0, 0, 0); PG8_SCHED; PG8_LDA(At, 0, 0); PG8_STAGE(PG8_SA(1, 1), a1 + hstepA, voffA);
;             PG8_WAIT_L(8); PG8_BAR; PG8_WAIT_L(0); PG8_MMA(0, 0, At, B0); PG8_BAR; PG8_SCHED;
;             PG8_LDB(B1, 0, 1); PG8_STAGE(PG8_SB(0, 0), b2, voffB);
;             PG8_BAR; PG8_WAIT_L(0); PG8_MMA(0, 1, At, B1); PG8_BAR;
;             PG8_LDA(At, 0, 1); PG8_STAGE(PG8_SA(0, 0), a2, voffA);
;             PG8_BAR; PG8_WAIT_L(0); PG8_MMA(1, 0, At, B0); PG8_BAR; PG8_SCHED;
;             PG8_STAGE(PG8_SB(0, 1), b2 + hstepB, voffB);
;             PG8_WAIT_V(6); PG8_BAR; PG8_MMA(1, 1, At, B1); PG8_BAR;
.LBB0_397:
	s_add_u32 s14, s2, 0xfffc0080
	s_addc_u32 s15, s3, -1
	s_add_i32 s38, 0, 0x10000
	v_add_u32_e32 v145, s38, v142
	ds_read_b128 v[146:149], v145
	ds_read_b128 v[150:153], v145 offset:1024
	ds_read_b128 v[154:157], v145 offset:2048
	ds_read_b128 v[158:161], v145 offset:3072
	s_cmp_eq_u32 s53, 12
	s_cselect_b32 s17, s11, s15
	s_cselect_b32 s16, s10, s14
	s_cselect_b32 s15, s7, s52
	s_cselect_b32 s14, s9, s47
	s_add_i32 m0, s5, 0xc000
	ds_read_b128 v[162:165], v144
	ds_read_b128 v[166:169], v144 offset:1024
	ds_read_b128 v[170:173], v144 offset:2048
	ds_read_b128 v[174:177], v144 offset:3072
	ds_read_b128 v[178:181], v144 offset:4096
	ds_read_b128 v[182:185], v144 offset:5120
	ds_read_b128 v[192:195], v144 offset:6144
	ds_read_b128 v[196:199], v144 offset:7168
	global_load_lds_dwordx4 v140, s[2:3]
	s_add_i32 m0, s5, 0xe000
	s_nop 0
	global_load_lds_dwordx4 v138, s[2:3]
	s_waitcnt lgkmcnt(8)
	s_barrier
	s_waitcnt lgkmcnt(0)
	v_mfma_f32_16x16x32_bf16 v[126:129], v[146:149], v[162:165], v[126:129]
	v_mfma_f32_16x16x32_bf16 v[122:125], v[154:157], v[162:165], v[122:125]
	v_mfma_f32_16x16x32_bf16 v[118:121], v[146:149], v[170:173], v[118:121]
	v_mfma_f32_16x16x32_bf16 v[114:117], v[154:157], v[170:173], v[114:117]
	v_mfma_f32_16x16x32_bf16 v[102:105], v[146:149], v[178:181], v[102:105]
	v_mfma_f32_16x16x32_bf16 v[98:101], v[154:157], v[178:181], v[98:101]
	v_mfma_f32_16x16x32_bf16 v[86:89], v[146:149], v[192:195], v[86:89]
	v_mfma_f32_16x16x32_bf16 v[82:85], v[154:157], v[192:195], v[82:85]
	v_mfma_f32_16x16x32_bf16 v[126:129], v[150:153], v[166:169], v[126:129]
	v_mfma_f32_16x16x32_bf16 v[122:125], v[158:161], v[166:169], v[122:125]
	v_mfma_f32_16x16x32_bf16 v[118:121], v[150:153], v[174:177], v[118:121]
	v_mfma_f32_16x16x32_bf16 v[114:117], v[158:161], v[174:177], v[114:117]
	v_mfma_f32_16x16x32_bf16 v[102:105], v[150:153], v[182:185], v[102:105]
	v_mfma_f32_16x16x32_bf16 v[98:101], v[158:161], v[182:185], v[98:101]
	v_mfma_f32_16x16x32_bf16 v[86:89], v[150:153], v[196:199], v[86:89]
	v_mfma_f32_16x16x32_bf16 v[82:85], v[158:161], v[196:199], v[82:85]
	s_barrier
	s_add_i32 s39, 0, 0x14000
	s_add_i32 s38, s38, s26
	v_add_u32_e32 v145, s39, v142
	s_add_u32 s80, s14, 0x80
	s_addc_u32 s81, s15, 0
	s_mov_b32 m0, s38
	ds_read_b128 v[200:203], v145
	ds_read_b128 v[204:207], v145 offset:1024
	ds_read_b128 v[208:211], v145 offset:2048
	ds_read_b128 v[212:215], v145 offset:3072
	global_load_lds_dwordx4 v134, s[14:15]
	s_add_i32 m0, s38, 0x2000
	s_nop 0
	global_load_lds_dwordx4 v130, s[14:15]
	s_barrier
	s_waitcnt lgkmcnt(0)
	v_mfma_f32_16x16x32_bf16 v[110:113], v[200:203], v[162:165], v[110:113]
	v_mfma_f32_16x16x32_bf16 v[106:109], v[208:211], v[162:165], v[106:109]
	v_mfma_f32_16x16x32_bf16 v[94:97], v[200:203], v[170:173], v[94:97]
	v_mfma_f32_16x16x32_bf16 v[90:93], v[208:211], v[170:173], v[90:93]
	v_mfma_f32_16x16x32_bf16 v[78:81], v[200:203], v[178:181], v[78:81]
	v_mfma_f32_16x16x32_bf16 v[74:77], v[208:211], v[178:181], v[74:77]
	v_mfma_f32_16x16x32_bf16 v[70:73], v[200:203], v[192:195], v[70:73]
	v_mfma_f32_16x16x32_bf16 v[66:69], v[208:211], v[192:195], v[66:69]
	v_mfma_f32_16x16x32_bf16 v[110:113], v[204:207], v[166:169], v[110:113]
	v_mfma_f32_16x16x32_bf16 v[106:109], v[212:215], v[166:169], v[106:109]
	v_mfma_f32_16x16x32_bf16 v[94:97], v[204:207], v[174:177], v[94:97]
	v_mfma_f32_16x16x32_bf16 v[90:93], v[212:215], v[174:177], v[90:93]
	v_mfma_f32_16x16x32_bf16 v[78:81], v[204:207], v[182:185], v[78:81]
	v_mfma_f32_16x16x32_bf16 v[74:77], v[212:215], v[182:185], v[74:77]
	v_mfma_f32_16x16x32_bf16 v[70:73], v[204:207], v[196:199], v[70:73]
	v_mfma_f32_16x16x32_bf16 v[66:69], v[212:215], v[196:199], v[66:69]
	s_mov_b32 m0, s5
	s_add_u32 s96, s16, 0x80
	s_addc_u32 s97, s17, 0
	s_barrier
	ds_read_b128 v[162:165], v144 offset:16384
	ds_read_b128 v[166:169], v144 offset:17408
	ds_read_b128 v[170:173], v144 offset:18432
	ds_read_b128 v[174:177], v144 offset:19456
	ds_read_b128 v[178:181], v144 offset:20480
	ds_read_b128 v[182:185], v144 offset:21504
	ds_read_b128 v[192:195], v144 offset:22528
	ds_read_b128 v[196:199], v144 offset:23552
	global_load_lds_dwordx4 v136, s[16:17]
	s_mov_b32 m0, s28
	s_nop 0
	global_load_lds_dwordx4 v132, s[16:17]
	s_barrier
	s_waitcnt lgkmcnt(0)
	v_mfma_f32_16x16x32_bf16 v[62:65], v[146:149], v[162:165], v[62:65]
	v_mfma_f32_16x16x32_bf16 v[58:61], v[154:157], v[162:165], v[58:61]
	v_mfma_f32_16x16x32_bf16 v[54:57], v[146:149], v[170:173], v[54:57]
	v_mfma_f32_16x16x32_bf16 v[50:53], v[154:157], v[170:173], v[50:53]
	v_mfma_f32_16x16x32_bf16 v[38:41], v[146:149], v[178:181], v[38:41]
	v_mfma_f32_16x16x32_bf16 v[34:37], v[154:157], v[178:181], v[34:37]
	v_mfma_f32_16x16x32_bf16 v[22:25], v[146:149], v[192:195], v[22:25]
	v_mfma_f32_16x16x32_bf16 v[18:21], v[154:157], v[192:195], v[18:21]
	v_mfma_f32_16x16x32_bf16 v[62:65], v[150:153], v[166:169], v[62:65]
	v_mfma_f32_16x16x32_bf16 v[58:61], v[158:161], v[166:169], v[58:61]
	v_mfma_f32_16x16x32_bf16 v[54:57], v[150:153], v[174:177], v[54:57]
	v_mfma_f32_16x16x32_bf16 v[50:53], v[158:161], v[174:177], v[50:53]
	v_mfma_f32_16x16x32_bf16 v[38:41], v[150:153], v[182:185], v[38:41]
	v_mfma_f32_16x16x32_bf16 v[34:37], v[158:161], v[182:185], v[34:37]
	v_mfma_f32_16x16x32_bf16 v[22:25], v[150:153], v[196:199], v[22:25]
	v_mfma_f32_16x16x32_bf16 v[18:21], v[158:161], v[196:199], v[18:21]
	s_barrier
	s_add_u32 s56, s14, 0x40000
	s_addc_u32 s57, s15, 0
	s_add_i32 s38, s39, s26
	s_mov_b32 m0, s38
	s_nop 0
	global_load_lds_dwordx4 v134, s[56:57]
	s_add_i32 m0, s38, 0x2000
	s_nop 0
	global_load_lds_dwordx4 v130, s[56:57]
	s_waitcnt vmcnt(6)
	s_barrier
; #define PG8_STAGE(bufoff, gbase, voff) do { _Pragma("unroll") for (int _i = 0; _i < 2; ++_i) \
;         __builtin_amdgcn_global_load_lds((const unsigned*)((const char*)(gbase) + (voff)[_i]), (LAS unsigned*)(lds + (bufoff) + ldsw + _i * 8192), 16, 0, 0); } while (0)
; #define PG8_LDA(dst, b, h) do { _Pragma("unroll") for (int m = 0; m < 4; ++m) _Pragma("unroll") for (int k = 0; k < 2; ++k) dst[m][k] = *(const LAS bf16x8*)(lds + PG8_SA(b, h) + aoff + m * 2048 + k * 1024); } while (0)
; #define PG8_LDB(dst, b, h) do { _Pragma("unroll") for (int n = 0; n < 2; ++n) _Pragma("unroll") for (int k = 0; k < 2; ++k) dst[n][k] = *(const LAS bf16x8*)(lds + PG8_SB(b, h) + boff + n * 2048 + k * 1024); } while (0)
; #define PG8_MMA(ai, bj, At, Bt) do { __builtin_amdgcn_s_setprio(1); _Pragma("unroll") for (int m = 0; m < 4; ++m) _Pragma("unroll") for (int n = 0; n < 2; ++n) _Pragma("unroll") for (int k = 0; k < 2; ++k) \
;         acc[ai][bj][m][n] = __builtin_amdgcn_mfma_f32_16x16x32_bf16(Bt[n][k], At[m][k], acc[ai][bj][m][n], 0, 0, 0); __builtin_amdgcn_s_setprio(0); } while (0)
; #define PG8_WAIT_V(n) asm volatile("s_waitcnt vmcnt(" #n ")" ::: "memory")
; #define PG8_WAIT_L(n) asm volatile("s_waitcnt lgkmcnt(" #n ")" ::: "memory")
; #define PG8_BAR __builtin_amdgcn_s_barrier()
; #define PG8_SCHED __builtin_amdgcn_sched_barrier(0)
; template <class Epi, class Sched, bool AREMAP>
; __device__ __forceinline__ void gemm_phase(LAS unsigned char* lds, const Gemm g, const Sched& S, const Epi& E, int wv) {
;     ...
;             PG8_WAIT_V(6); PG8_BAR; PG8_MMA(1, 1, At, B1); PG8_BAR;
;             PG8_LDB(B0, 1, 0); PG8_SCHED; PG8_LDA(At, 1, 0); PG8_STAGE(PG8_SA(0, 1), a2 + hstepA, voffA);
;             PG8_WAIT_L(8); PG8_BAR; PG8_WAIT_L(0); PG8_MMA(0, 0, At, B0); PG8_BAR; PG8_SCHED;
;             PG8_LDB(B1, 1, 1); PG8_STAGE(PG8_SB(1, 0), b3, voffB);
;             PG8_BAR; PG8_WAIT_L(0); PG8_MMA(0, 1, At, B1); PG8_BAR;
;             PG8_LDA(At, 1, 1); PG8_STAGE(PG8_SA(1, 0), a3, voffA);
	v_mfma_f32_16x16x32_bf16 v[46:49], v[200:203], v[162:165], v[46:49]
	v_mfma_f32_16x16x32_bf16 v[42:45], v[208:211], v[162:165], v[42:45]
	v_mfma_f32_16x16x32_bf16 v[30:33], v[200:203], v[170:173], v[30:33]
	v_mfma_f32_16x16x32_bf16 v[26:29], v[208:211], v[170:173], v[26:29]
	v_mfma_f32_16x16x32_bf16 v[14:17], v[200:203], v[178:181], v[14:17]
	v_mfma_f32_16x16x32_bf16 v[10:13], v[208:211], v[178:181], v[10:13]
	v_mfma_f32_16x16x32_bf16 v[6:9], v[200:203], v[192:195], v[6:9]
	v_mfma_f32_16x16x32_bf16 v[2:5], v[208:211], v[192:195], v[2:5]
	v_mfma_f32_16x16x32_bf16 v[46:49], v[204:207], v[166:169], v[46:49]
	v_mfma_f32_16x16x32_bf16 v[42:45], v[212:215], v[166:169], v[42:45]
	v_mfma_f32_16x16x32_bf16 v[30:33], v[204:207], v[174:177], v[30:33]
	v_mfma_f32_16x16x32_bf16 v[26:29], v[212:215], v[174:177], v[26:29]
	v_mfma_f32_16x16x32_bf16 v[14:17], v[204:207], v[182:185], v[14:17]
	v_mfma_f32_16x16x32_bf16 v[10:13], v[212:215], v[182:185], v[10:13]
	v_mfma_f32_16x16x32_bf16 v[6:9], v[204:207], v[196:199], v[6:9]
	v_mfma_f32_16x16x32_bf16 v[2:5], v[212:215], v[196:199], v[2:5]
	s_add_i32 s38, 0, 0x18000
	v_add_u32_e32 v145, s38, v142
	s_barrier
	ds_read_b128 v[146:149], v145
	ds_read_b128 v[150:153], v145 offset:1024
	ds_read_b128 v[154:157], v145 offset:2048
	ds_read_b128 v[158:161], v145 offset:3072
	s_add_u32 s16, s16, 0x40000
	s_addc_u32 s17, s17, 0
	s_mov_b32 m0, s29
	ds_read_b128 v[162:165], v144 offset:32768
	ds_read_b128 v[166:169], v144 offset:33792
	ds_read_b128 v[170:173], v144 offset:34816
	ds_read_b128 v[174:177], v144 offset:35840
	ds_read_b128 v[178:181], v144 offset:36864
	ds_read_b128 v[182:185], v144 offset:37888
	ds_read_b128 v[192:195], v144 offset:38912
	ds_read_b128 v[196:199], v144 offset:39936
	global_load_lds_dwordx4 v136, s[16:17]
	s_mov_b32 m0, s30
	s_nop 0
	global_load_lds_dwordx4 v132, s[16:17]
	s_waitcnt lgkmcnt(8)
	s_barrier
	s_waitcnt lgkmcnt(0)
	v_mfma_f32_16x16x32_bf16 v[126:129], v[146:149], v[162:165], v[126:129]
	v_mfma_f32_16x16x32_bf16 v[122:125], v[154:157], v[162:165], v[122:125]
	v_mfma_f32_16x16x32_bf16 v[118:121], v[146:149], v[170:173], v[118:121]
	v_mfma_f32_16x16x32_bf16 v[114:117], v[154:157], v[170:173], v[114:117]
	v_mfma_f32_16x16x32_bf16 v[102:105], v[146:149], v[178:181], v[102:105]
	v_mfma_f32_16x16x32_bf16 v[98:101], v[154:157], v[178:181], v[98:101]
	v_mfma_f32_16x16x32_bf16 v[86:89], v[146:149], v[192:195], v[86:89]
	v_mfma_f32_16x16x32_bf16 v[82:85], v[154:157], v[192:195], v[82:85]
	v_mfma_f32_16x16x32_bf16 v[126:129], v[150:153], v[166:169], v[126:129]
	v_mfma_f32_16x16x32_bf16 v[122:125], v[158:161], v[166:169], v[122:125]
	v_mfma_f32_16x16x32_bf16 v[118:121], v[150:153], v[174:177], v[118:121]
	v_mfma_f32_16x16x32_bf16 v[114:117], v[158:161], v[174:177], v[114:117]
	v_mfma_f32_16x16x32_bf16 v[102:105], v[150:153], v[182:185], v[102:105]
	v_mfma_f32_16x16x32_bf16 v[98:101], v[158:161], v[182:185], v[98:101]
	v_mfma_f32_16x16x32_bf16 v[86:89], v[150:153], v[196:199], v[86:89]
	v_mfma_f32_16x16x32_bf16 v[82:85], v[158:161], v[196:199], v[82:85]
	s_barrier
	s_add_i32 s16, 0, 0x1c000
	s_add_i32 s17, s38, s26
	v_add_u32_e32 v145, s16, v142
	s_mov_b32 m0, s17
	ds_read_b128 v[200:203], v145
	ds_read_b128 v[204:207], v145 offset:1024
	ds_read_b128 v[208:211], v145 offset:2048
	ds_read_b128 v[212:215], v145 offset:3072
	global_load_lds_dwordx4 v134, s[80:81]
	s_add_i32 m0, s17, 0x2000
	s_nop 0
	global_load_lds_dwordx4 v130, s[80:81]
	s_barrier
	s_waitcnt lgkmcnt(0)
	v_mfma_f32_16x16x32_bf16 v[110:113], v[200:203], v[162:165], v[110:113]
	v_mfma_f32_16x16x32_bf16 v[106:109], v[208:211], v[162:165], v[106:109]
	v_mfma_f32_16x16x32_bf16 v[94:97], v[200:203], v[170:173], v[94:97]
	v_mfma_f32_16x16x32_bf16 v[90:93], v[208:211], v[170:173], v[90:93]
	v_mfma_f32_16x16x32_bf16 v[78:81], v[200:203], v[178:181], v[78:81]
	v_mfma_f32_16x16x32_bf16 v[74:77], v[208:211], v[178:181], v[74:77]
	v_mfma_f32_16x16x32_bf16 v[70:73], v[200:203], v[192:195], v[70:73]
	v_mfma_f32_16x16x32_bf16 v[66:69], v[208:211], v[192:195], v[66:69]
	v_mfma_f32_16x16x32_bf16 v[110:113], v[204:207], v[166:169], v[110:113]
	v_mfma_f32_16x16x32_bf16 v[106:109], v[212:215], v[166:169], v[106:109]
	v_mfma_f32_16x16x32_bf16 v[94:97], v[204:207], v[174:177], v[94:97]
	v_mfma_f32_16x16x32_bf16 v[90:93], v[212:215], v[174:177], v[90:93]
	v_mfma_f32_16x16x32_bf16 v[78:81], v[204:207], v[182:185], v[78:81]
	v_mfma_f32_16x16x32_bf16 v[74:77], v[212:215], v[182:185], v[74:77]
	v_mfma_f32_16x16x32_bf16 v[70:73], v[204:207], v[196:199], v[70:73]
	v_mfma_f32_16x16x32_bf16 v[66:69], v[212:215], v[196:199], v[66:69]
	s_mov_b32 m0, s35
	s_barrier
	ds_read_b128 v[162:165], v144 offset:49152
	ds_read_b128 v[166:169], v144 offset:50176
	ds_read_b128 v[170:173], v144 offset:51200
	ds_read_b128 v[174:177], v144 offset:52224
	ds_read_b128 v[178:181], v144 offset:53248
	ds_read_b128 v[182:185], v144 offset:54272
	ds_read_b128 v[192:195], v144 offset:55296
	ds_read_b128 v[196:199], v144 offset:56320
	global_load_lds_dwordx4 v136, s[96:97]
	s_mov_b32 m0, s36
	s_nop 0
	global_load_lds_dwordx4 v132, s[96:97]
	s_barrier
; #define PG8_STAGE(bufoff, gbase, voff) do { _Pragma("unroll") for (int _i = 0; _i < 2; ++_i) \
;         __builtin_amdgcn_global_load_lds((const unsigned*)((const char*)(gbase) + (voff)[_i]), (LAS unsigned*)(lds + (bufoff) + ldsw + _i * 8192), 16, 0, 0); } while (0)
; #define PG8_MMA(ai, bj, At, Bt) do { __builtin_amdgcn_s_setprio(1); _Pragma("unroll") for (int m = 0; m < 4; ++m) _Pragma("unroll") for (int n = 0; n < 2; ++n) _Pragma("unroll") for (int k = 0; k < 2; ++k) \
;         acc[ai][bj][m][n] = __builtin_amdgcn_mfma_f32_16x16x32_bf16(Bt[n][k], At[m][k], acc[ai][bj][m][n], 0, 0, 0); __builtin_amdgcn_s_setprio(0); } while (0)
; #define PG8_WAIT_V(n) asm volatile("s_waitcnt vmcnt(" #n ")" ::: "memory")
; #define PG8_WAIT_L(n) asm volatile("s_waitcnt lgkmcnt(" #n ")" ::: "memory")
; #define PG8_BAR __builtin_amdgcn_s_barrier()
; #define PG8_SCHED __builtin_amdgcn_sched_barrier(0)
; template <class Epi, class Sched, bool AREMAP>
; __device__ __forceinline__ void gemm_phase(LAS unsigned char* lds, const Gemm g, const Sched& S, const Epi& E, int wv) {
;     ...
;             PG8_BAR; PG8_WAIT_L(0); PG8_MMA(1, 0, At, B0); PG8_BAR; PG8_SCHED;
;             PG8_STAGE(PG8_SB(1, 1), b3 + hstepB, voffB);
;             PG8_WAIT_V(6); PG8_BAR; PG8_MMA(1, 1, At, B1); PG8_BAR;
;         }
	s_waitcnt lgkmcnt(0)
	v_mfma_f32_16x16x32_bf16 v[62:65], v[146:149], v[162:165], v[62:65]
	v_mfma_f32_16x16x32_bf16 v[58:61], v[154:157], v[162:165], v[58:61]
	v_mfma_f32_16x16x32_bf16 v[54:57], v[146:149], v[170:173], v[54:57]
	v_mfma_f32_16x16x32_bf16 v[50:53], v[154:157], v[170:173], v[50:53]
	v_mfma_f32_16x16x32_bf16 v[38:41], v[146:149], v[178:181], v[38:41]
	v_mfma_f32_16x16x32_bf16 v[34:37], v[154:157], v[178:181], v[34:37]
	v_mfma_f32_16x16x32_bf16 v[22:25], v[146:149], v[192:195], v[22:25]
	v_mfma_f32_16x16x32_bf16 v[18:21], v[154:157], v[192:195], v[18:21]
	v_mfma_f32_16x16x32_bf16 v[62:65], v[150:153], v[166:169], v[62:65]
	v_mfma_f32_16x16x32_bf16 v[58:61], v[158:161], v[166:169], v[58:61]
	v_mfma_f32_16x16x32_bf16 v[54:57], v[150:153], v[174:177], v[54:57]
	v_mfma_f32_16x16x32_bf16 v[50:53], v[158:161], v[174:177], v[50:53]
	v_mfma_f32_16x16x32_bf16 v[38:41], v[150:153], v[182:185], v[38:41]
	v_mfma_f32_16x16x32_bf16 v[34:37], v[158:161], v[182:185], v[34:37]
	v_mfma_f32_16x16x32_bf16 v[22:25], v[150:153], v[196:199], v[22:25]
	v_mfma_f32_16x16x32_bf16 v[18:21], v[158:161], v[196:199], v[18:21]
	s_barrier
	s_add_u32 s14, s14, 0x40080
	s_addc_u32 s15, s15, 0
	s_add_i32 s16, s16, s26
	s_mov_b32 m0, s16
	s_nop 0
	global_load_lds_dwordx4 v134, s[14:15]
	s_add_i32 m0, s16, 0x2000
	s_nop 0
	global_load_lds_dwordx4 v130, s[14:15]
	s_waitcnt vmcnt(6)
	s_barrier
	v_mfma_f32_16x16x32_bf16 v[46:49], v[200:203], v[162:165], v[46:49]
	v_mfma_f32_16x16x32_bf16 v[42:45], v[208:211], v[162:165], v[42:45]
	v_mfma_f32_16x16x32_bf16 v[30:33], v[200:203], v[170:173], v[30:33]
	v_mfma_f32_16x16x32_bf16 v[26:29], v[208:211], v[170:173], v[26:29]
	v_mfma_f32_16x16x32_bf16 v[14:17], v[200:203], v[178:181], v[14:17]
	v_mfma_f32_16x16x32_bf16 v[10:13], v[208:211], v[178:181], v[10:13]
	v_mfma_f32_16x16x32_bf16 v[6:9], v[200:203], v[192:195], v[6:9]
	v_mfma_f32_16x16x32_bf16 v[2:5], v[208:211], v[192:195], v[2:5]
	v_mfma_f32_16x16x32_bf16 v[46:49], v[204:207], v[166:169], v[46:49]
	v_mfma_f32_16x16x32_bf16 v[42:45], v[212:215], v[166:169], v[42:45]
	v_mfma_f32_16x16x32_bf16 v[30:33], v[204:207], v[174:177], v[30:33]
	v_mfma_f32_16x16x32_bf16 v[26:29], v[212:215], v[174:177], v[26:29]
	v_mfma_f32_16x16x32_bf16 v[14:17], v[204:207], v[182:185], v[14:17]
	v_mfma_f32_16x16x32_bf16 v[10:13], v[212:215], v[182:185], v[10:13]
	v_mfma_f32_16x16x32_bf16 v[6:9], v[204:207], v[196:199], v[6:9]
	v_mfma_f32_16x16x32_bf16 v[2:5], v[212:215], v[196:199], v[2:5]
	s_add_i32 s53, s53, 2
	s_add_u32 s47, s47, 0x100
	s_addc_u32 s52, s52, 0
	s_add_u32 s2, s2, 0x100
	s_addc_u32 s3, s3, 0
	s_cmp_gt_u32 s53, 13
	s_barrier
	s_cbranch_scc0 .LBB0_397
; __device__ __forceinline__ unsigned cvt_pk_bf16(float lo, float hi) { f32x2_t f = {lo, hi}; bf16x2_t v = __builtin_convertvector(f, bf16x2_t); return __builtin_bit_cast(unsigned, v); }
;     __device__ __forceinline__ void operator()(const f32x4 (&acc)[2][2][4][2], const Unit& u, int wr, int wc, int fr, int fq) const {
;         const int row0 = u.pm * BM + wr * 64 + fr; int colt = u.pn * BM; bf16_t* base = O;
;         if (split_cols) { const int t = colt / split_cols; base += (size_t)t * split_stride; colt -= t * split_cols; }
;         const int col0 = colt + wc * 32 + 8 * fq;
; #pragma unroll
;         for (int ai = 0; ai < 2; ++ai)
; #pragma unroll
;             for (int m = 0; m < 4; ++m) { bf16_t* rowp = base + (size_t)(row0 + ai * HALF + m * 16) * ldc + col0;
; #pragma unroll
;                 for (int bj = 0; bj < 2; ++bj) { const f32x4 v0 = acc[ai][bj][m][0], v1 = acc[ai][bj][m][1];
;                     u32x4 w; w.x = cvt_pk_bf16(v0[0], v0[1]); w.y = cvt_pk_bf16(v0[2], v0[3]); w.z = cvt_pk_bf16(v1[0], v1[1]); w.w = cvt_pk_bf16(v1[2], v1[3]);
;                     *(u32x4*)(rowp + bj * HALF) = w; } }
;     }
	s_ashr_i32 s2, s46, 31
	s_lshr_b32 s2, s2, 29
	s_add_i32 s2, s46, s2
	s_ashr_i32 s2, s2, 3
	s_ashr_i32 s3, s2, 31
	s_lshl_b32 s7, s46, 8
	s_lshl_b64 s[14:15], s[2:3], 27
	s_add_u32 s14, s31, s14
	s_addc_u32 s15, s34, s15
	s_lshl_b32 s2, s2, 11
	s_sub_i32 s2, s7, s2
	v_lshl_add_u32 v146, s4, 8, v1
	v_or_b32_e32 v148, s2, v143
	v_ashrrev_i32_e32 v149, 31, v148
	v_ashrrev_i32_e32 v147, 31, v146
	v_lshl_add_u64 v[148:149], v[148:149], 1, s[14:15]
	v_lshlrev_b64 v[150:151], 12, v[146:147]
	v_lshl_add_u64 v[150:151], v[148:149], 0, v[150:151]
	s_mov_b64 s[2:3], 0x80000
	v_cvt_pk_bf16_f32 v70, v70, v71
	v_cvt_pk_bf16_f32 v71, v72, v73
	v_cvt_pk_bf16_f32 v72, v66, v67
	v_lshl_add_u64 v[66:67], v[150:151], 0, s[2:3]
	s_mov_b32 s2, 0x80000
	v_cvt_pk_bf16_f32 v62, v62, v63
	v_cvt_pk_bf16_f32 v63, v64, v65
	v_cvt_pk_bf16_f32 v64, v58, v59
	v_add_co_u32_e32 v58, vcc, s2, v150
	v_cvt_pk_bf16_f32 v46, v46, v47
	v_cvt_pk_bf16_f32 v47, v48, v49
	v_cvt_pk_bf16_f32 v48, v42, v43
	v_cvt_pk_bf16_f32 v49, v44, v45
	s_mov_b64 s[2:3], 0x90000
	v_addc_co_u32_e32 v59, vcc, 0, v151, vcc
	global_store_dwordx4 v[66:67], v[46:49], off offset:256
	v_cvt_pk_bf16_f32 v30, v30, v31
	v_cvt_pk_bf16_f32 v31, v32, v33
	v_lshl_add_u64 v[46:47], v[150:151], 0, s[2:3]
	s_mov_b32 s2, 0x90000
	v_add_co_u32_e32 v48, vcc, s2, v150
	v_cvt_pk_bf16_f32 v32, v26, v27
	v_cvt_pk_bf16_f32 v33, v28, v29
	s_mov_b64 s[2:3], 0xa0000
	v_cvt_pk_bf16_f32 v110, v110, v111
	v_cvt_pk_bf16_f32 v111, v112, v113
	v_cvt_pk_bf16_f32 v112, v106, v107
	v_or_b32_e32 v106, 16, v146
	v_addc_co_u32_e32 v49, vcc, 0, v151, vcc
	global_store_dwordx4 v[46:47], v[30:33], off offset:256
	v_ashrrev_i32_e32 v107, 31, v106
	v_cvt_pk_bf16_f32 v94, v94, v95
	v_lshl_add_u64 v[30:31], v[150:151], 0, s[2:3]
	s_mov_b32 s2, 0xa0000
	v_cvt_pk_bf16_f32 v95, v96, v97
	v_cvt_pk_bf16_f32 v96, v90, v91
	v_or_b32_e32 v90, 32, v146
	v_add_co_u32_e32 v32, vcc, s2, v150
	v_cvt_pk_bf16_f32 v14, v14, v15
	v_cvt_pk_bf16_f32 v15, v16, v17
	v_cvt_pk_bf16_f32 v16, v10, v11
	v_cvt_pk_bf16_f32 v17, v12, v13
	s_mov_b64 s[2:3], 0xb0000
	v_cvt_pk_bf16_f32 v113, v108, v109
	v_lshlrev_b64 v[106:107], 12, v[106:107]
	v_ashrrev_i32_e32 v91, 31, v90
	v_cvt_pk_bf16_f32 v78, v78, v79
	v_cvt_pk_bf16_f32 v79, v80, v81
	v_cvt_pk_bf16_f32 v80, v74, v75
	v_or_b32_e32 v74, 48, v146
	v_addc_co_u32_e32 v33, vcc, 0, v151, vcc
	global_store_dwordx4 v[30:31], v[14:17], off offset:256
	global_store_dwordx4 v[150:151], v[110:113], off offset:256
	v_cvt_pk_bf16_f32 v97, v92, v93
	v_lshl_add_u64 v[14:15], v[150:151], 0, s[2:3]
	s_mov_b32 s2, 0xb0000
	v_lshl_add_u64 v[110:111], v[148:149], 0, v[106:107]
	v_lshlrev_b64 v[90:91], 12, v[90:91]
	v_ashrrev_i32_e32 v75, 31, v74
	v_add_co_u32_e32 v16, vcc, s2, v150
	global_store_dwordx4 v[110:111], v[94:97], off offset:256
	v_cvt_pk_bf16_f32 v81, v76, v77
	v_lshlrev_b64 v[74:75], 12, v[74:75]
	v_lshl_add_u64 v[94:95], v[148:149], 0, v[90:91]
	v_addc_co_u32_e32 v17, vcc, 0, v151, vcc
	v_cvt_pk_bf16_f32 v126, v126, v127
	v_cvt_pk_bf16_f32 v127, v128, v129
	v_cvt_pk_bf16_f32 v128, v122, v123
	v_cvt_pk_bf16_f32 v129, v124, v125
	v_cvt_pk_bf16_f32 v106, v118, v119
	v_cvt_pk_bf16_f32 v107, v120, v121
	v_cvt_pk_bf16_f32 v108, v114, v115
	v_cvt_pk_bf16_f32 v109, v116, v117
	v_cvt_pk_bf16_f32 v90, v102, v103
	v_cvt_pk_bf16_f32 v91, v104, v105
	v_cvt_pk_bf16_f32 v92, v98, v99
	v_cvt_pk_bf16_f32 v93, v100, v101
	global_store_dwordx4 v[94:95], v[78:81], off offset:256
	v_cvt_pk_bf16_f32 v76, v82, v83
	v_cvt_pk_bf16_f32 v77, v84, v85
	v_lshl_add_u64 v[78:79], v[148:149], 0, v[74:75]
	v_cvt_pk_bf16_f32 v74, v86, v87
	v_cvt_pk_bf16_f32 v75, v88, v89
	v_cvt_pk_bf16_f32 v73, v68, v69
	v_cvt_pk_bf16_f32 v65, v60, v61
	v_cvt_pk_bf16_f32 v42, v54, v55
	v_cvt_pk_bf16_f32 v43, v56, v57
	v_cvt_pk_bf16_f32 v44, v50, v51
	v_cvt_pk_bf16_f32 v45, v52, v53
	v_cvt_pk_bf16_f32 v26, v38, v39
	v_cvt_pk_bf16_f32 v27, v40, v41
	v_cvt_pk_bf16_f32 v28, v34, v35
	v_cvt_pk_bf16_f32 v29, v36, v37
	v_cvt_pk_bf16_f32 v10, v22, v23
	v_cvt_pk_bf16_f32 v11, v24, v25
	v_cvt_pk_bf16_f32 v12, v18, v19
	v_cvt_pk_bf16_f32 v13, v20, v21
	v_cvt_pk_bf16_f32 v6, v6, v7
	v_cvt_pk_bf16_f32 v7, v8, v9
	v_cvt_pk_bf16_f32 v8, v2, v3
	v_cvt_pk_bf16_f32 v9, v4, v5
	s_and_b64 vcc, exec, s[0:1]
	s_mov_b32 s46, s6
	s_mov_b32 s4, s8
	s_mov_b64 s[14:15], s[12:13]
	s_mov_b64 s[16:17], s[10:11]
	s_mov_b32 s39, 0xb2a5705f
	global_store_dwordx4 v[150:151], v[126:129], off
	global_store_dwordx4 v[110:111], v[106:109], off
	global_store_dwordx4 v[94:95], v[90:93], off
	global_store_dwordx4 v[78:79], v[74:77], off
	global_store_dwordx4 v[78:79], v[70:73], off offset:256
	global_store_dwordx4 v[58:59], v[62:65], off
	global_store_dwordx4 v[48:49], v[42:45], off
	global_store_dwordx4 v[32:33], v[26:29], off
	global_store_dwordx4 v[16:17], v[10:13], off
	global_store_dwordx4 v[14:15], v[6:9], off offset:256
	s_cbranch_vccz .LBB0_392
	s_waitcnt vmcnt(0)
	s_cmpk_gt_u32 s20, 0xff
	v_readlane_b32 s31, v254, 22
	v_readlane_b32 s33, v254, 23
	s_mov_b32 s41, 0xe020
	s_cbranch_scc1 .LBB0_401
	s_barrier

; #define PG8_STAGE(bufoff, gbase, voff) do { _Pragma("unroll") for (int _i = 0; _i < 2; ++_i) \
;         __builtin_amdgcn_global_load_lds((const unsigned*)((const char*)(gbase) + (voff)[_i]), (LAS unsigned*)(lds + (bufoff) + ldsw + _i * 8192), 16, 0, 0); } while (0)
; #define PG8_LDA(dst, b, h) do { _Pragma("unroll") for (int m = 0; m < 4; ++m) _Pragma("unroll") for (int k = 0; k < 2; ++k) dst[m][k] = *(const LAS bf16x8*)(lds + PG8_SA(b, h) + aoff + m * 2048 + k * 1024); } while (0)
; #define PG8_LDB(dst, b, h) do { _Pragma("unroll") for (int n = 0; n < 2; ++n) _Pragma("unroll") for (int k = 0; k < 2; ++k) dst[n][k] = *(const LAS bf16x8*)(lds + PG8_SB(b, h) + boff + n * 2048 + k * 1024); } while (0)
; #define PG8_MMA(ai, bj, At, Bt) do { __builtin_amdgcn_s_setprio(1); _Pragma("unroll") for (int m = 0; m < 4; ++m) _Pragma("unroll") for (int n = 0; n < 2; ++n) _Pragma("unroll") for (int k = 0; k < 2; ++k) \
;         acc[ai][bj][m][n] = __builtin_amdgcn_mfma_f32_16x16x32_bf16(Bt[n][k], At[m][k], acc[ai][bj][m][n], 0, 0, 0); __builtin_amdgcn_s_setprio(0); } while (0)
; #define PG8_WAIT_V(n) asm volatile("s_waitcnt vmcnt(" #n ")" ::: "memory")
; #define PG8_WAIT_L(n) asm volatile("s_waitcnt lgkmcnt(" #n ")" ::: "memory")
; #define PG8_BAR __builtin_amdgcn_s_barrier()
; #define PG8_SCHED __builtin_amdgcn_sched_barrier(0)
; template <class Epi, class Sched, bool AREMAP>
; __device__ __forceinline__ void gemm_phase(LAS unsigned char* lds, const Gemm g, const Sched& S, const Epi& E, int wv) {
;     ...
;             const char* a1 = cA + (size_t)(t + 1) * kstep;
;             const char* a2 = last ? nA : cA + (size_t)(t + 2) * kstep; const char* b2 = last ? nB : cB + (size_t)(t + 2) * kstep;
;             const char* a3 = a2 + kstep; const char* b3 = b2 + kstep;
;             PG8_LDB(B0, 0, 0); PG8_SCHED; PG8_LDA(At, 0, 0); PG8_STAGE(PG8_SA(1, 1), a1 + hstepA, voffA);
;             PG8_WAIT_L(8); PG8_BAR; PG8_WAIT_L(0); PG8_MMA(0, 0, At, B0); PG8_BAR; PG8_SCHED;
;             PG8_LDB(B1, 0, 1); PG8_STAGE(PG8_SB(0, 0), b2, voffB);
;             PG8_BAR; PG8_WAIT_L(0); PG8_MMA(0, 1, At, B1); PG8_BAR;
;             PG8_LDA(At, 0, 1); PG8_STAGE(PG8_SA(0, 0), a2, voffA);
;             PG8_BAR; PG8_WAIT_L(0); PG8_MMA(1, 0, At, B0); PG8_BAR; PG8_SCHED;
;             PG8_STAGE(PG8_SB(0, 1), b2 + hstepB, voffB);
;             PG8_WAIT_V(6); PG8_BAR; PG8_MMA(1, 1, At, B1); PG8_BAR;
.LBB0_426:
	s_add_u32 s20, s18, 0xfff80080
	s_addc_u32 s21, s19, -1
	s_add_i32 s38, 0, 0x10000
	v_add_u32_e32 v142, s38, v186
	ds_read_b128 v[130:133], v142
	ds_read_b128 v[134:137], v142 offset:1024
	ds_read_b128 v[138:141], v142 offset:2048
	ds_read_b128 v[142:145], v142 offset:3072
	s_cmp_eq_u32 s46, 28
	s_cselect_b32 s23, s3, s21
	s_cselect_b32 s22, s5, s20
	s_cselect_b32 s21, s11, s37
	s_cselect_b32 s20, s13, s36
	s_add_i32 m0, s35, 0xc000
	ds_read_b128 v[146:149], v196
	ds_read_b128 v[150:153], v196 offset:1024
	ds_read_b128 v[154:157], v196 offset:2048
	ds_read_b128 v[158:161], v196 offset:3072
	ds_read_b128 v[174:177], v196 offset:4096
	ds_read_b128 v[178:181], v196 offset:5120
	ds_read_b128 v[182:185], v196 offset:6144
	ds_read_b128 v[192:195], v196 offset:7168
	global_load_lds_dwordx4 v172, s[18:19]
	s_add_i32 m0, s35, 0xe000
	s_nop 0
	global_load_lds_dwordx4 v170, s[18:19]
	s_waitcnt lgkmcnt(8)
	s_barrier
	s_waitcnt lgkmcnt(0)
	v_mfma_f32_16x16x32_bf16 v[126:129], v[130:133], v[146:149], v[126:129]
	v_mfma_f32_16x16x32_bf16 v[122:125], v[138:141], v[146:149], v[122:125]
	v_mfma_f32_16x16x32_bf16 v[110:113], v[130:133], v[154:157], v[110:113]
	v_mfma_f32_16x16x32_bf16 v[106:109], v[138:141], v[154:157], v[106:109]
	v_mfma_f32_16x16x32_bf16 v[94:97], v[130:133], v[174:177], v[94:97]
	v_mfma_f32_16x16x32_bf16 v[90:93], v[138:141], v[174:177], v[90:93]
	v_mfma_f32_16x16x32_bf16 v[78:81], v[130:133], v[182:185], v[78:81]
	v_mfma_f32_16x16x32_bf16 v[74:77], v[138:141], v[182:185], v[74:77]
	v_mfma_f32_16x16x32_bf16 v[126:129], v[134:137], v[150:153], v[126:129]
	v_mfma_f32_16x16x32_bf16 v[122:125], v[142:145], v[150:153], v[122:125]
	v_mfma_f32_16x16x32_bf16 v[110:113], v[134:137], v[158:161], v[110:113]
	v_mfma_f32_16x16x32_bf16 v[106:109], v[142:145], v[158:161], v[106:109]
	v_mfma_f32_16x16x32_bf16 v[94:97], v[134:137], v[178:181], v[94:97]
	v_mfma_f32_16x16x32_bf16 v[90:93], v[142:145], v[178:181], v[90:93]
	v_mfma_f32_16x16x32_bf16 v[78:81], v[134:137], v[192:195], v[78:81]
	v_mfma_f32_16x16x32_bf16 v[74:77], v[142:145], v[192:195], v[74:77]
	s_barrier
	s_add_i32 s39, 0, 0x14000
	s_add_i32 s38, s38, s34
	v_add_u32_e32 v197, s39, v186
	s_add_u32 s80, s20, 0x80
	s_addc_u32 s81, s21, 0
	s_mov_b32 m0, s38
	ds_read_b128 v[198:201], v197
	ds_read_b128 v[202:205], v197 offset:1024
	ds_read_b128 v[206:209], v197 offset:2048
	ds_read_b128 v[210:213], v197 offset:3072
	global_load_lds_dwordx4 v164, s[20:21]
	s_add_i32 m0, s38, 0x2000
	s_nop 0
	global_load_lds_dwordx4 v168, s[20:21]
	s_barrier
	s_waitcnt lgkmcnt(0)
	v_mfma_f32_16x16x32_bf16 v[118:121], v[198:201], v[146:149], v[118:121]
	v_mfma_f32_16x16x32_bf16 v[114:117], v[206:209], v[146:149], v[114:117]
	v_mfma_f32_16x16x32_bf16 v[102:105], v[198:201], v[154:157], v[102:105]
	v_mfma_f32_16x16x32_bf16 v[98:101], v[206:209], v[154:157], v[98:101]
	v_mfma_f32_16x16x32_bf16 v[86:89], v[198:201], v[174:177], v[86:89]
	v_mfma_f32_16x16x32_bf16 v[82:85], v[206:209], v[174:177], v[82:85]
	v_mfma_f32_16x16x32_bf16 v[70:73], v[198:201], v[182:185], v[70:73]
	v_mfma_f32_16x16x32_bf16 v[66:69], v[206:209], v[182:185], v[66:69]
	v_mfma_f32_16x16x32_bf16 v[118:121], v[202:205], v[150:153], v[118:121]
	v_mfma_f32_16x16x32_bf16 v[114:117], v[210:213], v[150:153], v[114:117]
	v_mfma_f32_16x16x32_bf16 v[102:105], v[202:205], v[158:161], v[102:105]
	v_mfma_f32_16x16x32_bf16 v[98:101], v[210:213], v[158:161], v[98:101]
	v_mfma_f32_16x16x32_bf16 v[86:89], v[202:205], v[178:181], v[86:89]
	v_mfma_f32_16x16x32_bf16 v[82:85], v[210:213], v[178:181], v[82:85]
	v_mfma_f32_16x16x32_bf16 v[70:73], v[202:205], v[192:195], v[70:73]
	v_mfma_f32_16x16x32_bf16 v[66:69], v[210:213], v[192:195], v[66:69]
	s_mov_b32 m0, s35
	s_add_u32 s96, s22, 0x80
	s_addc_u32 s97, s23, 0
	s_barrier
	ds_read_b128 v[146:149], v196 offset:16384
	ds_read_b128 v[150:153], v196 offset:17408
	ds_read_b128 v[154:157], v196 offset:18432
	ds_read_b128 v[158:161], v196 offset:19456
	ds_read_b128 v[174:177], v196 offset:20480
	ds_read_b128 v[178:181], v196 offset:21504
	ds_read_b128 v[182:185], v196 offset:22528
	ds_read_b128 v[192:195], v196 offset:23552
	global_load_lds_dwordx4 v162, s[22:23]
	s_mov_b32 m0, s41
	s_nop 0
	global_load_lds_dwordx4 v166, s[22:23]
	s_barrier
	s_waitcnt lgkmcnt(0)
	v_mfma_f32_16x16x32_bf16 v[62:65], v[130:133], v[146:149], v[62:65]
	v_mfma_f32_16x16x32_bf16 v[58:61], v[138:141], v[146:149], v[58:61]
	v_mfma_f32_16x16x32_bf16 v[46:49], v[130:133], v[154:157], v[46:49]
	v_mfma_f32_16x16x32_bf16 v[42:45], v[138:141], v[154:157], v[42:45]
	v_mfma_f32_16x16x32_bf16 v[30:33], v[130:133], v[174:177], v[30:33]
	v_mfma_f32_16x16x32_bf16 v[26:29], v[138:141], v[174:177], v[26:29]
	v_mfma_f32_16x16x32_bf16 v[14:17], v[130:133], v[182:185], v[14:17]
	v_mfma_f32_16x16x32_bf16 v[10:13], v[138:141], v[182:185], v[10:13]
	v_mfma_f32_16x16x32_bf16 v[62:65], v[134:137], v[150:153], v[62:65]
	v_mfma_f32_16x16x32_bf16 v[58:61], v[142:145], v[150:153], v[58:61]
	v_mfma_f32_16x16x32_bf16 v[46:49], v[134:137], v[158:161], v[46:49]
	v_mfma_f32_16x16x32_bf16 v[42:45], v[142:145], v[158:161], v[42:45]
	v_mfma_f32_16x16x32_bf16 v[30:33], v[134:137], v[178:181], v[30:33]
	v_mfma_f32_16x16x32_bf16 v[26:29], v[142:145], v[178:181], v[26:29]
	v_mfma_f32_16x16x32_bf16 v[14:17], v[134:137], v[192:195], v[14:17]
	v_mfma_f32_16x16x32_bf16 v[10:13], v[142:145], v[192:195], v[10:13]
	s_barrier
	s_add_u32 s66, s20, 0x80000
	s_addc_u32 s67, s21, 0
	s_add_i32 s38, s39, s34
	s_mov_b32 m0, s38
	s_nop 0
	global_load_lds_dwordx4 v164, s[66:67]
	s_add_i32 m0, s38, 0x2000
	s_nop 0
	global_load_lds_dwordx4 v168, s[66:67]
	s_waitcnt vmcnt(6)
	s_barrier
; #define PG8_STAGE(bufoff, gbase, voff) do { _Pragma("unroll") for (int _i = 0; _i < 2; ++_i) \
;         __builtin_amdgcn_global_load_lds((const unsigned*)((const char*)(gbase) + (voff)[_i]), (LAS unsigned*)(lds + (bufoff) + ldsw + _i * 8192), 16, 0, 0); } while (0)
; #define PG8_LDA(dst, b, h) do { _Pragma("unroll") for (int m = 0; m < 4; ++m) _Pragma("unroll") for (int k = 0; k < 2; ++k) dst[m][k] = *(const LAS bf16x8*)(lds + PG8_SA(b, h) + aoff + m * 2048 + k * 1024); } while (0)
; #define PG8_LDB(dst, b, h) do { _Pragma("unroll") for (int n = 0; n < 2; ++n) _Pragma("unroll") for (int k = 0; k < 2; ++k) dst[n][k] = *(const LAS bf16x8*)(lds + PG8_SB(b, h) + boff + n * 2048 + k * 1024); } while (0)
; #define PG8_MMA(ai, bj, At, Bt) do { __builtin_amdgcn_s_setprio(1); _Pragma("unroll") for (int m = 0; m < 4; ++m) _Pragma("unroll") for (int n = 0; n < 2; ++n) _Pragma("unroll") for (int k = 0; k < 2; ++k) \
;         acc[ai][bj][m][n] = __builtin_amdgcn_mfma_f32_16x16x32_bf16(Bt[n][k], At[m][k], acc[ai][bj][m][n], 0, 0, 0); __builtin_amdgcn_s_setprio(0); } while (0)
; #define PG8_WAIT_V(n) asm volatile("s_waitcnt vmcnt(" #n ")" ::: "memory")
; #define PG8_WAIT_L(n) asm volatile("s_waitcnt lgkmcnt(" #n ")" ::: "memory")
; #define PG8_BAR __builtin_amdgcn_s_barrier()
; #define PG8_SCHED __builtin_amdgcn_sched_barrier(0)
; template <class Epi, class Sched, bool AREMAP>
; __device__ __forceinline__ void gemm_phase(LAS unsigned char* lds, const Gemm g, const Sched& S, const Epi& E, int wv) {
;     ...
;             PG8_WAIT_V(6); PG8_BAR; PG8_MMA(1, 1, At, B1); PG8_BAR;
;             PG8_LDB(B0, 1, 0); PG8_SCHED; PG8_LDA(At, 1, 0); PG8_STAGE(PG8_SA(0, 1), a2 + hstepA, voffA);
;             PG8_WAIT_L(8); PG8_BAR; PG8_WAIT_L(0); PG8_MMA(0, 0, At, B0); PG8_BAR; PG8_SCHED;
;             PG8_LDB(B1, 1, 1); PG8_STAGE(PG8_SB(1, 0), b3, voffB);
;             PG8_BAR; PG8_WAIT_L(0); PG8_MMA(0, 1, At, B1); PG8_BAR;
	v_mfma_f32_16x16x32_bf16 v[54:57], v[198:201], v[146:149], v[54:57]
	v_mfma_f32_16x16x32_bf16 v[50:53], v[206:209], v[146:149], v[50:53]
	v_mfma_f32_16x16x32_bf16 v[38:41], v[198:201], v[154:157], v[38:41]
	v_mfma_f32_16x16x32_bf16 v[34:37], v[206:209], v[154:157], v[34:37]
	v_mfma_f32_16x16x32_bf16 v[22:25], v[198:201], v[174:177], v[22:25]
	v_mfma_f32_16x16x32_bf16 v[18:21], v[206:209], v[174:177], v[18:21]
	v_mfma_f32_16x16x32_bf16 v[6:9], v[198:201], v[182:185], v[6:9]
	v_mfma_f32_16x16x32_bf16 v[2:5], v[206:209], v[182:185], v[2:5]
	v_mfma_f32_16x16x32_bf16 v[54:57], v[202:205], v[150:153], v[54:57]
	v_mfma_f32_16x16x32_bf16 v[50:53], v[210:213], v[150:153], v[50:53]
	v_mfma_f32_16x16x32_bf16 v[38:41], v[202:205], v[158:161], v[38:41]
	v_mfma_f32_16x16x32_bf16 v[34:37], v[210:213], v[158:161], v[34:37]
	v_mfma_f32_16x16x32_bf16 v[22:25], v[202:205], v[178:181], v[22:25]
	v_mfma_f32_16x16x32_bf16 v[18:21], v[210:213], v[178:181], v[18:21]
	v_mfma_f32_16x16x32_bf16 v[6:9], v[202:205], v[192:195], v[6:9]
	v_mfma_f32_16x16x32_bf16 v[2:5], v[210:213], v[192:195], v[2:5]
	s_add_i32 s38, 0, 0x18000
	v_add_u32_e32 v142, s38, v186
	s_barrier
	ds_read_b128 v[130:133], v142
	ds_read_b128 v[134:137], v142 offset:1024
	ds_read_b128 v[138:141], v142 offset:2048
	ds_read_b128 v[142:145], v142 offset:3072
	s_add_u32 s22, s22, 0x80000
	s_addc_u32 s23, s23, 0
	s_mov_b32 m0, s52
	ds_read_b128 v[146:149], v196 offset:32768
	ds_read_b128 v[150:153], v196 offset:33792
	ds_read_b128 v[154:157], v196 offset:34816
	ds_read_b128 v[158:161], v196 offset:35840
	ds_read_b128 v[174:177], v196 offset:36864
	ds_read_b128 v[178:181], v196 offset:37888
	ds_read_b128 v[182:185], v196 offset:38912
	ds_read_b128 v[192:195], v196 offset:39936
	global_load_lds_dwordx4 v162, s[22:23]
	s_mov_b32 m0, s53
	s_nop 0
	global_load_lds_dwordx4 v166, s[22:23]
	s_waitcnt lgkmcnt(8)
	s_barrier
	s_waitcnt lgkmcnt(0)
	v_mfma_f32_16x16x32_bf16 v[126:129], v[130:133], v[146:149], v[126:129]
	v_mfma_f32_16x16x32_bf16 v[122:125], v[138:141], v[146:149], v[122:125]
	v_mfma_f32_16x16x32_bf16 v[110:113], v[130:133], v[154:157], v[110:113]
	v_mfma_f32_16x16x32_bf16 v[106:109], v[138:141], v[154:157], v[106:109]
	v_mfma_f32_16x16x32_bf16 v[94:97], v[130:133], v[174:177], v[94:97]
	v_mfma_f32_16x16x32_bf16 v[90:93], v[138:141], v[174:177], v[90:93]
	v_mfma_f32_16x16x32_bf16 v[78:81], v[130:133], v[182:185], v[78:81]
	v_mfma_f32_16x16x32_bf16 v[74:77], v[138:141], v[182:185], v[74:77]
	v_mfma_f32_16x16x32_bf16 v[126:129], v[134:137], v[150:153], v[126:129]
	v_mfma_f32_16x16x32_bf16 v[122:125], v[142:145], v[150:153], v[122:125]
	v_mfma_f32_16x16x32_bf16 v[110:113], v[134:137], v[158:161], v[110:113]
	v_mfma_f32_16x16x32_bf16 v[106:109], v[142:145], v[158:161], v[106:109]
	v_mfma_f32_16x16x32_bf16 v[94:97], v[134:137], v[178:181], v[94:97]
	v_mfma_f32_16x16x32_bf16 v[90:93], v[142:145], v[178:181], v[90:93]
	v_mfma_f32_16x16x32_bf16 v[78:81], v[134:137], v[192:195], v[78:81]
	v_mfma_f32_16x16x32_bf16 v[74:77], v[142:145], v[192:195], v[74:77]
	s_barrier
	s_add_i32 s22, 0, 0x1c000
	s_add_i32 s23, s38, s34
	v_add_u32_e32 v197, s22, v186
	s_mov_b32 m0, s23
	ds_read_b128 v[198:201], v197
	ds_read_b128 v[202:205], v197 offset:1024
	ds_read_b128 v[206:209], v197 offset:2048
	ds_read_b128 v[210:213], v197 offset:3072
	global_load_lds_dwordx4 v164, s[80:81]
	s_add_i32 m0, s23, 0x2000
	s_nop 0
	global_load_lds_dwordx4 v168, s[80:81]
	s_barrier
	s_waitcnt lgkmcnt(0)
	v_mfma_f32_16x16x32_bf16 v[118:121], v[198:201], v[146:149], v[118:121]
	v_mfma_f32_16x16x32_bf16 v[114:117], v[206:209], v[146:149], v[114:117]
	v_mfma_f32_16x16x32_bf16 v[102:105], v[198:201], v[154:157], v[102:105]
	v_mfma_f32_16x16x32_bf16 v[98:101], v[206:209], v[154:157], v[98:101]
	v_mfma_f32_16x16x32_bf16 v[86:89], v[198:201], v[174:177], v[86:89]
	v_mfma_f32_16x16x32_bf16 v[82:85], v[206:209], v[174:177], v[82:85]
	v_mfma_f32_16x16x32_bf16 v[70:73], v[198:201], v[182:185], v[70:73]
	v_mfma_f32_16x16x32_bf16 v[66:69], v[206:209], v[182:185], v[66:69]
	v_mfma_f32_16x16x32_bf16 v[118:121], v[202:205], v[150:153], v[118:121]
	v_mfma_f32_16x16x32_bf16 v[114:117], v[210:213], v[150:153], v[114:117]
	v_mfma_f32_16x16x32_bf16 v[102:105], v[202:205], v[158:161], v[102:105]
	v_mfma_f32_16x16x32_bf16 v[98:101], v[210:213], v[158:161], v[98:101]
	v_mfma_f32_16x16x32_bf16 v[86:89], v[202:205], v[178:181], v[86:89]
	v_mfma_f32_16x16x32_bf16 v[82:85], v[210:213], v[178:181], v[82:85]
	v_mfma_f32_16x16x32_bf16 v[70:73], v[202:205], v[192:195], v[70:73]
	v_mfma_f32_16x16x32_bf16 v[66:69], v[210:213], v[192:195], v[66:69]
	s_mov_b32 m0, s57
	s_barrier
; __device__ __forceinline__ int otid(int wv) { int t = (wv << 6) | (int)__builtin_amdgcn_mbcnt_hi(~0u, __builtin_amdgcn_mbcnt_lo(~0u, 0u)); asm volatile("" : "+v"(t)); return t; }
; #define PG8_STAGE(bufoff, gbase, voff) do { _Pragma("unroll") for (int _i = 0; _i < 2; ++_i) \
;         __builtin_amdgcn_global_load_lds((const unsigned*)((const char*)(gbase) + (voff)[_i]), (LAS unsigned*)(lds + (bufoff) + ldsw + _i * 8192), 16, 0, 0); } while (0)
; #define PG8_LDA(dst, b, h) do { _Pragma("unroll") for (int m = 0; m < 4; ++m) _Pragma("unroll") for (int k = 0; k < 2; ++k) dst[m][k] = *(const LAS bf16x8*)(lds + PG8_SA(b, h) + aoff + m * 2048 + k * 1024); } while (0)
; #define PG8_WAIT_V(n) asm volatile("s_waitcnt vmcnt(" #n ")" ::: "memory")
; #define PG8_WAIT_L(n) asm volatile("s_waitcnt lgkmcnt(" #n ")" ::: "memory")
; template <class Epi, class Sched, bool AREMAP>
; __device__ __forceinline__ void gemm_phase(LAS unsigned char* lds, const Gemm g, const Sched& S, const Epi& E, int wv) {
;     ...
;             PG8_LDA(At, 1, 1); PG8_STAGE(PG8_SA(1, 0), a3, voffA);
;             PG8_BAR; PG8_WAIT_L(0); PG8_MMA(1, 0, At, B0); PG8_BAR; PG8_SCHED;
;             PG8_STAGE(PG8_SB(1, 1), b3 + hstepB, voffB);
;             PG8_WAIT_V(6); PG8_BAR; PG8_MMA(1, 1, At, B1); PG8_BAR;
;         }
;     __device__ __forceinline__ void operator()(const f32x4 (&acc)[2][2][4][2], const Unit& u, int wr, int wc, int fr, int fq) const {
;         const int b = u.pn >> 3, pn8 = u.pn & 7;
;         const int row0 = u.pm * BM + wr * 64 + fr, col0 = pn8 * BM + wc * 32 + 8 * fq;
;         const bf16_t* yb = YB + (size_t)b * NTOK * DM;
;         u32x4* sc = (u32x4*)scratch + otid(wv);
; #pragma unroll
;         for (int ai = 0; ai < 2; ++ai)
; #pragma unroll
;             for (int mp = 0; mp < 2; ++mp) {
;                 u32x4 y[2][2], pr[2][2];
; #pragma unroll
;                 for (int mm = 0; mm < 2; ++mm)
; #pragma unroll
;                     for (int bj = 0; bj < 2; ++bj) { const int m = mp * 2 + mm; const size_t off = (size_t)(row0 + ai * HALF + m * 16) * DM + col0;
;                         y[mm][bj] = *(const u32x4*)(yb + off + bj * HALF);
;                         const int slot = (ai * 4 + m) * 2 + bj;
;                         pr[mm][bj] = (u32x4){0u, 0u, 0u, 0u};
;                         if (b > 0) pr[mm][bj] = sc[(size_t)slot * NTHR]; }
	ds_read_b128 v[146:149], v196 offset:49152
	ds_read_b128 v[150:153], v196 offset:50176
	ds_read_b128 v[154:157], v196 offset:51200
	ds_read_b128 v[158:161], v196 offset:52224
	ds_read_b128 v[174:177], v196 offset:53248
	ds_read_b128 v[178:181], v196 offset:54272
	ds_read_b128 v[182:185], v196 offset:55296
	ds_read_b128 v[192:195], v196 offset:56320
	global_load_lds_dwordx4 v162, s[96:97]
	s_mov_b32 m0, s62
	s_nop 0
	global_load_lds_dwordx4 v166, s[96:97]
	s_barrier
	s_waitcnt lgkmcnt(0)
	v_mfma_f32_16x16x32_bf16 v[62:65], v[130:133], v[146:149], v[62:65]
	v_mfma_f32_16x16x32_bf16 v[58:61], v[138:141], v[146:149], v[58:61]
	v_mfma_f32_16x16x32_bf16 v[46:49], v[130:133], v[154:157], v[46:49]
	v_mfma_f32_16x16x32_bf16 v[42:45], v[138:141], v[154:157], v[42:45]
	v_mfma_f32_16x16x32_bf16 v[30:33], v[130:133], v[174:177], v[30:33]
	v_mfma_f32_16x16x32_bf16 v[26:29], v[138:141], v[174:177], v[26:29]
	v_mfma_f32_16x16x32_bf16 v[14:17], v[130:133], v[182:185], v[14:17]
	v_mfma_f32_16x16x32_bf16 v[10:13], v[138:141], v[182:185], v[10:13]
	v_mfma_f32_16x16x32_bf16 v[62:65], v[134:137], v[150:153], v[62:65]
	v_mfma_f32_16x16x32_bf16 v[58:61], v[142:145], v[150:153], v[58:61]
	v_mfma_f32_16x16x32_bf16 v[46:49], v[134:137], v[158:161], v[46:49]
	v_mfma_f32_16x16x32_bf16 v[42:45], v[142:145], v[158:161], v[42:45]
	v_mfma_f32_16x16x32_bf16 v[30:33], v[134:137], v[178:181], v[30:33]
	v_mfma_f32_16x16x32_bf16 v[26:29], v[142:145], v[178:181], v[26:29]
	v_mfma_f32_16x16x32_bf16 v[14:17], v[134:137], v[192:195], v[14:17]
	v_mfma_f32_16x16x32_bf16 v[10:13], v[142:145], v[192:195], v[10:13]
	s_barrier
	s_add_u32 s20, s20, 0x80080
	s_addc_u32 s21, s21, 0
	s_add_i32 s22, s22, s34
	s_mov_b32 m0, s22
	s_nop 0
	global_load_lds_dwordx4 v164, s[20:21]
	s_add_i32 m0, s22, 0x2000
	s_nop 0
	global_load_lds_dwordx4 v168, s[20:21]
	s_waitcnt vmcnt(6)
	s_barrier
	v_mfma_f32_16x16x32_bf16 v[54:57], v[198:201], v[146:149], v[54:57]
	v_mfma_f32_16x16x32_bf16 v[50:53], v[206:209], v[146:149], v[50:53]
	v_mfma_f32_16x16x32_bf16 v[38:41], v[198:201], v[154:157], v[38:41]
	v_mfma_f32_16x16x32_bf16 v[34:37], v[206:209], v[154:157], v[34:37]
	v_mfma_f32_16x16x32_bf16 v[22:25], v[198:201], v[174:177], v[22:25]
	v_mfma_f32_16x16x32_bf16 v[18:21], v[206:209], v[174:177], v[18:21]
	v_mfma_f32_16x16x32_bf16 v[6:9], v[198:201], v[182:185], v[6:9]
	v_mfma_f32_16x16x32_bf16 v[2:5], v[206:209], v[182:185], v[2:5]
	v_mfma_f32_16x16x32_bf16 v[54:57], v[202:205], v[150:153], v[54:57]
	v_mfma_f32_16x16x32_bf16 v[50:53], v[210:213], v[150:153], v[50:53]
	v_mfma_f32_16x16x32_bf16 v[38:41], v[202:205], v[158:161], v[38:41]
	v_mfma_f32_16x16x32_bf16 v[34:37], v[210:213], v[158:161], v[34:37]
	v_mfma_f32_16x16x32_bf16 v[22:25], v[202:205], v[178:181], v[22:25]
	v_mfma_f32_16x16x32_bf16 v[18:21], v[210:213], v[178:181], v[18:21]
	v_mfma_f32_16x16x32_bf16 v[6:9], v[202:205], v[192:195], v[6:9]
	v_mfma_f32_16x16x32_bf16 v[2:5], v[210:213], v[192:195], v[2:5]
	s_add_i32 s46, s46, 2
	s_add_u32 s36, s36, 0x100
	s_addc_u32 s37, s37, 0
	s_add_u32 s18, s18, 0x100
	s_addc_u32 s19, s19, 0
	s_cmp_gt_u32 s46, 29
	s_barrier
	s_cbranch_scc0 .LBB0_426
	s_ashr_i32 s18, s4, 3
	v_lshl_add_u32 v178, s2, 8, v1
	s_lshl_b32 s2, s4, 8
	s_and_b32 s2, s2, 0x700
	s_ashr_i32 s19, s18, 31
	v_or_b32_e32 v132, s2, v187
	s_lshl_b64 s[2:3], s[18:19], 27
	s_add_u32 s2, s55, s2
	s_addc_u32 s3, s56, s3
	v_mov_b32_e32 v130, v236
	v_lshlrev_b32_e32 v176, 1, v132
	v_mov_b32_e32 v177, v0
	v_ashrrev_i32_e32 v179, 31, v178
	v_lshl_add_u64 v[180:181], s[2:3], 0, v[176:177]
	v_ashrrev_i32_e32 v131, 31, v130
	v_lshlrev_b64 v[184:185], 12, v[178:179]
	v_lshl_add_u64 v[174:175], v[130:131], 4, s[6:7]
	v_lshl_add_u64 v[130:131], v[180:181], 0, v[184:185]
	v_mov_b64_e32 v[250:251], v[130:131]
	s_mov_b32 s20, 0x20000
	s_mov_b32 s21, 0
	v_lshl_add_u64 v[252:253], v[250:251], 0, s[20:21]
	global_load_dwordx4 v[198:201], v[252:253], off
	global_load_dwordx4 v[202:205], v[252:253], off offset:256
	s_mov_b32 s20, 0x30000
	v_lshl_add_u64 v[252:253], v[250:251], 0, s[20:21]
	global_load_dwordx4 v[206:209], v[252:253], off
	global_load_dwordx4 v[210:213], v[252:253], off offset:256
	global_load_dwordx4 v[154:157], v[130:131], off
	s_cmp_gt_i32 s18, 0
	s_cselect_b64 s[2:3], -1, 0
	s_cmp_lt_i32 s18, 1
	s_cbranch_scc1 .LBB0_429
	global_load_dwordx4 v[158:161], v[174:175], off
	s_branch .LBB0_430

; #define PG8_STAGE(bufoff, gbase, voff) do { _Pragma("unroll") for (int _i = 0; _i < 2; ++_i) \
;         __builtin_amdgcn_global_load_lds((const unsigned*)((const char*)(gbase) + (voff)[_i]), (LAS unsigned*)(lds + (bufoff) + ldsw + _i * 8192), 16, 0, 0); } while (0)
; #define PG8_LDA(dst, b, h) do { _Pragma("unroll") for (int m = 0; m < 4; ++m) _Pragma("unroll") for (int k = 0; k < 2; ++k) dst[m][k] = *(const LAS bf16x8*)(lds + PG8_SA(b, h) + aoff + m * 2048 + k * 1024); } while (0)
; #define PG8_LDB(dst, b, h) do { _Pragma("unroll") for (int n = 0; n < 2; ++n) _Pragma("unroll") for (int k = 0; k < 2; ++k) dst[n][k] = *(const LAS bf16x8*)(lds + PG8_SB(b, h) + boff + n * 2048 + k * 1024); } while (0)
; #define PG8_MMA(ai, bj, At, Bt) do { __builtin_amdgcn_s_setprio(1); _Pragma("unroll") for (int m = 0; m < 4; ++m) _Pragma("unroll") for (int n = 0; n < 2; ++n) _Pragma("unroll") for (int k = 0; k < 2; ++k) \
;         acc[ai][bj][m][n] = __builtin_amdgcn_mfma_f32_16x16x32_bf16(Bt[n][k], At[m][k], acc[ai][bj][m][n], 0, 0, 0); __builtin_amdgcn_s_setprio(0); } while (0)
; #define PG8_WAIT_V(n) asm volatile("s_waitcnt vmcnt(" #n ")" ::: "memory")
; #define PG8_WAIT_L(n) asm volatile("s_waitcnt lgkmcnt(" #n ")" ::: "memory")
; #define PG8_BAR __builtin_amdgcn_s_barrier()
; #define PG8_SCHED __builtin_amdgcn_sched_barrier(0)
; template <class Epi, class Sched, bool AREMAP>
; __device__ __forceinline__ void gemm_phase(LAS unsigned char* lds, const Gemm g, const Sched& S, const Epi& E, int wv) {
;     ...
;             const char* a1 = cA + (size_t)(t + 1) * kstep;
;             const char* a2 = last ? nA : cA + (size_t)(t + 2) * kstep; const char* b2 = last ? nB : cB + (size_t)(t + 2) * kstep;
;             const char* a3 = a2 + kstep; const char* b3 = b2 + kstep;
;             PG8_LDB(B0, 0, 0); PG8_SCHED; PG8_LDA(At, 0, 0); PG8_STAGE(PG8_SA(1, 1), a1 + hstepA, voffA);
;             PG8_WAIT_L(8); PG8_BAR; PG8_WAIT_L(0); PG8_MMA(0, 0, At, B0); PG8_BAR; PG8_SCHED;
;             PG8_LDB(B1, 0, 1); PG8_STAGE(PG8_SB(0, 0), b2, voffB);
;             PG8_BAR; PG8_WAIT_L(0); PG8_MMA(0, 1, At, B1); PG8_BAR;
;             PG8_LDA(At, 0, 1); PG8_STAGE(PG8_SA(0, 0), a2, voffA);
;             PG8_BAR; PG8_WAIT_L(0); PG8_MMA(1, 0, At, B0); PG8_BAR; PG8_SCHED;
;             PG8_STAGE(PG8_SB(0, 1), b2 + hstepB, voffB);
;             PG8_WAIT_V(6); PG8_BAR; PG8_MMA(1, 1, At, B1); PG8_BAR;
.LBB0_552:
	s_add_u32 s34, s2, 0x100
	s_addc_u32 s35, s3, 0
	s_add_i32 s38, 0, 0x10000
	v_add_u32_e32 v1, s38, v250
	ds_read_b128 v[130:133], v1
	ds_read_b128 v[134:137], v1 offset:1024
	ds_read_b128 v[138:141], v1 offset:2048
	ds_read_b128 v[142:145], v1 offset:3072
	s_cmp_eq_u32 s76, 28
	s_cselect_b32 s67, s23, s35
	s_cselect_b32 s66, s72, s34
	s_cselect_b32 s63, s21, s75
	s_cselect_b32 s62, s73, s74
	s_add_i32 m0, s29, 0xc000
	ds_read_b128 v[146:149], v252
	ds_read_b128 v[150:153], v252 offset:1024
	ds_read_b128 v[154:157], v252 offset:2048
	ds_read_b128 v[158:161], v252 offset:3072
	ds_read_b128 v[162:165], v252 offset:4096
	ds_read_b128 v[166:169], v252 offset:5120
	ds_read_b128 v[170:173], v252 offset:6144
	ds_read_b128 v[174:177], v252 offset:7168
	global_load_lds_dwordx4 v202, s[2:3]
	s_add_i32 m0, s29, 0xe000
	s_nop 0
	global_load_lds_dwordx4 v200, s[2:3]
	s_waitcnt lgkmcnt(8)
	s_barrier
	s_waitcnt lgkmcnt(0)
	v_mfma_f32_16x16x32_bf16 v[126:129], v[130:133], v[146:149], v[126:129]
	v_mfma_f32_16x16x32_bf16 v[110:113], v[138:141], v[146:149], v[110:113]
	v_mfma_f32_16x16x32_bf16 v[122:125], v[130:133], v[154:157], v[122:125]
	v_mfma_f32_16x16x32_bf16 v[106:109], v[138:141], v[154:157], v[106:109]
	v_mfma_f32_16x16x32_bf16 v[118:121], v[130:133], v[162:165], v[118:121]
	v_mfma_f32_16x16x32_bf16 v[102:105], v[138:141], v[162:165], v[102:105]
	v_mfma_f32_16x16x32_bf16 v[114:117], v[130:133], v[170:173], v[114:117]
	v_mfma_f32_16x16x32_bf16 v[98:101], v[138:141], v[170:173], v[98:101]
	v_mfma_f32_16x16x32_bf16 v[126:129], v[134:137], v[150:153], v[126:129]
	v_mfma_f32_16x16x32_bf16 v[110:113], v[142:145], v[150:153], v[110:113]
	v_mfma_f32_16x16x32_bf16 v[122:125], v[134:137], v[158:161], v[122:125]
	v_mfma_f32_16x16x32_bf16 v[106:109], v[142:145], v[158:161], v[106:109]
	v_mfma_f32_16x16x32_bf16 v[118:121], v[134:137], v[166:169], v[118:121]
	v_mfma_f32_16x16x32_bf16 v[102:105], v[142:145], v[166:169], v[102:105]
	v_mfma_f32_16x16x32_bf16 v[114:117], v[134:137], v[174:177], v[114:117]
	v_mfma_f32_16x16x32_bf16 v[98:101], v[142:145], v[174:177], v[98:101]
	s_barrier
	s_add_i32 s39, 0, 0x14000
	s_add_i32 s2, s38, s53
	v_add_u32_e32 v1, s39, v250
	s_add_u32 s80, s62, 0x80
	s_addc_u32 s81, s63, 0
	s_mov_b32 m0, s2
	ds_read_b128 v[178:181], v1
	ds_read_b128 v[182:185], v1 offset:1024
	ds_read_b128 v[192:195], v1 offset:2048
	ds_read_b128 v[204:207], v1 offset:3072
	global_load_lds_dwordx4 v196, s[62:63]
	s_add_i32 m0, s2, 0x2000
	s_nop 0
	global_load_lds_dwordx4 v198, s[62:63]
	s_barrier
	s_waitcnt lgkmcnt(0)
	v_mfma_f32_16x16x32_bf16 v[94:97], v[178:181], v[146:149], v[94:97]
	v_mfma_f32_16x16x32_bf16 v[78:81], v[192:195], v[146:149], v[78:81]
	v_mfma_f32_16x16x32_bf16 v[90:93], v[178:181], v[154:157], v[90:93]
	v_mfma_f32_16x16x32_bf16 v[74:77], v[192:195], v[154:157], v[74:77]
	v_mfma_f32_16x16x32_bf16 v[86:89], v[178:181], v[162:165], v[86:89]
	v_mfma_f32_16x16x32_bf16 v[70:73], v[192:195], v[162:165], v[70:73]
	v_mfma_f32_16x16x32_bf16 v[82:85], v[178:181], v[170:173], v[82:85]
	v_mfma_f32_16x16x32_bf16 v[66:69], v[192:195], v[170:173], v[66:69]
	v_mfma_f32_16x16x32_bf16 v[94:97], v[182:185], v[150:153], v[94:97]
	v_mfma_f32_16x16x32_bf16 v[78:81], v[204:207], v[150:153], v[78:81]
	v_mfma_f32_16x16x32_bf16 v[90:93], v[182:185], v[158:161], v[90:93]
	v_mfma_f32_16x16x32_bf16 v[74:77], v[204:207], v[158:161], v[74:77]
	v_mfma_f32_16x16x32_bf16 v[86:89], v[182:185], v[166:169], v[86:89]
	v_mfma_f32_16x16x32_bf16 v[70:73], v[204:207], v[166:169], v[70:73]
	v_mfma_f32_16x16x32_bf16 v[82:85], v[182:185], v[174:177], v[82:85]
	v_mfma_f32_16x16x32_bf16 v[66:69], v[204:207], v[174:177], v[66:69]
	s_mov_b32 m0, s29
	s_add_u32 s96, s66, 0x80
	s_addc_u32 s97, s67, 0
	s_barrier
	ds_read_b128 v[146:149], v252 offset:16384
	ds_read_b128 v[150:153], v252 offset:17408
	ds_read_b128 v[154:157], v252 offset:18432
	ds_read_b128 v[158:161], v252 offset:19456
	ds_read_b128 v[162:165], v252 offset:20480
	ds_read_b128 v[166:169], v252 offset:21504
	ds_read_b128 v[170:173], v252 offset:22528
	ds_read_b128 v[174:177], v252 offset:23552
	global_load_lds_dwordx4 v196, s[66:67]
	s_mov_b32 m0, s31
	s_nop 0
	global_load_lds_dwordx4 v198, s[66:67]
	s_barrier
	s_waitcnt lgkmcnt(0)
	v_mfma_f32_16x16x32_bf16 v[62:65], v[130:133], v[146:149], v[62:65]
	v_mfma_f32_16x16x32_bf16 v[46:49], v[138:141], v[146:149], v[46:49]
	v_mfma_f32_16x16x32_bf16 v[58:61], v[130:133], v[154:157], v[58:61]
	v_mfma_f32_16x16x32_bf16 v[42:45], v[138:141], v[154:157], v[42:45]
	v_mfma_f32_16x16x32_bf16 v[54:57], v[130:133], v[162:165], v[54:57]
	v_mfma_f32_16x16x32_bf16 v[38:41], v[138:141], v[162:165], v[38:41]
	v_mfma_f32_16x16x32_bf16 v[50:53], v[130:133], v[170:173], v[50:53]
	v_mfma_f32_16x16x32_bf16 v[34:37], v[138:141], v[170:173], v[34:37]
	v_mfma_f32_16x16x32_bf16 v[62:65], v[134:137], v[150:153], v[62:65]
	v_mfma_f32_16x16x32_bf16 v[46:49], v[142:145], v[150:153], v[46:49]
	v_mfma_f32_16x16x32_bf16 v[58:61], v[134:137], v[158:161], v[58:61]
	v_mfma_f32_16x16x32_bf16 v[42:45], v[142:145], v[158:161], v[42:45]
	v_mfma_f32_16x16x32_bf16 v[54:57], v[134:137], v[166:169], v[54:57]
	v_mfma_f32_16x16x32_bf16 v[38:41], v[142:145], v[166:169], v[38:41]
	v_mfma_f32_16x16x32_bf16 v[50:53], v[134:137], v[174:177], v[50:53]
	v_mfma_f32_16x16x32_bf16 v[34:37], v[142:145], v[174:177], v[34:37]
	s_barrier
	s_add_u32 s2, s62, 0x80000
	s_addc_u32 s3, s63, 0
	s_add_i32 s38, s39, s53
	s_mov_b32 m0, s38
	s_nop 0
	global_load_lds_dwordx4 v196, s[2:3]
	s_add_i32 m0, s38, 0x2000
	s_nop 0
	global_load_lds_dwordx4 v198, s[2:3]
	s_waitcnt vmcnt(6)
	s_barrier
; #define PG8_STAGE(bufoff, gbase, voff) do { _Pragma("unroll") for (int _i = 0; _i < 2; ++_i) \
;         __builtin_amdgcn_global_load_lds((const unsigned*)((const char*)(gbase) + (voff)[_i]), (LAS unsigned*)(lds + (bufoff) + ldsw + _i * 8192), 16, 0, 0); } while (0)
; #define PG8_LDA(dst, b, h) do { _Pragma("unroll") for (int m = 0; m < 4; ++m) _Pragma("unroll") for (int k = 0; k < 2; ++k) dst[m][k] = *(const LAS bf16x8*)(lds + PG8_SA(b, h) + aoff + m * 2048 + k * 1024); } while (0)
; #define PG8_LDB(dst, b, h) do { _Pragma("unroll") for (int n = 0; n < 2; ++n) _Pragma("unroll") for (int k = 0; k < 2; ++k) dst[n][k] = *(const LAS bf16x8*)(lds + PG8_SB(b, h) + boff + n * 2048 + k * 1024); } while (0)
; #define PG8_MMA(ai, bj, At, Bt) do { __builtin_amdgcn_s_setprio(1); _Pragma("unroll") for (int m = 0; m < 4; ++m) _Pragma("unroll") for (int n = 0; n < 2; ++n) _Pragma("unroll") for (int k = 0; k < 2; ++k) \
;         acc[ai][bj][m][n] = __builtin_amdgcn_mfma_f32_16x16x32_bf16(Bt[n][k], At[m][k], acc[ai][bj][m][n], 0, 0, 0); __builtin_amdgcn_s_setprio(0); } while (0)
; #define PG8_WAIT_V(n) asm volatile("s_waitcnt vmcnt(" #n ")" ::: "memory")
; #define PG8_WAIT_L(n) asm volatile("s_waitcnt lgkmcnt(" #n ")" ::: "memory")
; #define PG8_BAR __builtin_amdgcn_s_barrier()
; #define PG8_SCHED __builtin_amdgcn_sched_barrier(0)
; template <class Epi, class Sched, bool AREMAP>
; __device__ __forceinline__ void gemm_phase(LAS unsigned char* lds, const Gemm g, const Sched& S, const Epi& E, int wv) {
;     ...
;             PG8_WAIT_V(6); PG8_BAR; PG8_MMA(1, 1, At, B1); PG8_BAR;
;             PG8_LDB(B0, 1, 0); PG8_SCHED; PG8_LDA(At, 1, 0); PG8_STAGE(PG8_SA(0, 1), a2 + hstepA, voffA);
;             PG8_WAIT_L(8); PG8_BAR; PG8_WAIT_L(0); PG8_MMA(0, 0, At, B0); PG8_BAR; PG8_SCHED;
;             PG8_LDB(B1, 1, 1); PG8_STAGE(PG8_SB(1, 0), b3, voffB);
;             PG8_BAR; PG8_WAIT_L(0); PG8_MMA(0, 1, At, B1); PG8_BAR;
	v_mfma_f32_16x16x32_bf16 v[30:33], v[178:181], v[146:149], v[30:33]
	v_mfma_f32_16x16x32_bf16 v[14:17], v[192:195], v[146:149], v[14:17]
	v_mfma_f32_16x16x32_bf16 v[26:29], v[178:181], v[154:157], v[26:29]
	v_mfma_f32_16x16x32_bf16 v[10:13], v[192:195], v[154:157], v[10:13]
	v_mfma_f32_16x16x32_bf16 v[22:25], v[178:181], v[162:165], v[22:25]
	v_mfma_f32_16x16x32_bf16 v[6:9], v[192:195], v[162:165], v[6:9]
	v_mfma_f32_16x16x32_bf16 v[18:21], v[178:181], v[170:173], v[18:21]
	v_mfma_f32_16x16x32_bf16 v[2:5], v[192:195], v[170:173], v[2:5]
	v_mfma_f32_16x16x32_bf16 v[30:33], v[182:185], v[150:153], v[30:33]
	v_mfma_f32_16x16x32_bf16 v[14:17], v[204:207], v[150:153], v[14:17]
	v_mfma_f32_16x16x32_bf16 v[26:29], v[182:185], v[158:161], v[26:29]
	v_mfma_f32_16x16x32_bf16 v[10:13], v[204:207], v[158:161], v[10:13]
	v_mfma_f32_16x16x32_bf16 v[22:25], v[182:185], v[166:169], v[22:25]
	v_mfma_f32_16x16x32_bf16 v[6:9], v[204:207], v[166:169], v[6:9]
	v_mfma_f32_16x16x32_bf16 v[18:21], v[182:185], v[174:177], v[18:21]
	v_mfma_f32_16x16x32_bf16 v[2:5], v[204:207], v[174:177], v[2:5]
	s_add_i32 s38, 0, 0x18000
	v_add_u32_e32 v1, s38, v250
	s_barrier
	ds_read_b128 v[130:133], v1
	ds_read_b128 v[134:137], v1 offset:1024
	ds_read_b128 v[138:141], v1 offset:2048
	ds_read_b128 v[142:145], v1 offset:3072
	s_add_u32 s2, s66, 0x80000
	s_addc_u32 s3, s67, 0
	s_mov_b32 m0, s55
	ds_read_b128 v[146:149], v252 offset:32768
	ds_read_b128 v[150:153], v252 offset:33792
	ds_read_b128 v[154:157], v252 offset:34816
	ds_read_b128 v[158:161], v252 offset:35840
	ds_read_b128 v[162:165], v252 offset:36864
	ds_read_b128 v[166:169], v252 offset:37888
	ds_read_b128 v[170:173], v252 offset:38912
	ds_read_b128 v[174:177], v252 offset:39936
	global_load_lds_dwordx4 v196, s[2:3]
	s_mov_b32 m0, s56
	s_nop 0
	global_load_lds_dwordx4 v198, s[2:3]
	s_waitcnt lgkmcnt(8)
	s_barrier
	s_waitcnt lgkmcnt(0)
	v_mfma_f32_16x16x32_bf16 v[126:129], v[130:133], v[146:149], v[126:129]
	v_mfma_f32_16x16x32_bf16 v[110:113], v[138:141], v[146:149], v[110:113]
	v_mfma_f32_16x16x32_bf16 v[122:125], v[130:133], v[154:157], v[122:125]
	v_mfma_f32_16x16x32_bf16 v[106:109], v[138:141], v[154:157], v[106:109]
	v_mfma_f32_16x16x32_bf16 v[118:121], v[130:133], v[162:165], v[118:121]
	v_mfma_f32_16x16x32_bf16 v[102:105], v[138:141], v[162:165], v[102:105]
	v_mfma_f32_16x16x32_bf16 v[114:117], v[130:133], v[170:173], v[114:117]
	v_mfma_f32_16x16x32_bf16 v[98:101], v[138:141], v[170:173], v[98:101]
	v_mfma_f32_16x16x32_bf16 v[126:129], v[134:137], v[150:153], v[126:129]
	v_mfma_f32_16x16x32_bf16 v[110:113], v[142:145], v[150:153], v[110:113]
	v_mfma_f32_16x16x32_bf16 v[122:125], v[134:137], v[158:161], v[122:125]
	v_mfma_f32_16x16x32_bf16 v[106:109], v[142:145], v[158:161], v[106:109]
	v_mfma_f32_16x16x32_bf16 v[118:121], v[134:137], v[166:169], v[118:121]
	v_mfma_f32_16x16x32_bf16 v[102:105], v[142:145], v[166:169], v[102:105]
	v_mfma_f32_16x16x32_bf16 v[114:117], v[134:137], v[174:177], v[114:117]
	v_mfma_f32_16x16x32_bf16 v[98:101], v[142:145], v[174:177], v[98:101]
	s_barrier
	s_add_i32 s39, 0, 0x1c000
	s_add_i32 s2, s38, s53
	v_add_u32_e32 v1, s39, v250
	s_mov_b32 m0, s2
	ds_read_b128 v[178:181], v1
	ds_read_b128 v[182:185], v1 offset:1024
	ds_read_b128 v[192:195], v1 offset:2048
	ds_read_b128 v[204:207], v1 offset:3072
	global_load_lds_dwordx4 v196, s[80:81]
	s_add_i32 m0, s2, 0x2000
	s_nop 0
	global_load_lds_dwordx4 v198, s[80:81]
	s_barrier
	s_waitcnt lgkmcnt(0)
	v_mfma_f32_16x16x32_bf16 v[94:97], v[178:181], v[146:149], v[94:97]
	v_mfma_f32_16x16x32_bf16 v[78:81], v[192:195], v[146:149], v[78:81]
	v_mfma_f32_16x16x32_bf16 v[90:93], v[178:181], v[154:157], v[90:93]
	v_mfma_f32_16x16x32_bf16 v[74:77], v[192:195], v[154:157], v[74:77]
	v_mfma_f32_16x16x32_bf16 v[86:89], v[178:181], v[162:165], v[86:89]
	v_mfma_f32_16x16x32_bf16 v[70:73], v[192:195], v[162:165], v[70:73]
	v_mfma_f32_16x16x32_bf16 v[82:85], v[178:181], v[170:173], v[82:85]
	v_mfma_f32_16x16x32_bf16 v[66:69], v[192:195], v[170:173], v[66:69]
	v_mfma_f32_16x16x32_bf16 v[94:97], v[182:185], v[150:153], v[94:97]
	v_mfma_f32_16x16x32_bf16 v[78:81], v[204:207], v[150:153], v[78:81]
	v_mfma_f32_16x16x32_bf16 v[90:93], v[182:185], v[158:161], v[90:93]
	v_mfma_f32_16x16x32_bf16 v[74:77], v[204:207], v[158:161], v[74:77]
	v_mfma_f32_16x16x32_bf16 v[86:89], v[182:185], v[166:169], v[86:89]
	v_mfma_f32_16x16x32_bf16 v[70:73], v[204:207], v[166:169], v[70:73]
	v_mfma_f32_16x16x32_bf16 v[82:85], v[182:185], v[174:177], v[82:85]
	v_mfma_f32_16x16x32_bf16 v[66:69], v[204:207], v[174:177], v[66:69]
	s_mov_b32 m0, s57
	s_barrier
; #define PG8_STAGE(bufoff, gbase, voff) do { _Pragma("unroll") for (int _i = 0; _i < 2; ++_i) \
;         __builtin_amdgcn_global_load_lds((const unsigned*)((const char*)(gbase) + (voff)[_i]), (LAS unsigned*)(lds + (bufoff) + ldsw + _i * 8192), 16, 0, 0); } while (0)
; #define PG8_MMA(ai, bj, At, Bt) do { __builtin_amdgcn_s_setprio(1); _Pragma("unroll") for (int m = 0; m < 4; ++m) _Pragma("unroll") for (int n = 0; n < 2; ++n) _Pragma("unroll") for (int k = 0; k < 2; ++k) \
;         acc[ai][bj][m][n] = __builtin_amdgcn_mfma_f32_16x16x32_bf16(Bt[n][k], At[m][k], acc[ai][bj][m][n], 0, 0, 0); __builtin_amdgcn_s_setprio(0); } while (0)
; #define PG8_WAIT_V(n) asm volatile("s_waitcnt vmcnt(" #n ")" ::: "memory")
; #define PG8_WAIT_L(n) asm volatile("s_waitcnt lgkmcnt(" #n ")" ::: "memory")
; #define PG8_BAR __builtin_amdgcn_s_barrier()
; #define PG8_SCHED __builtin_amdgcn_sched_barrier(0)
; template <class Epi, class Sched, bool AREMAP>
; __device__ __forceinline__ void gemm_phase(LAS unsigned char* lds, const Gemm g, const Sched& S, const Epi& E, int wv) {
;     ...
;             PG8_BAR; PG8_WAIT_L(0); PG8_MMA(1, 0, At, B0); PG8_BAR; PG8_SCHED;
;             PG8_STAGE(PG8_SB(1, 1), b3 + hstepB, voffB);
;             PG8_WAIT_V(6); PG8_BAR; PG8_MMA(1, 1, At, B1); PG8_BAR;
;         }
;     __device__ __forceinline__ void operator()(const f32x4 (&acc)[2][2][4][2], const Unit& u, int wr, int wc, int fr, int fq) const {
;         const int row0 = u.pm * BM + wr * 64 + fr, col0 = u.pn * BM + wc * 32 + 4 * fq;
;         const float* gv = gate + (size_t)(u.pm >> 3) * 12288 + col0;
; #pragma unroll
;         for (int ai = 0; ai < 2; ++ai) {
;             float mu[4], rs[4];
; #pragma unroll
;             for (int m = 0; m < 4; ++m) { mu[m] = 0.f; rs[m] = 1.f;
;                 if (stats) { const float* sp = stats + (size_t)(row0 + ai * HALF + m * 16) * 2; mu[m] = sp[0]; rs[m] = sp[1]; } }
	ds_read_b128 v[146:149], v252 offset:49152
	ds_read_b128 v[150:153], v252 offset:50176
	ds_read_b128 v[154:157], v252 offset:51200
	ds_read_b128 v[158:161], v252 offset:52224
	ds_read_b128 v[162:165], v252 offset:53248
	ds_read_b128 v[166:169], v252 offset:54272
	ds_read_b128 v[170:173], v252 offset:55296
	ds_read_b128 v[174:177], v252 offset:56320
	global_load_lds_dwordx4 v196, s[96:97]
	s_mov_b32 m0, s65
	s_nop 0
	global_load_lds_dwordx4 v198, s[96:97]
	s_barrier
	s_waitcnt lgkmcnt(0)
	v_mfma_f32_16x16x32_bf16 v[62:65], v[130:133], v[146:149], v[62:65]
	v_mfma_f32_16x16x32_bf16 v[46:49], v[138:141], v[146:149], v[46:49]
	v_mfma_f32_16x16x32_bf16 v[58:61], v[130:133], v[154:157], v[58:61]
	v_mfma_f32_16x16x32_bf16 v[42:45], v[138:141], v[154:157], v[42:45]
	v_mfma_f32_16x16x32_bf16 v[54:57], v[130:133], v[162:165], v[54:57]
	v_mfma_f32_16x16x32_bf16 v[38:41], v[138:141], v[162:165], v[38:41]
	v_mfma_f32_16x16x32_bf16 v[50:53], v[130:133], v[170:173], v[50:53]
	v_mfma_f32_16x16x32_bf16 v[34:37], v[138:141], v[170:173], v[34:37]
	v_mfma_f32_16x16x32_bf16 v[62:65], v[134:137], v[150:153], v[62:65]
	v_mfma_f32_16x16x32_bf16 v[46:49], v[142:145], v[150:153], v[46:49]
	v_mfma_f32_16x16x32_bf16 v[58:61], v[134:137], v[158:161], v[58:61]
	v_mfma_f32_16x16x32_bf16 v[42:45], v[142:145], v[158:161], v[42:45]
	v_mfma_f32_16x16x32_bf16 v[54:57], v[134:137], v[166:169], v[54:57]
	v_mfma_f32_16x16x32_bf16 v[38:41], v[142:145], v[166:169], v[38:41]
	v_mfma_f32_16x16x32_bf16 v[50:53], v[134:137], v[174:177], v[50:53]
	v_mfma_f32_16x16x32_bf16 v[34:37], v[142:145], v[174:177], v[34:37]
	s_barrier
	s_add_u32 s2, s62, 0x80080
	s_addc_u32 s3, s63, 0
	s_add_i32 s38, s39, s53
	s_mov_b32 m0, s38
	s_nop 0
	global_load_lds_dwordx4 v196, s[2:3]
	s_add_i32 m0, s38, 0x2000
	s_nop 0
	global_load_lds_dwordx4 v198, s[2:3]
	s_waitcnt vmcnt(6)
	s_barrier
	v_mfma_f32_16x16x32_bf16 v[30:33], v[178:181], v[146:149], v[30:33]
	v_mfma_f32_16x16x32_bf16 v[14:17], v[192:195], v[146:149], v[14:17]
	v_mfma_f32_16x16x32_bf16 v[26:29], v[178:181], v[154:157], v[26:29]
	v_mfma_f32_16x16x32_bf16 v[10:13], v[192:195], v[154:157], v[10:13]
	v_mfma_f32_16x16x32_bf16 v[22:25], v[178:181], v[162:165], v[22:25]
	v_mfma_f32_16x16x32_bf16 v[6:9], v[192:195], v[162:165], v[6:9]
	v_mfma_f32_16x16x32_bf16 v[18:21], v[178:181], v[170:173], v[18:21]
	v_mfma_f32_16x16x32_bf16 v[2:5], v[192:195], v[170:173], v[2:5]
	v_mfma_f32_16x16x32_bf16 v[30:33], v[182:185], v[150:153], v[30:33]
	v_mfma_f32_16x16x32_bf16 v[14:17], v[204:207], v[150:153], v[14:17]
	v_mfma_f32_16x16x32_bf16 v[26:29], v[182:185], v[158:161], v[26:29]
	v_mfma_f32_16x16x32_bf16 v[10:13], v[204:207], v[158:161], v[10:13]
	v_mfma_f32_16x16x32_bf16 v[22:25], v[182:185], v[166:169], v[22:25]
	v_mfma_f32_16x16x32_bf16 v[6:9], v[204:207], v[166:169], v[6:9]
	v_mfma_f32_16x16x32_bf16 v[18:21], v[182:185], v[174:177], v[18:21]
	v_mfma_f32_16x16x32_bf16 v[2:5], v[204:207], v[174:177], v[2:5]
	s_add_i32 s76, s76, 2
	s_add_u32 s74, s74, 0x100
	s_addc_u32 s75, s75, 0
	s_cmp_gt_u32 s76, 29
	s_mov_b64 s[2:3], s[34:35]
	s_barrier
	s_cbranch_scc0 .LBB0_552
	v_lshl_add_u32 v212, s28, 8, v249
	v_cndmask_b32_e64 v1, 0, 1, s[18:19]
	v_mov_b32_e32 v216, 1.0
	v_cmp_ne_u32_e64 s[2:3], 1, v1
	s_andn2_b64 vcc, exec, s[18:19]
	v_ashrrev_i32_e32 v213, 31, v212
	s_cbranch_vccnz .LBB0_556
	v_lshl_add_u64 v[130:131], v[212:213], 3, s[12:13]
	global_load_dwordx2 v[134:135], v[130:131], off
	v_or_b32_e32 v140, 16, v212
	s_and_b64 vcc, exec, s[2:3]
	v_ashrrev_i32_e32 v141, 31, v140
	s_cbranch_vccnz .LBB0_557

; #define PG8_STAGE(bufoff, gbase, voff) do { _Pragma("unroll") for (int _i = 0; _i < 2; ++_i) \
;         __builtin_amdgcn_global_load_lds((const unsigned*)((const char*)(gbase) + (voff)[_i]), (LAS unsigned*)(lds + (bufoff) + ldsw + _i * 8192), 16, 0, 0); } while (0)
; #define PG8_LDA(dst, b, h) do { _Pragma("unroll") for (int m = 0; m < 4; ++m) _Pragma("unroll") for (int k = 0; k < 2; ++k) dst[m][k] = *(const LAS bf16x8*)(lds + PG8_SA(b, h) + aoff + m * 2048 + k * 1024); } while (0)
; #define PG8_LDB(dst, b, h) do { _Pragma("unroll") for (int n = 0; n < 2; ++n) _Pragma("unroll") for (int k = 0; k < 2; ++k) dst[n][k] = *(const LAS bf16x8*)(lds + PG8_SB(b, h) + boff + n * 2048 + k * 1024); } while (0)
; #define PG8_MMA(ai, bj, At, Bt) do { __builtin_amdgcn_s_setprio(1); _Pragma("unroll") for (int m = 0; m < 4; ++m) _Pragma("unroll") for (int n = 0; n < 2; ++n) _Pragma("unroll") for (int k = 0; k < 2; ++k) \
;         acc[ai][bj][m][n] = __builtin_amdgcn_mfma_f32_16x16x32_bf16(Bt[n][k], At[m][k], acc[ai][bj][m][n], 0, 0, 0); __builtin_amdgcn_s_setprio(0); } while (0)
; #define PG8_WAIT_V(n) asm volatile("s_waitcnt vmcnt(" #n ")" ::: "memory")
; #define PG8_WAIT_L(n) asm volatile("s_waitcnt lgkmcnt(" #n ")" ::: "memory")
; #define PG8_BAR __builtin_amdgcn_s_barrier()
; #define PG8_SCHED __builtin_amdgcn_sched_barrier(0)
; template <class Epi, class Sched, bool AREMAP>
; __device__ __forceinline__ void gemm_phase(LAS unsigned char* lds, const Gemm g, const Sched& S, const Epi& E, int wv) {
;     ...
;             const char* a1 = cA + (size_t)(t + 1) * kstep;
;             const char* a2 = last ? nA : cA + (size_t)(t + 2) * kstep; const char* b2 = last ? nB : cB + (size_t)(t + 2) * kstep;
;             const char* a3 = a2 + kstep; const char* b3 = b2 + kstep;
;             PG8_LDB(B0, 0, 0); PG8_SCHED; PG8_LDA(At, 0, 0); PG8_STAGE(PG8_SA(1, 1), a1 + hstepA, voffA);
;             PG8_WAIT_L(8); PG8_BAR; PG8_WAIT_L(0); PG8_MMA(0, 0, At, B0); PG8_BAR; PG8_SCHED;
;             PG8_LDB(B1, 0, 1); PG8_STAGE(PG8_SB(0, 0), b2, voffB);
;             PG8_BAR; PG8_WAIT_L(0); PG8_MMA(0, 1, At, B1); PG8_BAR;
;             PG8_LDA(At, 0, 1); PG8_STAGE(PG8_SA(0, 0), a2, voffA);
;             PG8_BAR; PG8_WAIT_L(0); PG8_MMA(1, 0, At, B0); PG8_BAR; PG8_SCHED;
;             PG8_STAGE(PG8_SB(0, 1), b2 + hstepB, voffB);
;             PG8_WAIT_V(6); PG8_BAR; PG8_MMA(1, 1, At, B1); PG8_BAR;
.LBB0_619:
	s_add_u32 s38, s78, 0xfffc0080
	s_addc_u32 s39, s79, -1
	s_add_i32 s33, 0, 0x10000
	v_add_u32_e32 v142, s33, v1
	ds_read_b128 v[130:133], v142
	ds_read_b128 v[134:137], v142 offset:1024
	ds_read_b128 v[138:141], v142 offset:2048
	ds_read_b128 v[142:145], v142 offset:3072
	s_cmp_eq_u32 vcc_hi, 28
	s_cselect_b32 s97, s46, s39
	s_cselect_b32 s96, s47, s38
	s_cselect_b32 s81, s63, vcc_lo
	s_cselect_b32 s80, s67, s77
	s_add_i32 m0, s10, 0xc000
	ds_read_b128 v[146:149], v183
	ds_read_b128 v[150:153], v183 offset:1024
	ds_read_b128 v[170:173], v183 offset:2048
	ds_read_b128 v[174:177], v183 offset:3072
	ds_read_b128 v[184:187], v183 offset:4096
	ds_read_b128 v[192:195], v183 offset:5120
	ds_read_b128 v[196:199], v183 offset:6144
	ds_read_b128 v[200:203], v183 offset:7168
	global_load_lds_dwordx4 v168, s[78:79]
	s_add_i32 m0, s10, 0xe000
	s_nop 0
	global_load_lds_dwordx4 v166, s[78:79]
	s_waitcnt lgkmcnt(8)
	s_barrier
	s_waitcnt lgkmcnt(0)
	v_mfma_f32_16x16x32_bf16 v[126:129], v[130:133], v[146:149], v[126:129]
	v_mfma_f32_16x16x32_bf16 v[62:65], v[138:141], v[146:149], v[62:65]
	v_mfma_f32_16x16x32_bf16 v[118:121], v[130:133], v[170:173], v[118:121]
	v_mfma_f32_16x16x32_bf16 v[54:57], v[138:141], v[170:173], v[54:57]
	v_mfma_f32_16x16x32_bf16 v[110:113], v[130:133], v[184:187], v[110:113]
	v_mfma_f32_16x16x32_bf16 v[46:49], v[138:141], v[184:187], v[46:49]
	v_mfma_f32_16x16x32_bf16 v[102:105], v[130:133], v[196:199], v[102:105]
	v_mfma_f32_16x16x32_bf16 v[38:41], v[138:141], v[196:199], v[38:41]
	v_mfma_f32_16x16x32_bf16 v[126:129], v[134:137], v[150:153], v[126:129]
	v_mfma_f32_16x16x32_bf16 v[62:65], v[142:145], v[150:153], v[62:65]
	v_mfma_f32_16x16x32_bf16 v[118:121], v[134:137], v[174:177], v[118:121]
	v_mfma_f32_16x16x32_bf16 v[54:57], v[142:145], v[174:177], v[54:57]
	v_mfma_f32_16x16x32_bf16 v[110:113], v[134:137], v[192:195], v[110:113]
	v_mfma_f32_16x16x32_bf16 v[46:49], v[142:145], v[192:195], v[46:49]
	v_mfma_f32_16x16x32_bf16 v[102:105], v[134:137], v[200:203], v[102:105]
	v_mfma_f32_16x16x32_bf16 v[38:41], v[142:145], v[200:203], v[38:41]
	s_barrier
	s_add_i32 s58, 0, 0x14000
	v_add_u32_e32 v178, s58, v1
	s_add_i32 s33, s33, s91
	ds_read_b128 v[204:207], v178
	ds_read_b128 v[208:211], v178 offset:1024
	ds_read_b128 v[212:215], v178 offset:2048
	ds_read_b128 v[216:219], v178 offset:3072
	s_mov_b32 m0, s33
	s_nop 0
	global_load_lds_dwordx4 v158, s[80:81]
	s_add_i32 m0, s33, 0x2000
	s_nop 0
	global_load_lds_dwordx4 v154, s[80:81]
	s_add_u32 s80, s80, 0x80
	s_addc_u32 s81, s81, 0
	s_barrier
	s_waitcnt lgkmcnt(0)
	v_mfma_f32_16x16x32_bf16 v[122:125], v[204:207], v[146:149], v[122:125]
	v_mfma_f32_16x16x32_bf16 v[58:61], v[212:215], v[146:149], v[58:61]
	v_mfma_f32_16x16x32_bf16 v[114:117], v[204:207], v[170:173], v[114:117]
	v_mfma_f32_16x16x32_bf16 v[50:53], v[212:215], v[170:173], v[50:53]
	v_mfma_f32_16x16x32_bf16 v[106:109], v[204:207], v[184:187], v[106:109]
	v_mfma_f32_16x16x32_bf16 v[42:45], v[212:215], v[184:187], v[42:45]
	v_mfma_f32_16x16x32_bf16 v[98:101], v[204:207], v[196:199], v[98:101]
	v_mfma_f32_16x16x32_bf16 v[34:37], v[212:215], v[196:199], v[34:37]
	v_mfma_f32_16x16x32_bf16 v[122:125], v[208:211], v[150:153], v[122:125]
	v_mfma_f32_16x16x32_bf16 v[58:61], v[216:219], v[150:153], v[58:61]
	v_mfma_f32_16x16x32_bf16 v[114:117], v[208:211], v[174:177], v[114:117]
	v_mfma_f32_16x16x32_bf16 v[50:53], v[216:219], v[174:177], v[50:53]
	v_mfma_f32_16x16x32_bf16 v[106:109], v[208:211], v[192:195], v[106:109]
	v_mfma_f32_16x16x32_bf16 v[42:45], v[216:219], v[192:195], v[42:45]
	v_mfma_f32_16x16x32_bf16 v[98:101], v[208:211], v[200:203], v[98:101]
	v_mfma_f32_16x16x32_bf16 v[34:37], v[216:219], v[200:203], v[34:37]
	s_mov_b32 m0, s10
	s_barrier
	ds_read_b128 v[146:149], v183 offset:16384
	ds_read_b128 v[150:153], v183 offset:17408
	ds_read_b128 v[170:173], v183 offset:18432
	ds_read_b128 v[174:177], v183 offset:19456
	ds_read_b128 v[184:187], v183 offset:20480
	ds_read_b128 v[192:195], v183 offset:21504
	ds_read_b128 v[196:199], v183 offset:22528
	ds_read_b128 v[200:203], v183 offset:23552
	global_load_lds_dwordx4 v160, s[96:97]
	s_mov_b32 m0, s11
	s_nop 0
	global_load_lds_dwordx4 v156, s[96:97]
	s_add_u32 s96, s96, 0x80
	s_addc_u32 s97, s97, 0
	s_barrier
	s_waitcnt lgkmcnt(0)
	v_mfma_f32_16x16x32_bf16 v[94:97], v[130:133], v[146:149], v[94:97]
	v_mfma_f32_16x16x32_bf16 v[30:33], v[138:141], v[146:149], v[30:33]
	v_mfma_f32_16x16x32_bf16 v[86:89], v[130:133], v[170:173], v[86:89]
	v_mfma_f32_16x16x32_bf16 v[22:25], v[138:141], v[170:173], v[22:25]
	v_mfma_f32_16x16x32_bf16 v[78:81], v[130:133], v[184:187], v[78:81]
	v_mfma_f32_16x16x32_bf16 v[14:17], v[138:141], v[184:187], v[14:17]
	v_mfma_f32_16x16x32_bf16 v[70:73], v[130:133], v[196:199], v[70:73]
	v_mfma_f32_16x16x32_bf16 v[6:9], v[138:141], v[196:199], v[6:9]
	v_mfma_f32_16x16x32_bf16 v[94:97], v[134:137], v[150:153], v[94:97]
	v_mfma_f32_16x16x32_bf16 v[30:33], v[142:145], v[150:153], v[30:33]
	v_mfma_f32_16x16x32_bf16 v[86:89], v[134:137], v[174:177], v[86:89]
	v_mfma_f32_16x16x32_bf16 v[22:25], v[142:145], v[174:177], v[22:25]
	v_mfma_f32_16x16x32_bf16 v[78:81], v[134:137], v[192:195], v[78:81]
	v_mfma_f32_16x16x32_bf16 v[14:17], v[142:145], v[192:195], v[14:17]
	v_mfma_f32_16x16x32_bf16 v[70:73], v[134:137], v[200:203], v[70:73]
	v_mfma_f32_16x16x32_bf16 v[6:9], v[142:145], v[200:203], v[6:9]
	s_barrier
	s_add_u32 s38, s80, 0x7ff80
	s_addc_u32 s39, s81, 0
	s_add_i32 s33, s58, s91
	s_mov_b32 m0, s33
	s_nop 0
	global_load_lds_dwordx4 v158, s[38:39]
	s_add_i32 m0, s33, 0x2000
	s_nop 0
	global_load_lds_dwordx4 v154, s[38:39]
	s_waitcnt vmcnt(6)
	s_barrier
; #define PG8_STAGE(bufoff, gbase, voff) do { _Pragma("unroll") for (int _i = 0; _i < 2; ++_i) \
;         __builtin_amdgcn_global_load_lds((const unsigned*)((const char*)(gbase) + (voff)[_i]), (LAS unsigned*)(lds + (bufoff) + ldsw + _i * 8192), 16, 0, 0); } while (0)
; #define PG8_LDA(dst, b, h) do { _Pragma("unroll") for (int m = 0; m < 4; ++m) _Pragma("unroll") for (int k = 0; k < 2; ++k) dst[m][k] = *(const LAS bf16x8*)(lds + PG8_SA(b, h) + aoff + m * 2048 + k * 1024); } while (0)
; #define PG8_LDB(dst, b, h) do { _Pragma("unroll") for (int n = 0; n < 2; ++n) _Pragma("unroll") for (int k = 0; k < 2; ++k) dst[n][k] = *(const LAS bf16x8*)(lds + PG8_SB(b, h) + boff + n * 2048 + k * 1024); } while (0)
; #define PG8_MMA(ai, bj, At, Bt) do { __builtin_amdgcn_s_setprio(1); _Pragma("unroll") for (int m = 0; m < 4; ++m) _Pragma("unroll") for (int n = 0; n < 2; ++n) _Pragma("unroll") for (int k = 0; k < 2; ++k) \
;         acc[ai][bj][m][n] = __builtin_amdgcn_mfma_f32_16x16x32_bf16(Bt[n][k], At[m][k], acc[ai][bj][m][n], 0, 0, 0); __builtin_amdgcn_s_setprio(0); } while (0)
; #define PG8_WAIT_V(n) asm volatile("s_waitcnt vmcnt(" #n ")" ::: "memory")
; #define PG8_WAIT_L(n) asm volatile("s_waitcnt lgkmcnt(" #n ")" ::: "memory")
; #define PG8_BAR __builtin_amdgcn_s_barrier()
; #define PG8_SCHED __builtin_amdgcn_sched_barrier(0)
; template <class Epi, class Sched, bool AREMAP>
; __device__ __forceinline__ void gemm_phase(LAS unsigned char* lds, const Gemm g, const Sched& S, const Epi& E, int wv) {
;     ...
;             PG8_WAIT_V(6); PG8_BAR; PG8_MMA(1, 1, At, B1); PG8_BAR;
;             PG8_LDB(B0, 1, 0); PG8_SCHED; PG8_LDA(At, 1, 0); PG8_STAGE(PG8_SA(0, 1), a2 + hstepA, voffA);
;             PG8_WAIT_L(8); PG8_BAR; PG8_WAIT_L(0); PG8_MMA(0, 0, At, B0); PG8_BAR; PG8_SCHED;
;             PG8_LDB(B1, 1, 1); PG8_STAGE(PG8_SB(1, 0), b3, voffB);
;             PG8_BAR; PG8_WAIT_L(0); PG8_MMA(0, 1, At, B1); PG8_BAR;
	v_mfma_f32_16x16x32_bf16 v[90:93], v[204:207], v[146:149], v[90:93]
	v_mfma_f32_16x16x32_bf16 v[26:29], v[212:215], v[146:149], v[26:29]
	v_mfma_f32_16x16x32_bf16 v[82:85], v[204:207], v[170:173], v[82:85]
	v_mfma_f32_16x16x32_bf16 v[18:21], v[212:215], v[170:173], v[18:21]
	v_mfma_f32_16x16x32_bf16 v[74:77], v[204:207], v[184:187], v[74:77]
	v_mfma_f32_16x16x32_bf16 v[10:13], v[212:215], v[184:187], v[10:13]
	v_mfma_f32_16x16x32_bf16 v[66:69], v[204:207], v[196:199], v[66:69]
	v_mfma_f32_16x16x32_bf16 v[2:5], v[212:215], v[196:199], v[2:5]
	v_mfma_f32_16x16x32_bf16 v[90:93], v[208:211], v[150:153], v[90:93]
	v_mfma_f32_16x16x32_bf16 v[26:29], v[216:219], v[150:153], v[26:29]
	v_mfma_f32_16x16x32_bf16 v[82:85], v[208:211], v[174:177], v[82:85]
	v_mfma_f32_16x16x32_bf16 v[18:21], v[216:219], v[174:177], v[18:21]
	v_mfma_f32_16x16x32_bf16 v[74:77], v[208:211], v[192:195], v[74:77]
	v_mfma_f32_16x16x32_bf16 v[10:13], v[216:219], v[192:195], v[10:13]
	v_mfma_f32_16x16x32_bf16 v[66:69], v[208:211], v[200:203], v[66:69]
	v_mfma_f32_16x16x32_bf16 v[2:5], v[216:219], v[200:203], v[2:5]
	s_add_i32 s33, 0, 0x18000
	v_add_u32_e32 v142, s33, v1
	s_barrier
	ds_read_b128 v[130:133], v142
	ds_read_b128 v[134:137], v142 offset:1024
	ds_read_b128 v[138:141], v142 offset:2048
	ds_read_b128 v[142:145], v142 offset:3072
	s_add_u32 s38, s96, 0x3ff80
	s_addc_u32 s39, s97, 0
	s_mov_b32 m0, s12
	ds_read_b128 v[146:149], v183 offset:32768
	ds_read_b128 v[150:153], v183 offset:33792
	ds_read_b128 v[170:173], v183 offset:34816
	ds_read_b128 v[174:177], v183 offset:35840
	ds_read_b128 v[184:187], v183 offset:36864
	ds_read_b128 v[192:195], v183 offset:37888
	ds_read_b128 v[196:199], v183 offset:38912
	ds_read_b128 v[200:203], v183 offset:39936
	global_load_lds_dwordx4 v160, s[38:39]
	s_mov_b32 m0, s13
	s_nop 0
	global_load_lds_dwordx4 v156, s[38:39]
	s_waitcnt lgkmcnt(8)
	s_barrier
	s_waitcnt lgkmcnt(0)
	v_mfma_f32_16x16x32_bf16 v[126:129], v[130:133], v[146:149], v[126:129]
	v_mfma_f32_16x16x32_bf16 v[62:65], v[138:141], v[146:149], v[62:65]
	v_mfma_f32_16x16x32_bf16 v[118:121], v[130:133], v[170:173], v[118:121]
	v_mfma_f32_16x16x32_bf16 v[54:57], v[138:141], v[170:173], v[54:57]
	v_mfma_f32_16x16x32_bf16 v[110:113], v[130:133], v[184:187], v[110:113]
	v_mfma_f32_16x16x32_bf16 v[46:49], v[138:141], v[184:187], v[46:49]
	v_mfma_f32_16x16x32_bf16 v[102:105], v[130:133], v[196:199], v[102:105]
	v_mfma_f32_16x16x32_bf16 v[38:41], v[138:141], v[196:199], v[38:41]
	v_mfma_f32_16x16x32_bf16 v[126:129], v[134:137], v[150:153], v[126:129]
	v_mfma_f32_16x16x32_bf16 v[62:65], v[142:145], v[150:153], v[62:65]
	v_mfma_f32_16x16x32_bf16 v[118:121], v[134:137], v[174:177], v[118:121]
	v_mfma_f32_16x16x32_bf16 v[54:57], v[142:145], v[174:177], v[54:57]
	v_mfma_f32_16x16x32_bf16 v[110:113], v[134:137], v[192:195], v[110:113]
	v_mfma_f32_16x16x32_bf16 v[46:49], v[142:145], v[192:195], v[46:49]
	v_mfma_f32_16x16x32_bf16 v[102:105], v[134:137], v[200:203], v[102:105]
	v_mfma_f32_16x16x32_bf16 v[38:41], v[142:145], v[200:203], v[38:41]
	s_barrier
	s_add_i32 s58, 0, 0x1c000
	s_add_i32 s33, s33, s91
	v_add_u32_e32 v216, s58, v1
	s_mov_b32 m0, s33
	ds_read_b128 v[204:207], v216
	ds_read_b128 v[208:211], v216 offset:1024
	ds_read_b128 v[212:215], v216 offset:2048
	ds_read_b128 v[216:219], v216 offset:3072
	global_load_lds_dwordx4 v158, s[80:81]
	s_add_i32 m0, s33, 0x2000
	s_nop 0
	global_load_lds_dwordx4 v154, s[80:81]
	s_barrier
	s_waitcnt lgkmcnt(0)
	v_mfma_f32_16x16x32_bf16 v[122:125], v[204:207], v[146:149], v[122:125]
	v_mfma_f32_16x16x32_bf16 v[58:61], v[212:215], v[146:149], v[58:61]
	v_mfma_f32_16x16x32_bf16 v[114:117], v[204:207], v[170:173], v[114:117]
	v_mfma_f32_16x16x32_bf16 v[50:53], v[212:215], v[170:173], v[50:53]
	v_mfma_f32_16x16x32_bf16 v[106:109], v[204:207], v[184:187], v[106:109]
	v_mfma_f32_16x16x32_bf16 v[42:45], v[212:215], v[184:187], v[42:45]
	v_mfma_f32_16x16x32_bf16 v[98:101], v[204:207], v[196:199], v[98:101]
	v_mfma_f32_16x16x32_bf16 v[34:37], v[212:215], v[196:199], v[34:37]
	v_mfma_f32_16x16x32_bf16 v[122:125], v[208:211], v[150:153], v[122:125]
	v_mfma_f32_16x16x32_bf16 v[58:61], v[216:219], v[150:153], v[58:61]
	v_mfma_f32_16x16x32_bf16 v[114:117], v[208:211], v[174:177], v[114:117]
	v_mfma_f32_16x16x32_bf16 v[50:53], v[216:219], v[174:177], v[50:53]
	v_mfma_f32_16x16x32_bf16 v[106:109], v[208:211], v[192:195], v[106:109]
	v_mfma_f32_16x16x32_bf16 v[42:45], v[216:219], v[192:195], v[42:45]
	v_mfma_f32_16x16x32_bf16 v[98:101], v[208:211], v[200:203], v[98:101]
	v_mfma_f32_16x16x32_bf16 v[34:37], v[216:219], v[200:203], v[34:37]
	s_mov_b32 m0, s14
	s_barrier
	ds_read_b128 v[146:149], v183 offset:49152
	ds_read_b128 v[150:153], v183 offset:50176
	ds_read_b128 v[170:173], v183 offset:51200
	ds_read_b128 v[174:177], v183 offset:52224
	ds_read_b128 v[184:187], v183 offset:53248
	ds_read_b128 v[192:195], v183 offset:54272
	ds_read_b128 v[196:199], v183 offset:55296
	ds_read_b128 v[200:203], v183 offset:56320
	global_load_lds_dwordx4 v160, s[96:97]
	s_mov_b32 m0, s15
	s_nop 0
	global_load_lds_dwordx4 v156, s[96:97]
	s_barrier
; #define PG8_STAGE(bufoff, gbase, voff) do { _Pragma("unroll") for (int _i = 0; _i < 2; ++_i) \
;         __builtin_amdgcn_global_load_lds((const unsigned*)((const char*)(gbase) + (voff)[_i]), (LAS unsigned*)(lds + (bufoff) + ldsw + _i * 8192), 16, 0, 0); } while (0)
; #define PG8_LDA(dst, b, h) do { _Pragma("unroll") for (int m = 0; m < 4; ++m) _Pragma("unroll") for (int k = 0; k < 2; ++k) dst[m][k] = *(const LAS bf16x8*)(lds + PG8_SA(b, h) + aoff + m * 2048 + k * 1024); } while (0)
; #define PG8_MMA(ai, bj, At, Bt) do { __builtin_amdgcn_s_setprio(1); _Pragma("unroll") for (int m = 0; m < 4; ++m) _Pragma("unroll") for (int n = 0; n < 2; ++n) _Pragma("unroll") for (int k = 0; k < 2; ++k) \
;         acc[ai][bj][m][n] = __builtin_amdgcn_mfma_f32_16x16x32_bf16(Bt[n][k], At[m][k], acc[ai][bj][m][n], 0, 0, 0); __builtin_amdgcn_s_setprio(0); } while (0)
; #define PG8_WAIT_V(n) asm volatile("s_waitcnt vmcnt(" #n ")" ::: "memory")
; #define PG8_WAIT_L(n) asm volatile("s_waitcnt lgkmcnt(" #n ")" ::: "memory")
; #define PG8_BAR __builtin_amdgcn_s_barrier()
; #define PG8_SCHED __builtin_amdgcn_sched_barrier(0)
; template <class Epi, class Sched, bool AREMAP>
; __device__ __forceinline__ void gemm_phase(LAS unsigned char* lds, const Gemm g, const Sched& S, const Epi& E, int wv) {
;     ...
;             PG8_LDA(At, 1, 1); PG8_STAGE(PG8_SA(1, 0), a3, voffA);
;             PG8_BAR; PG8_WAIT_L(0); PG8_MMA(1, 0, At, B0); PG8_BAR; PG8_SCHED;
;             PG8_STAGE(PG8_SB(1, 1), b3 + hstepB, voffB);
;             PG8_WAIT_V(6); PG8_BAR; PG8_MMA(1, 1, At, B1); PG8_BAR;
;         }
	s_waitcnt lgkmcnt(0)
	v_mfma_f32_16x16x32_bf16 v[94:97], v[130:133], v[146:149], v[94:97]
	v_mfma_f32_16x16x32_bf16 v[30:33], v[138:141], v[146:149], v[30:33]
	v_mfma_f32_16x16x32_bf16 v[86:89], v[130:133], v[170:173], v[86:89]
	v_mfma_f32_16x16x32_bf16 v[22:25], v[138:141], v[170:173], v[22:25]
	v_mfma_f32_16x16x32_bf16 v[78:81], v[130:133], v[184:187], v[78:81]
	v_mfma_f32_16x16x32_bf16 v[14:17], v[138:141], v[184:187], v[14:17]
	v_mfma_f32_16x16x32_bf16 v[70:73], v[130:133], v[196:199], v[70:73]
	v_mfma_f32_16x16x32_bf16 v[6:9], v[138:141], v[196:199], v[6:9]
	v_mfma_f32_16x16x32_bf16 v[94:97], v[134:137], v[150:153], v[94:97]
	v_mfma_f32_16x16x32_bf16 v[30:33], v[142:145], v[150:153], v[30:33]
	v_mfma_f32_16x16x32_bf16 v[86:89], v[134:137], v[174:177], v[86:89]
	v_mfma_f32_16x16x32_bf16 v[22:25], v[142:145], v[174:177], v[22:25]
	v_mfma_f32_16x16x32_bf16 v[78:81], v[134:137], v[192:195], v[78:81]
	v_mfma_f32_16x16x32_bf16 v[14:17], v[142:145], v[192:195], v[14:17]
	v_mfma_f32_16x16x32_bf16 v[70:73], v[134:137], v[200:203], v[70:73]
	v_mfma_f32_16x16x32_bf16 v[6:9], v[142:145], v[200:203], v[6:9]
	s_barrier
	s_add_u32 s38, s80, 0x80000
	s_addc_u32 s39, s81, 0
	s_add_i32 s33, s58, s91
	s_mov_b32 m0, s33
	s_nop 0
	global_load_lds_dwordx4 v158, s[38:39]
	s_add_i32 m0, s33, 0x2000
	s_nop 0
	global_load_lds_dwordx4 v154, s[38:39]
	s_waitcnt vmcnt(6)
	s_barrier
	v_mfma_f32_16x16x32_bf16 v[90:93], v[204:207], v[146:149], v[90:93]
	v_mfma_f32_16x16x32_bf16 v[26:29], v[212:215], v[146:149], v[26:29]
	v_mfma_f32_16x16x32_bf16 v[82:85], v[204:207], v[170:173], v[82:85]
	v_mfma_f32_16x16x32_bf16 v[18:21], v[212:215], v[170:173], v[18:21]
	v_mfma_f32_16x16x32_bf16 v[74:77], v[204:207], v[184:187], v[74:77]
	v_mfma_f32_16x16x32_bf16 v[10:13], v[212:215], v[184:187], v[10:13]
	v_mfma_f32_16x16x32_bf16 v[66:69], v[204:207], v[196:199], v[66:69]
	v_mfma_f32_16x16x32_bf16 v[2:5], v[212:215], v[196:199], v[2:5]
	v_mfma_f32_16x16x32_bf16 v[90:93], v[208:211], v[150:153], v[90:93]
	v_mfma_f32_16x16x32_bf16 v[26:29], v[216:219], v[150:153], v[26:29]
	v_mfma_f32_16x16x32_bf16 v[82:85], v[208:211], v[174:177], v[82:85]
	v_mfma_f32_16x16x32_bf16 v[18:21], v[216:219], v[174:177], v[18:21]
	v_mfma_f32_16x16x32_bf16 v[74:77], v[208:211], v[192:195], v[74:77]
	v_mfma_f32_16x16x32_bf16 v[10:13], v[216:219], v[192:195], v[10:13]
	v_mfma_f32_16x16x32_bf16 v[66:69], v[208:211], v[200:203], v[66:69]
	v_mfma_f32_16x16x32_bf16 v[2:5], v[216:219], v[200:203], v[2:5]
	s_add_i32 vcc_hi, vcc_hi, 2
	s_add_u32 s77, s77, 0x100
	s_addc_u32 vcc_lo, vcc_lo, 0
	s_add_u32 s78, s78, 0x100
	s_addc_u32 s79, s79, 0
	s_cmp_gt_u32 vcc_hi, 29
	s_barrier
	s_cbranch_scc0 .LBB0_619
; __device__ __forceinline__ unsigned cvt_pk_bf16(float lo, float hi) { f32x2_t f = {lo, hi}; bf16x2_t v = __builtin_convertvector(f, bf16x2_t); return __builtin_bit_cast(unsigned, v); }
; __device__ __forceinline__ float sigmoidf_(float x) { return __builtin_amdgcn_rcpf(1.0f + __expf(-x)); }
;     __device__ __forceinline__ void operator()(const f32x4 (&acc)[2][2][4][2], const Unit& u, int wr, int wc, int fr, int fq) const {
;         const int lane = fq * 16 + fr;
;         const int ch0 = u.pn * 128 + wc * 32 + 8 * fq;
;         const int seg = u.pm * 2 + wr, tok0 = seg * 128 + fr;
;         const int src1 = (lane & 48) | ((fr + 15) & 15), src2 = (lane & 48) | ((fr + 14) & 15);
; #pragma unroll
;         for (int n = 0; n < 2; ++n) {
;             const int ch = ch0 + 4 * n;
;             f32x4 wv[3], wg[3];
; #pragma unroll
;             for (int k = 0; k < 3; ++k) { wv[k] = *(const f32x4*)(cw + k * NUP + ch); wg[k] = *(const f32x4*)(cw + k * NUP + DFF + ch); }
;             f32x4 pv1 = {0.f, 0.f, 0.f, 0.f}, pv2 = pv1, pg1 = pv1, pg2 = pv1;
; #pragma unroll
;             for (int q = 0; q < 8; ++q) {
;                 const int ai = q >> 2, m = q & 3;
;                 const f32x4 av = acc[ai][0][m][n], ag = acc[ai][1][m][n];
;                 f32x4 rv1, rv2, rg1, rg2;
; #pragma unroll
;                 for (int j = 0; j < 4; ++j) { rv1[j] = SHI(lane, av[j], src1); rv2[j] = SHI(lane, av[j], src2); rg1[j] = SHI(lane, ag[j], src1); rg2[j] = SHI(lane, ag[j], src2); }
;                 const f32x4 sv1 = fr >= 1 ? rv1 : pv1, sv2 = fr >= 2 ? rv2 : pv2, sg1 = fr >= 1 ? rg1 : pg1, sg2 = fr >= 2 ? rg2 : pg2;
;                 const f32x4 ov = wv[2] * av + wv[1] * sv1 + wv[0] * sv2;
;                 const f32x4 og = wg[2] * ag + wg[1] * sg1 + wg[0] * sg2;
;                 u32x2 w;
;                 w.x = cvt_pk_bf16(og[0] * sigmoidf_(og[0]) * ov[0], og[1] * sigmoidf_(og[1]) * ov[1]);
;                 w.y = cvt_pk_bf16(og[2] * sigmoidf_(og[2]) * ov[2], og[3] * sigmoidf_(og[3]) * ov[3]);
;                 *(u32x2*)(act + (size_t)(tok0 + q * 16) * DFF + ch) = w;
;                 if (q == 0 && fr < 2) { float* hp = halo + ((size_t)seg * 4 + fr) * NUP + ch; *(f32x4*)hp = av; *(f32x4*)(hp + DFF) = ag; }
;                 if (q == 7 && fr >= 14) { float* hp = halo + ((size_t)seg * 4 + (fr - 12)) * NUP + ch; *(f32x4*)hp = av; *(f32x4*)(hp + DFF) = ag; }
	v_lshl_or_b32 v170, s37, 7, v182
	s_lshl_b32 s37, s76, 1
	s_add_i32 s46, s37, s75
	s_ashr_i32 s47, s46, 31
	s_lshl_b64 s[76:77], s[46:47], 2
	v_lshl_add_u64 v[130:131], s[76:77], 0, v[162:163]
	s_mov_b32 s33, 0xb000
	v_ashrrev_i32_e32 v171, 31, v170
	v_lshl_or_b32 v184, s46, 7, v162
	v_mad_u64_u32 v[176:177], s[46:47], v130, s33, 0
	v_lshlrev_b64 v[142:143], 2, v[170:171]
	v_mad_i32_i24 v177, v131, s33, v177
	v_lshl_add_u64 v[130:131], s[24:25], 0, v[142:143]
	v_lshl_add_u64 v[138:139], s[26:27], 0, v[142:143]
	global_load_dwordx4 v[130:133], v[130:131], off
	v_lshl_add_u64 v[144:145], s[30:31], 0, v[142:143]
	global_load_dwordx4 v[146:149], v[138:139], off
	v_lshl_add_u64 v[172:173], s[18:19], 0, v[142:143]
	v_lshl_add_u64 v[138:139], s[28:29], 0, v[142:143]
	global_load_dwordx4 v[150:153], v[144:145], off
	global_load_dwordx4 v[134:137], v[172:173], off
	v_lshl_add_u64 v[142:143], s[34:35], 0, v[142:143]
	global_load_dwordx4 v[138:141], v[138:139], off
	v_mov_b32_dpp v199, v126 row_ror:1 row_mask:0xf bank_mask:0xf
	global_load_dwordx4 v[142:145], v[142:143], off
	v_mov_b32_dpp v204, v127 row_ror:1 row_mask:0xf bank_mask:0xf
	v_mov_b32_dpp v206, v128 row_ror:1 row_mask:0xf bank_mask:0xf
	v_mov_b32_dpp v208, v129 row_ror:1 row_mask:0xf bank_mask:0xf
	v_mov_b32_dpp v196, v126 row_ror:2 row_mask:0xf bank_mask:0xf
	v_mov_b32_dpp v186, v122 row_ror:1 row_mask:0xf bank_mask:0xf
	v_mov_b32_dpp v201, v127 row_ror:2 row_mask:0xf bank_mask:0xf
	v_mov_b32_dpp v198, v123 row_ror:1 row_mask:0xf bank_mask:0xf
	v_mov_b32_dpp v203, v128 row_ror:2 row_mask:0xf bank_mask:0xf
	v_mov_b32_dpp v200, v124 row_ror:1 row_mask:0xf bank_mask:0xf
	v_mov_b32_dpp v207, v129 row_ror:2 row_mask:0xf bank_mask:0xf
	v_mov_b32_dpp v205, v125 row_ror:1 row_mask:0xf bank_mask:0xf
	v_mov_b32_dpp v185, v122 row_ror:2 row_mask:0xf bank_mask:0xf
	v_mov_b32_dpp v187, v123 row_ror:2 row_mask:0xf bank_mask:0xf
	v_mov_b32_dpp v197, v124 row_ror:2 row_mask:0xf bank_mask:0xf
	v_mov_b32_dpp v202, v125 row_ror:2 row_mask:0xf bank_mask:0xf
	s_waitcnt lgkmcnt(0)
	v_cndmask_b32_e64 v175, v204, 0, s[0:1]
	v_cndmask_b32_e64 v174, v199, 0, s[0:1]
	v_cndmask_b32_e64 v179, v208, 0, s[0:1]
	v_cndmask_b32_e64 v178, v206, 0, s[0:1]
	v_cndmask_b32_e64 v193, 0, v201, s[2:3]
	v_cndmask_b32_e64 v192, 0, v196, s[2:3]
	v_cndmask_b32_e64 v195, 0, v207, s[2:3]
	v_cndmask_b32_e64 v194, 0, v203, s[2:3]
	v_cndmask_b32_e64 v211, v198, 0, s[0:1]
	v_cndmask_b32_e64 v210, v186, 0, s[0:1]
	v_cndmask_b32_e64 v213, v205, 0, s[0:1]
	v_cndmask_b32_e64 v212, v200, 0, s[0:1]
	v_cndmask_b32_e64 v215, 0, v187, s[2:3]
	v_cndmask_b32_e64 v214, 0, v185, s[2:3]
	v_cndmask_b32_e64 v217, 0, v202, s[2:3]
	v_cndmask_b32_e64 v216, 0, v197, s[2:3]
	s_movk_i32 s33, 0x2c00
	v_lshl_add_u64 v[176:177], s[22:23], 0, v[176:177]
	v_lshl_add_u64 v[176:177], v[170:171], 2, v[176:177]
	s_waitcnt vmcnt(0)
	v_pk_mul_f32 v[178:179], v[148:149], v[178:179]
	v_pk_mul_f32 v[174:175], v[146:147], v[174:175]
	v_pk_fma_f32 v[178:179], v[128:129], v[152:153], v[178:179]
	v_pk_fma_f32 v[174:175], v[126:127], v[150:151], v[174:175]
	v_pk_fma_f32 v[194:195], v[136:137], v[194:195], v[178:179]
	v_pk_fma_f32 v[174:175], v[134:135], v[192:193], v[174:175]
	v_pk_mul_f32 v[178:179], v[140:141], v[212:213]
	v_pk_mul_f32 v[192:193], v[138:139], v[210:211]
	v_pk_fma_f32 v[178:179], v[124:125], v[144:145], v[178:179]
	v_pk_fma_f32 v[192:193], v[122:123], v[142:143], v[192:193]
	v_pk_fma_f32 v[210:211], v[132:133], v[216:217], v[178:179]
	v_pk_fma_f32 v[178:179], v[130:131], v[214:215], v[192:193]
	s_nop 0
	v_mul_f32_e32 v192, 0xbfb8aa3b, v178
	v_mul_f32_e32 v193, 0xbfb8aa3b, v179
	v_exp_f32_e32 v192, v192
	v_exp_f32_e32 v193, v193
	v_add_f32_e32 v192, 1.0, v192
	v_add_f32_e32 v193, 1.0, v193
	v_rcp_f32_e32 v192, v192
	v_rcp_f32_e32 v193, v193
	s_nop 0
	v_pk_mul_f32 v[178:179], v[178:179], v[192:193]
	s_nop 0
	v_pk_mul_f32 v[174:175], v[174:175], v[178:179]
	s_nop 0
	v_cvt_pk_bf16_f32 v178, v174, v175
	v_mul_f32_e32 v174, 0xbfb8aa3b, v210
	v_mul_f32_e32 v175, 0xbfb8aa3b, v211
	v_exp_f32_e32 v174, v174
	v_exp_f32_e32 v175, v175
	v_add_f32_e32 v174, 1.0, v174
	v_add_f32_e32 v175, 1.0, v175
	v_rcp_f32_e32 v174, v174
	v_rcp_f32_e32 v175, v175
	s_nop 0
	v_pk_mul_f32 v[174:175], v[210:211], v[174:175]
	s_nop 0
	v_pk_mul_f32 v[174:175], v[194:195], v[174:175]
	s_nop 0
	v_cvt_pk_bf16_f32 v179, v174, v175
	v_mov_b64_e32 v[174:175], s[20:21]
	v_mad_i64_i32 v[174:175], s[46:47], v184, s33, v[174:175]
	v_lshl_add_u64 v[174:175], v[170:171], 1, v[174:175]
	global_store_dwordx2 v[174:175], v[178:179], off
	s_and_saveexec_b64 s[78:79], s[4:5]
	s_cbranch_execz .LBB0_622
	global_store_dwordx4 v[176:177], v[126:129], off
	s_nop 1
	v_add_co_u32_e32 v126, vcc, 0x5000, v176
	s_nop 1
	v_addc_co_u32_e32 v127, vcc, 0, v177, vcc
	global_store_dwordx4 v[126:127], v[122:125], off offset:2048

; #define PG8_STAGE(bufoff, gbase, voff) do { _Pragma("unroll") for (int _i = 0; _i < 2; ++_i) \
;         __builtin_amdgcn_global_load_lds((const unsigned*)((const char*)(gbase) + (voff)[_i]), (LAS unsigned*)(lds + (bufoff) + ldsw + _i * 8192), 16, 0, 0); } while (0)
; #define PG8_LDA(dst, b, h) do { _Pragma("unroll") for (int m = 0; m < 4; ++m) _Pragma("unroll") for (int k = 0; k < 2; ++k) dst[m][k] = *(const LAS bf16x8*)(lds + PG8_SA(b, h) + aoff + m * 2048 + k * 1024); } while (0)
; #define PG8_LDB(dst, b, h) do { _Pragma("unroll") for (int n = 0; n < 2; ++n) _Pragma("unroll") for (int k = 0; k < 2; ++k) dst[n][k] = *(const LAS bf16x8*)(lds + PG8_SB(b, h) + boff + n * 2048 + k * 1024); } while (0)
; #define PG8_MMA(ai, bj, At, Bt) do { __builtin_amdgcn_s_setprio(1); _Pragma("unroll") for (int m = 0; m < 4; ++m) _Pragma("unroll") for (int n = 0; n < 2; ++n) _Pragma("unroll") for (int k = 0; k < 2; ++k) \
;         acc[ai][bj][m][n] = __builtin_amdgcn_mfma_f32_16x16x32_bf16(Bt[n][k], At[m][k], acc[ai][bj][m][n], 0, 0, 0); __builtin_amdgcn_s_setprio(0); } while (0)
; #define PG8_WAIT_V(n) asm volatile("s_waitcnt vmcnt(" #n ")" ::: "memory")
; #define PG8_WAIT_L(n) asm volatile("s_waitcnt lgkmcnt(" #n ")" ::: "memory")
; #define PG8_BAR __builtin_amdgcn_s_barrier()
; #define PG8_SCHED __builtin_amdgcn_sched_barrier(0)
; template <class Epi, class Sched, bool AREMAP>
; __device__ __forceinline__ void gemm_phase(LAS unsigned char* lds, const Gemm g, const Sched& S, const Epi& E, int wv) {
;     ...
;             const char* a1 = cA + (size_t)(t + 1) * kstep;
;             const char* a2 = last ? nA : cA + (size_t)(t + 2) * kstep; const char* b2 = last ? nB : cB + (size_t)(t + 2) * kstep;
;             const char* a3 = a2 + kstep; const char* b3 = b2 + kstep;
;             PG8_LDB(B0, 0, 0); PG8_SCHED; PG8_LDA(At, 0, 0); PG8_STAGE(PG8_SA(1, 1), a1 + hstepA, voffA);
;             PG8_WAIT_L(8); PG8_BAR; PG8_WAIT_L(0); PG8_MMA(0, 0, At, B0); PG8_BAR; PG8_SCHED;
;             PG8_LDB(B1, 0, 1); PG8_STAGE(PG8_SB(0, 0), b2, voffB);
;             PG8_BAR; PG8_WAIT_L(0); PG8_MMA(0, 1, At, B1); PG8_BAR;
;             PG8_LDA(At, 0, 1); PG8_STAGE(PG8_SA(0, 0), a2, voffA);
;             PG8_BAR; PG8_WAIT_L(0); PG8_MMA(1, 0, At, B0); PG8_BAR; PG8_SCHED;
;             PG8_STAGE(PG8_SB(0, 1), b2 + hstepB, voffB);
;             PG8_WAIT_V(6); PG8_BAR; PG8_MMA(1, 1, At, B1); PG8_BAR;
.LBB0_674:
	s_add_u32 s2, s24, 0x100
	s_addc_u32 s3, s25, 0
	s_add_i32 s33, 0, 0x10000
	v_add_u32_e32 v1, s33, v250
	ds_read_b128 v[130:133], v1
	ds_read_b128 v[134:137], v1 offset:1024
	ds_read_b128 v[138:141], v1 offset:2048
	ds_read_b128 v[142:145], v1 offset:3072
	s_cmpk_eq_i32 s67, 0x54
	s_cselect_b32 s29, s23, s3
	s_cselect_b32 s28, s22, s2
	s_cselect_b32 s27, s5, s66
	s_cselect_b32 s26, s4, s65
	s_add_i32 m0, s35, 0xc000
	ds_read_b128 v[146:149], v252
	ds_read_b128 v[150:153], v252 offset:1024
	ds_read_b128 v[154:157], v252 offset:2048
	ds_read_b128 v[158:161], v252 offset:3072
	ds_read_b128 v[162:165], v252 offset:4096
	ds_read_b128 v[166:169], v252 offset:5120
	ds_read_b128 v[170:173], v252 offset:6144
	ds_read_b128 v[174:177], v252 offset:7168
	global_load_lds_dwordx4 v202, s[24:25]
	s_add_i32 m0, s35, 0xe000
	s_nop 0
	global_load_lds_dwordx4 v200, s[24:25]
	s_waitcnt lgkmcnt(8)
	s_barrier
	s_waitcnt lgkmcnt(0)
	v_mfma_f32_16x16x32_bf16 v[126:129], v[130:133], v[146:149], v[126:129]
	v_mfma_f32_16x16x32_bf16 v[110:113], v[138:141], v[146:149], v[110:113]
	v_mfma_f32_16x16x32_bf16 v[122:125], v[130:133], v[154:157], v[122:125]
	v_mfma_f32_16x16x32_bf16 v[106:109], v[138:141], v[154:157], v[106:109]
	v_mfma_f32_16x16x32_bf16 v[118:121], v[130:133], v[162:165], v[118:121]
	v_mfma_f32_16x16x32_bf16 v[102:105], v[138:141], v[162:165], v[102:105]
	v_mfma_f32_16x16x32_bf16 v[114:117], v[130:133], v[170:173], v[114:117]
	v_mfma_f32_16x16x32_bf16 v[98:101], v[138:141], v[170:173], v[98:101]
	v_mfma_f32_16x16x32_bf16 v[126:129], v[134:137], v[150:153], v[126:129]
	v_mfma_f32_16x16x32_bf16 v[110:113], v[142:145], v[150:153], v[110:113]
	v_mfma_f32_16x16x32_bf16 v[122:125], v[134:137], v[158:161], v[122:125]
	v_mfma_f32_16x16x32_bf16 v[106:109], v[142:145], v[158:161], v[106:109]
	v_mfma_f32_16x16x32_bf16 v[118:121], v[134:137], v[166:169], v[118:121]
	v_mfma_f32_16x16x32_bf16 v[102:105], v[142:145], v[166:169], v[102:105]
	v_mfma_f32_16x16x32_bf16 v[114:117], v[134:137], v[174:177], v[114:117]
	v_mfma_f32_16x16x32_bf16 v[98:101], v[142:145], v[174:177], v[98:101]
	s_barrier
	s_add_i32 s38, 0, 0x14000
	s_add_i32 s24, s33, s34
	v_add_u32_e32 v1, s38, v250
	s_add_u32 s80, s26, 0x80
	s_addc_u32 s81, s27, 0
	s_mov_b32 m0, s24
	ds_read_b128 v[178:181], v1
	ds_read_b128 v[182:185], v1 offset:1024
	ds_read_b128 v[192:195], v1 offset:2048
	ds_read_b128 v[204:207], v1 offset:3072
	global_load_lds_dwordx4 v196, s[26:27]
	s_add_i32 m0, s24, 0x2000
	s_nop 0
	global_load_lds_dwordx4 v198, s[26:27]
	s_barrier
	s_waitcnt lgkmcnt(0)
	v_mfma_f32_16x16x32_bf16 v[94:97], v[178:181], v[146:149], v[94:97]
	v_mfma_f32_16x16x32_bf16 v[78:81], v[192:195], v[146:149], v[78:81]
	v_mfma_f32_16x16x32_bf16 v[90:93], v[178:181], v[154:157], v[90:93]
	v_mfma_f32_16x16x32_bf16 v[74:77], v[192:195], v[154:157], v[74:77]
	v_mfma_f32_16x16x32_bf16 v[86:89], v[178:181], v[162:165], v[86:89]
	v_mfma_f32_16x16x32_bf16 v[70:73], v[192:195], v[162:165], v[70:73]
	v_mfma_f32_16x16x32_bf16 v[82:85], v[178:181], v[170:173], v[82:85]
	v_mfma_f32_16x16x32_bf16 v[66:69], v[192:195], v[170:173], v[66:69]
	v_mfma_f32_16x16x32_bf16 v[94:97], v[182:185], v[150:153], v[94:97]
	v_mfma_f32_16x16x32_bf16 v[78:81], v[204:207], v[150:153], v[78:81]
	v_mfma_f32_16x16x32_bf16 v[90:93], v[182:185], v[158:161], v[90:93]
	v_mfma_f32_16x16x32_bf16 v[74:77], v[204:207], v[158:161], v[74:77]
	v_mfma_f32_16x16x32_bf16 v[86:89], v[182:185], v[166:169], v[86:89]
	v_mfma_f32_16x16x32_bf16 v[70:73], v[204:207], v[166:169], v[70:73]
	v_mfma_f32_16x16x32_bf16 v[82:85], v[182:185], v[174:177], v[82:85]
	v_mfma_f32_16x16x32_bf16 v[66:69], v[204:207], v[174:177], v[66:69]
	s_mov_b32 m0, s35
	s_add_u32 s96, s28, 0x80
	s_addc_u32 s97, s29, 0
	s_barrier
	ds_read_b128 v[146:149], v252 offset:16384
	ds_read_b128 v[150:153], v252 offset:17408
	ds_read_b128 v[154:157], v252 offset:18432
	ds_read_b128 v[158:161], v252 offset:19456
	ds_read_b128 v[162:165], v252 offset:20480
	ds_read_b128 v[166:169], v252 offset:21504
	ds_read_b128 v[170:173], v252 offset:22528
	ds_read_b128 v[174:177], v252 offset:23552
	global_load_lds_dwordx4 v196, s[28:29]
	s_mov_b32 m0, s36
	s_nop 0
	global_load_lds_dwordx4 v198, s[28:29]
	s_barrier
	s_waitcnt lgkmcnt(0)
	v_mfma_f32_16x16x32_bf16 v[62:65], v[130:133], v[146:149], v[62:65]
	v_mfma_f32_16x16x32_bf16 v[46:49], v[138:141], v[146:149], v[46:49]
	v_mfma_f32_16x16x32_bf16 v[58:61], v[130:133], v[154:157], v[58:61]
	v_mfma_f32_16x16x32_bf16 v[42:45], v[138:141], v[154:157], v[42:45]
	v_mfma_f32_16x16x32_bf16 v[54:57], v[130:133], v[162:165], v[54:57]
	v_mfma_f32_16x16x32_bf16 v[38:41], v[138:141], v[162:165], v[38:41]
	v_mfma_f32_16x16x32_bf16 v[50:53], v[130:133], v[170:173], v[50:53]
	v_mfma_f32_16x16x32_bf16 v[34:37], v[138:141], v[170:173], v[34:37]
	v_mfma_f32_16x16x32_bf16 v[62:65], v[134:137], v[150:153], v[62:65]
	v_mfma_f32_16x16x32_bf16 v[46:49], v[142:145], v[150:153], v[46:49]
	v_mfma_f32_16x16x32_bf16 v[58:61], v[134:137], v[158:161], v[58:61]
	v_mfma_f32_16x16x32_bf16 v[42:45], v[142:145], v[158:161], v[42:45]
	v_mfma_f32_16x16x32_bf16 v[54:57], v[134:137], v[166:169], v[54:57]
	v_mfma_f32_16x16x32_bf16 v[38:41], v[142:145], v[166:169], v[38:41]
	v_mfma_f32_16x16x32_bf16 v[50:53], v[134:137], v[174:177], v[50:53]
	v_mfma_f32_16x16x32_bf16 v[34:37], v[142:145], v[174:177], v[34:37]
	s_barrier
	s_add_u32 s24, s26, 0x160000
	s_addc_u32 s25, s27, 0
	s_add_i32 s33, s38, s34
	s_mov_b32 m0, s33
	s_nop 0
	global_load_lds_dwordx4 v196, s[24:25]
	s_add_i32 m0, s33, 0x2000
	s_nop 0
	global_load_lds_dwordx4 v198, s[24:25]
	s_waitcnt vmcnt(6)
	s_barrier
; #define PG8_STAGE(bufoff, gbase, voff) do { _Pragma("unroll") for (int _i = 0; _i < 2; ++_i) \
;         __builtin_amdgcn_global_load_lds((const unsigned*)((const char*)(gbase) + (voff)[_i]), (LAS unsigned*)(lds + (bufoff) + ldsw + _i * 8192), 16, 0, 0); } while (0)
; #define PG8_LDA(dst, b, h) do { _Pragma("unroll") for (int m = 0; m < 4; ++m) _Pragma("unroll") for (int k = 0; k < 2; ++k) dst[m][k] = *(const LAS bf16x8*)(lds + PG8_SA(b, h) + aoff + m * 2048 + k * 1024); } while (0)
; #define PG8_LDB(dst, b, h) do { _Pragma("unroll") for (int n = 0; n < 2; ++n) _Pragma("unroll") for (int k = 0; k < 2; ++k) dst[n][k] = *(const LAS bf16x8*)(lds + PG8_SB(b, h) + boff + n * 2048 + k * 1024); } while (0)
; #define PG8_MMA(ai, bj, At, Bt) do { __builtin_amdgcn_s_setprio(1); _Pragma("unroll") for (int m = 0; m < 4; ++m) _Pragma("unroll") for (int n = 0; n < 2; ++n) _Pragma("unroll") for (int k = 0; k < 2; ++k) \
;         acc[ai][bj][m][n] = __builtin_amdgcn_mfma_f32_16x16x32_bf16(Bt[n][k], At[m][k], acc[ai][bj][m][n], 0, 0, 0); __builtin_amdgcn_s_setprio(0); } while (0)
; #define PG8_WAIT_V(n) asm volatile("s_waitcnt vmcnt(" #n ")" ::: "memory")
; #define PG8_WAIT_L(n) asm volatile("s_waitcnt lgkmcnt(" #n ")" ::: "memory")
; #define PG8_BAR __builtin_amdgcn_s_barrier()
; #define PG8_SCHED __builtin_amdgcn_sched_barrier(0)
; template <class Epi, class Sched, bool AREMAP>
; __device__ __forceinline__ void gemm_phase(LAS unsigned char* lds, const Gemm g, const Sched& S, const Epi& E, int wv) {
;     ...
;             PG8_WAIT_V(6); PG8_BAR; PG8_MMA(1, 1, At, B1); PG8_BAR;
;             PG8_LDB(B0, 1, 0); PG8_SCHED; PG8_LDA(At, 1, 0); PG8_STAGE(PG8_SA(0, 1), a2 + hstepA, voffA);
;             PG8_WAIT_L(8); PG8_BAR; PG8_WAIT_L(0); PG8_MMA(0, 0, At, B0); PG8_BAR; PG8_SCHED;
;             PG8_LDB(B1, 1, 1); PG8_STAGE(PG8_SB(1, 0), b3, voffB);
;             PG8_BAR; PG8_WAIT_L(0); PG8_MMA(0, 1, At, B1); PG8_BAR;
	v_mfma_f32_16x16x32_bf16 v[30:33], v[178:181], v[146:149], v[30:33]
	v_mfma_f32_16x16x32_bf16 v[14:17], v[192:195], v[146:149], v[14:17]
	v_mfma_f32_16x16x32_bf16 v[26:29], v[178:181], v[154:157], v[26:29]
	v_mfma_f32_16x16x32_bf16 v[10:13], v[192:195], v[154:157], v[10:13]
	v_mfma_f32_16x16x32_bf16 v[22:25], v[178:181], v[162:165], v[22:25]
	v_mfma_f32_16x16x32_bf16 v[6:9], v[192:195], v[162:165], v[6:9]
	v_mfma_f32_16x16x32_bf16 v[18:21], v[178:181], v[170:173], v[18:21]
	v_mfma_f32_16x16x32_bf16 v[2:5], v[192:195], v[170:173], v[2:5]
	v_mfma_f32_16x16x32_bf16 v[30:33], v[182:185], v[150:153], v[30:33]
	v_mfma_f32_16x16x32_bf16 v[14:17], v[204:207], v[150:153], v[14:17]
	v_mfma_f32_16x16x32_bf16 v[26:29], v[182:185], v[158:161], v[26:29]
	v_mfma_f32_16x16x32_bf16 v[10:13], v[204:207], v[158:161], v[10:13]
	v_mfma_f32_16x16x32_bf16 v[22:25], v[182:185], v[166:169], v[22:25]
	v_mfma_f32_16x16x32_bf16 v[6:9], v[204:207], v[166:169], v[6:9]
	v_mfma_f32_16x16x32_bf16 v[18:21], v[182:185], v[174:177], v[18:21]
	v_mfma_f32_16x16x32_bf16 v[2:5], v[204:207], v[174:177], v[2:5]
	s_add_i32 s33, 0, 0x18000
	v_add_u32_e32 v1, s33, v250
	s_barrier
	ds_read_b128 v[130:133], v1
	ds_read_b128 v[134:137], v1 offset:1024
	ds_read_b128 v[138:141], v1 offset:2048
	ds_read_b128 v[142:145], v1 offset:3072
	s_add_u32 s24, s28, 0x160000
	s_addc_u32 s25, s29, 0
	s_mov_b32 m0, s37
	ds_read_b128 v[146:149], v252 offset:32768
	ds_read_b128 v[150:153], v252 offset:33792
	ds_read_b128 v[154:157], v252 offset:34816
	ds_read_b128 v[158:161], v252 offset:35840
	ds_read_b128 v[162:165], v252 offset:36864
	ds_read_b128 v[166:169], v252 offset:37888
	ds_read_b128 v[170:173], v252 offset:38912
	ds_read_b128 v[174:177], v252 offset:39936
	global_load_lds_dwordx4 v196, s[24:25]
	s_mov_b32 m0, s41
	s_nop 0
	global_load_lds_dwordx4 v198, s[24:25]
	s_waitcnt lgkmcnt(8)
	s_barrier
	s_waitcnt lgkmcnt(0)
	v_mfma_f32_16x16x32_bf16 v[126:129], v[130:133], v[146:149], v[126:129]
	v_mfma_f32_16x16x32_bf16 v[110:113], v[138:141], v[146:149], v[110:113]
	v_mfma_f32_16x16x32_bf16 v[122:125], v[130:133], v[154:157], v[122:125]
	v_mfma_f32_16x16x32_bf16 v[106:109], v[138:141], v[154:157], v[106:109]
	v_mfma_f32_16x16x32_bf16 v[118:121], v[130:133], v[162:165], v[118:121]
	v_mfma_f32_16x16x32_bf16 v[102:105], v[138:141], v[162:165], v[102:105]
	v_mfma_f32_16x16x32_bf16 v[114:117], v[130:133], v[170:173], v[114:117]
	v_mfma_f32_16x16x32_bf16 v[98:101], v[138:141], v[170:173], v[98:101]
	v_mfma_f32_16x16x32_bf16 v[126:129], v[134:137], v[150:153], v[126:129]
	v_mfma_f32_16x16x32_bf16 v[110:113], v[142:145], v[150:153], v[110:113]
	v_mfma_f32_16x16x32_bf16 v[122:125], v[134:137], v[158:161], v[122:125]
	v_mfma_f32_16x16x32_bf16 v[106:109], v[142:145], v[158:161], v[106:109]
	v_mfma_f32_16x16x32_bf16 v[118:121], v[134:137], v[166:169], v[118:121]
	v_mfma_f32_16x16x32_bf16 v[102:105], v[142:145], v[166:169], v[102:105]
	v_mfma_f32_16x16x32_bf16 v[114:117], v[134:137], v[174:177], v[114:117]
	v_mfma_f32_16x16x32_bf16 v[98:101], v[142:145], v[174:177], v[98:101]
	s_barrier
	s_add_i32 s28, 0, 0x1c000
	s_add_i32 s24, s33, s34
	v_add_u32_e32 v1, s28, v250
	s_mov_b32 m0, s24
	ds_read_b128 v[178:181], v1
	ds_read_b128 v[182:185], v1 offset:1024
	ds_read_b128 v[192:195], v1 offset:2048
	ds_read_b128 v[204:207], v1 offset:3072
	global_load_lds_dwordx4 v196, s[80:81]
	s_add_i32 m0, s24, 0x2000
	s_nop 0
	global_load_lds_dwordx4 v198, s[80:81]
	s_barrier
	s_waitcnt lgkmcnt(0)
	v_mfma_f32_16x16x32_bf16 v[94:97], v[178:181], v[146:149], v[94:97]
	v_mfma_f32_16x16x32_bf16 v[78:81], v[192:195], v[146:149], v[78:81]
	v_mfma_f32_16x16x32_bf16 v[90:93], v[178:181], v[154:157], v[90:93]
	v_mfma_f32_16x16x32_bf16 v[74:77], v[192:195], v[154:157], v[74:77]
	v_mfma_f32_16x16x32_bf16 v[86:89], v[178:181], v[162:165], v[86:89]
	v_mfma_f32_16x16x32_bf16 v[70:73], v[192:195], v[162:165], v[70:73]
	v_mfma_f32_16x16x32_bf16 v[82:85], v[178:181], v[170:173], v[82:85]
	v_mfma_f32_16x16x32_bf16 v[66:69], v[192:195], v[170:173], v[66:69]
	v_mfma_f32_16x16x32_bf16 v[94:97], v[182:185], v[150:153], v[94:97]
	v_mfma_f32_16x16x32_bf16 v[78:81], v[204:207], v[150:153], v[78:81]
	v_mfma_f32_16x16x32_bf16 v[90:93], v[182:185], v[158:161], v[90:93]
	v_mfma_f32_16x16x32_bf16 v[74:77], v[204:207], v[158:161], v[74:77]
	v_mfma_f32_16x16x32_bf16 v[86:89], v[182:185], v[166:169], v[86:89]
	v_mfma_f32_16x16x32_bf16 v[70:73], v[204:207], v[166:169], v[70:73]
	v_mfma_f32_16x16x32_bf16 v[82:85], v[182:185], v[174:177], v[82:85]
	v_mfma_f32_16x16x32_bf16 v[66:69], v[204:207], v[174:177], v[66:69]
	s_mov_b32 m0, s46
	s_barrier
; #define PG8_STAGE(bufoff, gbase, voff) do { _Pragma("unroll") for (int _i = 0; _i < 2; ++_i) \
;         __builtin_amdgcn_global_load_lds((const unsigned*)((const char*)(gbase) + (voff)[_i]), (LAS unsigned*)(lds + (bufoff) + ldsw + _i * 8192), 16, 0, 0); } while (0)
; #define PG8_LDA(dst, b, h) do { _Pragma("unroll") for (int m = 0; m < 4; ++m) _Pragma("unroll") for (int k = 0; k < 2; ++k) dst[m][k] = *(const LAS bf16x8*)(lds + PG8_SA(b, h) + aoff + m * 2048 + k * 1024); } while (0)
; #define PG8_MMA(ai, bj, At, Bt) do { __builtin_amdgcn_s_setprio(1); _Pragma("unroll") for (int m = 0; m < 4; ++m) _Pragma("unroll") for (int n = 0; n < 2; ++n) _Pragma("unroll") for (int k = 0; k < 2; ++k) \
;         acc[ai][bj][m][n] = __builtin_amdgcn_mfma_f32_16x16x32_bf16(Bt[n][k], At[m][k], acc[ai][bj][m][n], 0, 0, 0); __builtin_amdgcn_s_setprio(0); } while (0)
; #define PG8_WAIT_V(n) asm volatile("s_waitcnt vmcnt(" #n ")" ::: "memory")
; #define PG8_WAIT_L(n) asm volatile("s_waitcnt lgkmcnt(" #n ")" ::: "memory")
; #define PG8_BAR __builtin_amdgcn_s_barrier()
; #define PG8_SCHED __builtin_amdgcn_sched_barrier(0)
; template <class Epi, class Sched, bool AREMAP>
; __device__ __forceinline__ void gemm_phase(LAS unsigned char* lds, const Gemm g, const Sched& S, const Epi& E, int wv) {
;     ...
;             PG8_LDA(At, 1, 1); PG8_STAGE(PG8_SA(1, 0), a3, voffA);
;             PG8_BAR; PG8_WAIT_L(0); PG8_MMA(1, 0, At, B0); PG8_BAR; PG8_SCHED;
;             PG8_STAGE(PG8_SB(1, 1), b3 + hstepB, voffB);
;             PG8_WAIT_V(6); PG8_BAR; PG8_MMA(1, 1, At, B1); PG8_BAR;
;         }
;     __device__ __forceinline__ void operator()(const f32x4 (&acc)[2][2][4][2], const Unit& u, int wr, int wc, int fr, int fq) const {
;         const int row0 = u.pm * BM + wr * 64 + fr, col0 = u.pn * BM + wc * 32 + 4 * fq;
;         const float* gv = gate + (size_t)(u.pm >> 3) * 12288 + col0;
; #pragma unroll
;         for (int ai = 0; ai < 2; ++ai) {
;             float mu[4], rs[4];
; #pragma unroll
;             for (int m = 0; m < 4; ++m) { mu[m] = 0.f; rs[m] = 1.f;
;                 if (stats) { const float* sp = stats + (size_t)(row0 + ai * HALF + m * 16) * 2; mu[m] = sp[0]; rs[m] = sp[1]; } }
	ds_read_b128 v[146:149], v252 offset:49152
	ds_read_b128 v[150:153], v252 offset:50176
	ds_read_b128 v[154:157], v252 offset:51200
	ds_read_b128 v[158:161], v252 offset:52224
	ds_read_b128 v[162:165], v252 offset:53248
	ds_read_b128 v[166:169], v252 offset:54272
	ds_read_b128 v[170:173], v252 offset:55296
	ds_read_b128 v[174:177], v252 offset:56320
	global_load_lds_dwordx4 v196, s[96:97]
	s_mov_b32 m0, s47
	s_nop 0
	global_load_lds_dwordx4 v198, s[96:97]
	s_barrier
	s_waitcnt lgkmcnt(0)
	v_mfma_f32_16x16x32_bf16 v[62:65], v[130:133], v[146:149], v[62:65]
	v_mfma_f32_16x16x32_bf16 v[46:49], v[138:141], v[146:149], v[46:49]
	v_mfma_f32_16x16x32_bf16 v[58:61], v[130:133], v[154:157], v[58:61]
	v_mfma_f32_16x16x32_bf16 v[42:45], v[138:141], v[154:157], v[42:45]
	v_mfma_f32_16x16x32_bf16 v[54:57], v[130:133], v[162:165], v[54:57]
	v_mfma_f32_16x16x32_bf16 v[38:41], v[138:141], v[162:165], v[38:41]
	v_mfma_f32_16x16x32_bf16 v[50:53], v[130:133], v[170:173], v[50:53]
	v_mfma_f32_16x16x32_bf16 v[34:37], v[138:141], v[170:173], v[34:37]
	v_mfma_f32_16x16x32_bf16 v[62:65], v[134:137], v[150:153], v[62:65]
	v_mfma_f32_16x16x32_bf16 v[46:49], v[142:145], v[150:153], v[46:49]
	v_mfma_f32_16x16x32_bf16 v[58:61], v[134:137], v[158:161], v[58:61]
	v_mfma_f32_16x16x32_bf16 v[42:45], v[142:145], v[158:161], v[42:45]
	v_mfma_f32_16x16x32_bf16 v[54:57], v[134:137], v[166:169], v[54:57]
	v_mfma_f32_16x16x32_bf16 v[38:41], v[142:145], v[166:169], v[38:41]
	v_mfma_f32_16x16x32_bf16 v[50:53], v[134:137], v[174:177], v[50:53]
	v_mfma_f32_16x16x32_bf16 v[34:37], v[142:145], v[174:177], v[34:37]
	s_barrier
	s_add_u32 s24, s26, 0x160080
	s_addc_u32 s25, s27, 0
	s_add_i32 s26, s28, s34
	s_mov_b32 m0, s26
	s_nop 0
	global_load_lds_dwordx4 v196, s[24:25]
	s_add_i32 m0, s26, 0x2000
	s_nop 0
	global_load_lds_dwordx4 v198, s[24:25]
	s_waitcnt vmcnt(6)
	s_barrier
	v_mfma_f32_16x16x32_bf16 v[30:33], v[178:181], v[146:149], v[30:33]
	v_mfma_f32_16x16x32_bf16 v[14:17], v[192:195], v[146:149], v[14:17]
	v_mfma_f32_16x16x32_bf16 v[26:29], v[178:181], v[154:157], v[26:29]
	v_mfma_f32_16x16x32_bf16 v[10:13], v[192:195], v[154:157], v[10:13]
	v_mfma_f32_16x16x32_bf16 v[22:25], v[178:181], v[162:165], v[22:25]
	v_mfma_f32_16x16x32_bf16 v[6:9], v[192:195], v[162:165], v[6:9]
	v_mfma_f32_16x16x32_bf16 v[18:21], v[178:181], v[170:173], v[18:21]
	v_mfma_f32_16x16x32_bf16 v[2:5], v[192:195], v[170:173], v[2:5]
	v_mfma_f32_16x16x32_bf16 v[30:33], v[182:185], v[150:153], v[30:33]
	v_mfma_f32_16x16x32_bf16 v[14:17], v[204:207], v[150:153], v[14:17]
	v_mfma_f32_16x16x32_bf16 v[26:29], v[182:185], v[158:161], v[26:29]
	v_mfma_f32_16x16x32_bf16 v[10:13], v[204:207], v[158:161], v[10:13]
	v_mfma_f32_16x16x32_bf16 v[22:25], v[182:185], v[166:169], v[22:25]
	v_mfma_f32_16x16x32_bf16 v[6:9], v[204:207], v[166:169], v[6:9]
	v_mfma_f32_16x16x32_bf16 v[18:21], v[182:185], v[174:177], v[18:21]
	v_mfma_f32_16x16x32_bf16 v[2:5], v[204:207], v[174:177], v[2:5]
	s_add_i32 s67, s67, 2
	s_add_u32 s65, s65, 0x100
	s_addc_u32 s66, s66, 0
	s_cmpk_gt_u32 s67, 0x55
	s_mov_b64 s[24:25], s[2:3]
	s_barrier
	s_cbranch_scc0 .LBB0_674
	v_lshl_add_u32 v212, s62, 8, v249
	v_cndmask_b32_e64 v1, 0, 1, s[20:21]
	v_mov_b32_e32 v216, 1.0
	v_cmp_ne_u32_e64 s[2:3], 1, v1
	s_andn2_b64 vcc, exec, s[20:21]
	v_ashrrev_i32_e32 v213, 31, v212
	s_cbranch_vccnz .LBB0_677
	v_lshl_add_u64 v[130:131], v[212:213], 3, s[18:19]
	global_load_dwordx2 v[134:135], v[130:131], off
	s_branch .LBB0_678
